# GEMM K-loops (6 phases): global loads use SGPR base + per-lane 32-bit offset (saddr form); 18 address VALU + 8 nops per iteration removed
# speedup vs baseline: 1.1092x; 1.0045x over previous
.LBB0_248:
	s_lshl_b32 s56, s52, 8
	v_or_b32_e32 v2, s56, v1
	v_ashrrev_i32_e32 v3, 31, v2
	v_lshlrev_b64 v[62:63], 11, v[2:3]
	v_lshl_add_u64 v[2:3], v[130:131], 0, v[62:63]
	v_add_co_u32_e32 v6, vcc, 0x20000, v2
	s_lshl_b32 s53, s47, 8
	s_nop 0
	v_addc_co_u32_e32 v7, vcc, 0, v3, vcc
	v_or_b32_e32 v4, s53, v1
	global_load_dwordx4 v[30:33], v[2:3], off
	global_load_dwordx4 v[34:37], v[6:7], off
	v_add_co_u32_e32 v6, vcc, 0x40000, v2
	v_ashrrev_i32_e32 v5, 31, v4
	s_nop 0
	v_addc_co_u32_e32 v7, vcc, 0, v3, vcc
	v_lshlrev_b64 v[64:65], 11, v[4:5]
	v_add_co_u32_e32 v2, vcc, 0x60000, v2
	v_lshl_add_u64 v[4:5], v[132:133], 0, v[64:65]
	s_nop 0
	v_addc_co_u32_e32 v3, vcc, 0, v3, vcc
	global_load_dwordx4 v[38:41], v[6:7], off
	global_load_dwordx4 v[42:45], v[2:3], off
	v_add_co_u32_e32 v2, vcc, s12, v4
	s_waitcnt vmcnt(63) expcnt(7) lgkmcnt(15)
	s_nop 0
	v_addc_co_u32_e32 v3, vcc, 0, v5, vcc
	s_barrier
	global_load_dwordx4 v[46:49], v[4:5], off
	global_load_dwordx4 v[50:53], v[2:3], off
	v_add_co_u32_e32 v2, vcc, s13, v4
	s_mov_b32 s57, 0
	s_nop 0
	v_addc_co_u32_e32 v3, vcc, 0, v5, vcc
	v_add_co_u32_e32 v4, vcc, s14, v4
	s_mov_b64 s[8:9], 0
	s_nop 0
	v_addc_co_u32_e32 v5, vcc, 0, v5, vcc
	global_load_dwordx4 v[54:57], v[2:3], off
	global_load_dwordx4 v[58:61], v[4:5], off
	v_mov_b32_e32 v2, 0
	v_mov_b32_e32 v3, v2
	v_mov_b32_e32 v4, v2
	v_mov_b32_e32 v5, v2
	v_mov_b32_e32 v6, v2
	v_mov_b32_e32 v7, v2
	v_mov_b32_e32 v8, v2
	v_mov_b32_e32 v9, v2
	v_mov_b32_e32 v10, v2
	v_mov_b32_e32 v11, v2
	v_mov_b32_e32 v12, v2
	v_mov_b32_e32 v13, v2
	v_mov_b32_e32 v14, v2
	v_mov_b32_e32 v15, v2
	v_mov_b32_e32 v16, v2
	v_mov_b32_e32 v17, v2
	v_mov_b32_e32 v18, v2
	v_mov_b32_e32 v19, v2
	v_mov_b32_e32 v20, v2
	v_mov_b32_e32 v21, v2
	v_mov_b32_e32 v22, v2
	v_mov_b32_e32 v23, v2
	v_mov_b32_e32 v24, v2
	v_mov_b32_e32 v25, v2
	v_mov_b32_e32 v26, v2
	v_mov_b32_e32 v27, v2
	v_mov_b32_e32 v28, v2
	v_lshl_add_u64 v[136:137], v[134:135], 0, v[62:63]
	v_lshl_add_u64 v[138:139], v[134:135], 0, v[64:65]
	v_mov_b32_e32 v29, v2
	v_mov_b32_e32 v62, v2
	v_mov_b32_e32 v63, v2
	v_mov_b32_e32 v64, v2
	v_mov_b32_e32 v65, v2
	v_mov_b32_e32 v66, v2
	v_mov_b32_e32 v67, v2
	v_mov_b32_e32 v68, v2
	v_mov_b32_e32 v69, v2
	v_mov_b32_e32 v70, v2
	v_mov_b32_e32 v71, v2
	v_mov_b32_e32 v72, v2
	v_mov_b32_e32 v73, v2
	v_mov_b32_e32 v74, v2
	v_mov_b32_e32 v75, v2
	v_mov_b32_e32 v76, v2
	v_mov_b32_e32 v77, v2
	v_mov_b32_e32 v78, v2
	v_mov_b32_e32 v79, v2
	v_mov_b32_e32 v80, v2
	v_mov_b32_e32 v81, v2
	v_mov_b32_e32 v82, v2
	v_mov_b32_e32 v83, v2
	v_mov_b32_e32 v84, v2
	s_waitcnt vmcnt(7)
	ds_write_b128 v146, v[30:33]
	s_waitcnt vmcnt(6)
	ds_write_b128 v146, v[34:37] offset:8192
	s_waitcnt vmcnt(5)
	ds_write_b128 v146, v[38:41] offset:16384
	s_waitcnt vmcnt(4)
	ds_write_b128 v146, v[42:45] offset:24576
	s_waitcnt vmcnt(3)
	ds_write_b128 v147, v[46:49]
	s_waitcnt vmcnt(2)
	ds_write_b128 v147, v[50:53] offset:8192
	s_waitcnt vmcnt(1)
	ds_write_b128 v147, v[54:57] offset:16384
	s_waitcnt vmcnt(0)
	ds_write_b128 v147, v[58:61] offset:24576
	v_mov_b32_e32 v30, v2
	v_mov_b32_e32 v31, v2
	v_mov_b32_e32 v32, v2
	v_mov_b32_e32 v33, v2
	v_mov_b32_e32 v34, v2
	v_mov_b32_e32 v35, v2
	v_mov_b32_e32 v36, v2
	v_mov_b32_e32 v37, v2
	v_mov_b32_e32 v38, v2
	v_mov_b32_e32 v39, v2
	v_mov_b32_e32 v40, v2
	v_mov_b32_e32 v41, v2
	v_mov_b32_e32 v42, v2
	v_mov_b32_e32 v43, v2
	v_mov_b32_e32 v44, v2
	v_mov_b32_e32 v45, v2
	v_mov_b32_e32 v46, v2
	v_mov_b32_e32 v47, v2
	v_mov_b32_e32 v48, v2
	v_mov_b32_e32 v49, v2
	v_mov_b32_e32 v50, v2
	v_mov_b32_e32 v51, v2
	v_mov_b32_e32 v52, v2
	v_mov_b32_e32 v53, v2
	v_mov_b32_e32 v54, v2
	v_mov_b32_e32 v55, v2
	v_mov_b32_e32 v56, v2
	v_mov_b32_e32 v57, v2
	v_mov_b32_e32 v58, v2
	v_mov_b32_e32 v59, v2
	v_mov_b32_e32 v60, v2
	v_mov_b32_e32 v61, v2
	v_mov_b32_e32 v85, v2
	v_mov_b32_e32 v86, v2
	v_mov_b32_e32 v87, v2
	v_mov_b32_e32 v88, v2
	v_mov_b32_e32 v89, v2
	v_mov_b32_e32 v90, v2
	v_mov_b32_e32 v91, v2
	v_mov_b32_e32 v92, v2
	v_mov_b32_e32 v93, v2
	v_mov_b32_e32 v94, v2
	v_mov_b32_e32 v95, v2
	v_mov_b32_e32 v96, v2
	v_mov_b32_e32 v97, v2
	v_mov_b32_e32 v98, v2
	v_mov_b32_e32 v99, v2
	v_mov_b32_e32 v100, v2
	v_mov_b32_e32 v101, v2
	v_mov_b32_e32 v102, v2
	v_mov_b32_e32 v103, v2
	v_mov_b32_e32 v104, v2
	v_mov_b32_e32 v105, v2
	v_mov_b32_e32 v106, v2
	v_mov_b32_e32 v107, v2
	v_mov_b32_e32 v108, v2
	v_mov_b32_e32 v109, v2
	v_mov_b32_e32 v110, v2
	v_mov_b32_e32 v111, v2
	v_mov_b32_e32 v112, v2
	v_mov_b32_e32 v113, v2
	v_mov_b32_e32 v114, v2
	v_mov_b32_e32 v115, v2
	v_mov_b32_e32 v116, v2
	v_mov_b32_e32 v117, v2
	v_mov_b32_e32 v118, v2
	v_mov_b32_e32 v119, v2
	v_mov_b32_e32 v120, v2
	v_mov_b32_e32 v121, v2
	v_mov_b32_e32 v122, v2
	v_mov_b32_e32 v123, v2
	v_mov_b32_e32 v124, v2
	v_mov_b32_e32 v125, v2
	v_mov_b32_e32 v126, v2
	v_mov_b32_e32 v127, v2
	v_mov_b32_e32 v128, v2
	v_mov_b32_e32 v129, v2
	s_waitcnt lgkmcnt(0)
	s_barrier
	v_readfirstlane_b32 s98, v136
	v_readfirstlane_b32 s99, v137
	v_subrev_u32_e32 v248, s98, v136
	s_add_u32 s98, s98, s8
	s_addc_u32 s99, s99, s9
	v_readfirstlane_b32 s100, v138
	v_readfirstlane_b32 s101, v139
	v_subrev_u32_e32 v250, s100, v138
	s_add_u32 s100, s100, s8
	s_addc_u32 s101, s101, s9
	v_add_u32_e32 v142, s15, v248
	v_add_u32_e32 v144, s16, v248
	v_add_u32_e32 v156, s17, v248
	v_add_u32_e32 v160, s28, v248
	global_load_dwordx4 v[140:143], v142, s[98:99] offset:128
	global_load_dwordx4 v[152:155], v144, s[98:99] offset:128
	global_load_dwordx4 v[156:159], v156, s[98:99] offset:128
	global_load_dwordx4 v[160:163], v160, s[98:99] offset:128
	v_add_u32_e32 v164, s29, v250
	v_add_u32_e32 v168, s38, v250
	v_add_u32_e32 v172, s39, v250
	v_add_u32_e32 v144, s42, v250
	global_load_dwordx4 v[164:167], v164, s[100:101] offset:128
	global_load_dwordx4 v[168:171], v168, s[100:101] offset:128
	global_load_dwordx4 v[172:175], v172, s[100:101] offset:128
	global_load_dwordx4 v[176:179], v144, s[100:101] offset:128
	v_mov_b32_e32 v223, v148
	v_mov_b32_e32 v249, v149
	v_xor_b32_e32 v251, 0x8000, v146
	v_xor_b32_e32 v252, 0x8000, v147
	ds_read_b128 v[180:183], v223
	ds_read_b128 v[184:187], v223 offset:2048
	ds_read_b128 v[188:191], v223 offset:4096
	ds_read_b128 v[192:195], v223 offset:6144
	ds_read_b128 v[212:215], v249
	ds_read_b128 v[218:221], v249 offset:2048
	ds_read_b128 v[224:227], v249 offset:4096
	ds_read_b128 v[228:231], v249 offset:6144
.Lg2_p4_loop:
	ds_read_b128 v[196:199], v223 offset:8192
	ds_read_b128 v[200:203], v223 offset:10240
	ds_read_b128 v[204:207], v223 offset:12288
	ds_read_b128 v[208:211], v223 offset:14336
	s_waitcnt lgkmcnt(4)
	v_mfma_f32_16x16x32_bf16 v[126:129], v[212:215], v[180:183], v[126:129]
	v_mfma_f32_16x16x32_bf16 v[122:125], v[218:221], v[180:183], v[122:125]
	v_mfma_f32_16x16x32_bf16 v[118:121], v[224:227], v[180:183], v[118:121]
	v_mfma_f32_16x16x32_bf16 v[114:117], v[228:231], v[180:183], v[114:117]
	v_mfma_f32_16x16x32_bf16 v[110:113], v[212:215], v[184:187], v[110:113]
	v_mfma_f32_16x16x32_bf16 v[106:109], v[218:221], v[184:187], v[106:109]
	v_mfma_f32_16x16x32_bf16 v[102:105], v[224:227], v[184:187], v[102:105]
	v_mfma_f32_16x16x32_bf16 v[98:101], v[228:231], v[184:187], v[98:101]
	v_mfma_f32_16x16x32_bf16 v[94:97], v[212:215], v[188:191], v[94:97]
	v_mfma_f32_16x16x32_bf16 v[90:93], v[218:221], v[188:191], v[90:93]
	v_mfma_f32_16x16x32_bf16 v[86:89], v[224:227], v[188:191], v[86:89]
	v_mfma_f32_16x16x32_bf16 v[82:85], v[228:231], v[188:191], v[82:85]
	v_mfma_f32_16x16x32_bf16 v[78:81], v[212:215], v[192:195], v[78:81]
	v_mfma_f32_16x16x32_bf16 v[74:77], v[218:221], v[192:195], v[74:77]
	v_mfma_f32_16x16x32_bf16 v[70:73], v[224:227], v[192:195], v[70:73]
	v_mfma_f32_16x16x32_bf16 v[66:69], v[228:231], v[192:195], v[66:69]
	ds_read_b128 v[180:183], v216
	ds_read_b128 v[184:187], v216 offset:2048
	ds_read_b128 v[188:191], v216 offset:4096
	ds_read_b128 v[192:195], v216 offset:6144
	ds_read_b128 v[232:235], v217
	ds_read_b128 v[236:239], v217 offset:2048
	ds_read_b128 v[240:243], v217 offset:4096
	ds_read_b128 v[244:247], v217 offset:6144
	s_waitcnt lgkmcnt(8)
	v_mfma_f32_16x16x32_bf16 v[62:65], v[212:215], v[196:199], v[62:65]
	v_mfma_f32_16x16x32_bf16 v[58:61], v[218:221], v[196:199], v[58:61]
	v_mfma_f32_16x16x32_bf16 v[54:57], v[224:227], v[196:199], v[54:57]
	v_mfma_f32_16x16x32_bf16 v[50:53], v[228:231], v[196:199], v[50:53]
	v_mfma_f32_16x16x32_bf16 v[46:49], v[212:215], v[200:203], v[46:49]
	v_mfma_f32_16x16x32_bf16 v[42:45], v[218:221], v[200:203], v[42:45]
	v_mfma_f32_16x16x32_bf16 v[38:41], v[224:227], v[200:203], v[38:41]
	v_mfma_f32_16x16x32_bf16 v[34:37], v[228:231], v[200:203], v[34:37]
	v_mfma_f32_16x16x32_bf16 v[30:33], v[212:215], v[204:207], v[30:33]
	v_mfma_f32_16x16x32_bf16 v[26:29], v[218:221], v[204:207], v[26:29]
	v_mfma_f32_16x16x32_bf16 v[22:25], v[224:227], v[204:207], v[22:25]
	v_mfma_f32_16x16x32_bf16 v[18:21], v[228:231], v[204:207], v[18:21]
	v_mfma_f32_16x16x32_bf16 v[14:17], v[212:215], v[208:211], v[14:17]
	v_mfma_f32_16x16x32_bf16 v[10:13], v[218:221], v[208:211], v[10:13]
	v_mfma_f32_16x16x32_bf16 v[6:9], v[224:227], v[208:211], v[6:9]
	v_mfma_f32_16x16x32_bf16 v[2:5], v[228:231], v[208:211], v[2:5]
	ds_read_b128 v[196:199], v216 offset:8192
	ds_read_b128 v[200:203], v216 offset:10240
	ds_read_b128 v[204:207], v216 offset:12288
	ds_read_b128 v[208:211], v216 offset:14336
	s_waitcnt lgkmcnt(4)
	v_mfma_f32_16x16x32_bf16 v[126:129], v[232:235], v[180:183], v[126:129]
	v_mfma_f32_16x16x32_bf16 v[122:125], v[236:239], v[180:183], v[122:125]
	s_waitcnt vmcnt(7)
	ds_write_b128 v251, v[140:143]
	v_mfma_f32_16x16x32_bf16 v[118:121], v[240:243], v[180:183], v[118:121]
	v_mfma_f32_16x16x32_bf16 v[114:117], v[244:247], v[180:183], v[114:117]
	s_waitcnt vmcnt(6)
	ds_write_b128 v251, v[152:155] offset:8192
	v_mfma_f32_16x16x32_bf16 v[110:113], v[232:235], v[184:187], v[110:113]
	v_mfma_f32_16x16x32_bf16 v[106:109], v[236:239], v[184:187], v[106:109]
	s_waitcnt vmcnt(5)
	ds_write_b128 v251, v[156:159] offset:16384
	v_mfma_f32_16x16x32_bf16 v[102:105], v[240:243], v[184:187], v[102:105]
	v_mfma_f32_16x16x32_bf16 v[98:101], v[244:247], v[184:187], v[98:101]
	s_waitcnt vmcnt(4)
	ds_write_b128 v251, v[160:163] offset:24576
	v_mfma_f32_16x16x32_bf16 v[94:97], v[232:235], v[188:191], v[94:97]
	v_mfma_f32_16x16x32_bf16 v[90:93], v[236:239], v[188:191], v[90:93]
	s_waitcnt vmcnt(3)
	ds_write_b128 v252, v[164:167]
	v_mfma_f32_16x16x32_bf16 v[86:89], v[240:243], v[188:191], v[86:89]
	v_mfma_f32_16x16x32_bf16 v[82:85], v[244:247], v[188:191], v[82:85]
	s_waitcnt vmcnt(2)
	ds_write_b128 v252, v[168:171] offset:8192
	v_mfma_f32_16x16x32_bf16 v[78:81], v[232:235], v[192:195], v[78:81]
	v_mfma_f32_16x16x32_bf16 v[74:77], v[236:239], v[192:195], v[74:77]
	s_waitcnt vmcnt(1)
	ds_write_b128 v252, v[172:175] offset:16384
	v_mfma_f32_16x16x32_bf16 v[70:73], v[240:243], v[192:195], v[70:73]
	v_mfma_f32_16x16x32_bf16 v[66:69], v[244:247], v[192:195], v[66:69]
	s_waitcnt vmcnt(0)
	ds_write_b128 v252, v[176:179] offset:24576
	s_waitcnt lgkmcnt(0)
	s_barrier
	s_add_u32 s8, s8, 0x80
	s_addc_u32 s9, s9, 0
	s_add_u32 s98, s98, 0x80
	s_addc_u32 s99, s99, 0
	s_add_u32 s100, s100, 0x80
	s_addc_u32 s101, s101, 0
	s_cmpk_eq_i32 s8, 0x780
	s_cbranch_scc1 .Lg2_p4_tail
	v_xor_b32_e32 v223, 0x8000, v223
	v_xor_b32_e32 v249, 0x8000, v249
	v_xor_b32_e32 v216, 0x8000, v216
	v_xor_b32_e32 v217, 0x8000, v217
	v_xor_b32_e32 v251, 0x8000, v251
	v_xor_b32_e32 v252, 0x8000, v252
	ds_read_b128 v[180:183], v223
	ds_read_b128 v[184:187], v223 offset:2048
	ds_read_b128 v[188:191], v223 offset:4096
	ds_read_b128 v[192:195], v223 offset:6144
	ds_read_b128 v[212:215], v249
	ds_read_b128 v[218:221], v249 offset:2048
	ds_read_b128 v[224:227], v249 offset:4096
	ds_read_b128 v[228:231], v249 offset:6144
	v_mfma_f32_16x16x32_bf16 v[62:65], v[232:235], v[196:199], v[62:65]
	v_add_u32_e32 v142, s15, v248
	v_mfma_f32_16x16x32_bf16 v[58:61], v[236:239], v[196:199], v[58:61]
	v_add_u32_e32 v144, s16, v248
	v_mfma_f32_16x16x32_bf16 v[54:57], v[240:243], v[196:199], v[54:57]
	v_add_u32_e32 v156, s17, v248
	v_mfma_f32_16x16x32_bf16 v[50:53], v[244:247], v[196:199], v[50:53]
	v_add_u32_e32 v160, s28, v248
	v_mfma_f32_16x16x32_bf16 v[46:49], v[232:235], v[200:203], v[46:49]
	global_load_dwordx4 v[140:143], v142, s[98:99] offset:128
	v_mfma_f32_16x16x32_bf16 v[42:45], v[236:239], v[200:203], v[42:45]
	global_load_dwordx4 v[152:155], v144, s[98:99] offset:128
	v_mfma_f32_16x16x32_bf16 v[38:41], v[240:243], v[200:203], v[38:41]
	global_load_dwordx4 v[156:159], v156, s[98:99] offset:128
	v_mfma_f32_16x16x32_bf16 v[34:37], v[244:247], v[200:203], v[34:37]
	global_load_dwordx4 v[160:163], v160, s[98:99] offset:128
	v_mfma_f32_16x16x32_bf16 v[30:33], v[232:235], v[204:207], v[30:33]
	v_add_u32_e32 v164, s29, v250
	v_mfma_f32_16x16x32_bf16 v[26:29], v[236:239], v[204:207], v[26:29]
	v_add_u32_e32 v168, s38, v250
	v_mfma_f32_16x16x32_bf16 v[22:25], v[240:243], v[204:207], v[22:25]
	v_add_u32_e32 v172, s39, v250
	v_mfma_f32_16x16x32_bf16 v[18:21], v[244:247], v[204:207], v[18:21]
	v_add_u32_e32 v144, s42, v250
	v_mfma_f32_16x16x32_bf16 v[14:17], v[232:235], v[208:211], v[14:17]
	global_load_dwordx4 v[164:167], v164, s[100:101] offset:128
	v_mfma_f32_16x16x32_bf16 v[10:13], v[236:239], v[208:211], v[10:13]
	global_load_dwordx4 v[168:171], v168, s[100:101] offset:128
	v_mfma_f32_16x16x32_bf16 v[6:9], v[240:243], v[208:211], v[6:9]
	global_load_dwordx4 v[172:175], v172, s[100:101] offset:128
	v_mfma_f32_16x16x32_bf16 v[2:5], v[244:247], v[208:211], v[2:5]
	global_load_dwordx4 v[176:179], v144, s[100:101] offset:128
	s_branch .Lg2_p4_loop
.Lg2_p4_tail:
	v_xor_b32_e32 v216, 64, v148
	v_xor_b32_e32 v217, 64, v149
	v_mfma_f32_16x16x32_bf16 v[62:65], v[232:235], v[196:199], v[62:65]
	v_mfma_f32_16x16x32_bf16 v[58:61], v[236:239], v[196:199], v[58:61]
	v_mfma_f32_16x16x32_bf16 v[54:57], v[240:243], v[196:199], v[54:57]
	v_mfma_f32_16x16x32_bf16 v[50:53], v[244:247], v[196:199], v[50:53]
	v_mfma_f32_16x16x32_bf16 v[46:49], v[232:235], v[200:203], v[46:49]
	v_mfma_f32_16x16x32_bf16 v[42:45], v[236:239], v[200:203], v[42:45]
	v_mfma_f32_16x16x32_bf16 v[38:41], v[240:243], v[200:203], v[38:41]
	v_mfma_f32_16x16x32_bf16 v[34:37], v[244:247], v[200:203], v[34:37]
	v_mfma_f32_16x16x32_bf16 v[30:33], v[232:235], v[204:207], v[30:33]
	v_mfma_f32_16x16x32_bf16 v[26:29], v[236:239], v[204:207], v[26:29]
	v_mfma_f32_16x16x32_bf16 v[22:25], v[240:243], v[204:207], v[22:25]
	v_mfma_f32_16x16x32_bf16 v[18:21], v[244:247], v[204:207], v[18:21]
	v_mfma_f32_16x16x32_bf16 v[14:17], v[232:235], v[208:211], v[14:17]
	v_mfma_f32_16x16x32_bf16 v[10:13], v[236:239], v[208:211], v[10:13]
	v_mfma_f32_16x16x32_bf16 v[6:9], v[240:243], v[208:211], v[6:9]
	v_mfma_f32_16x16x32_bf16 v[2:5], v[244:247], v[208:211], v[2:5]
	ds_read_b128 v[136:139], v149 offset:32768
	ds_read_b128 v[140:143], v149 offset:34816
	ds_read_b128 v[152:155], v149 offset:36864
	ds_read_b128 v[156:159], v149 offset:38912
	ds_read_b128 v[160:163], v148 offset:32768
	ds_read_b128 v[164:167], v148 offset:34816
	ds_read_b128 v[168:171], v148 offset:36864
	ds_read_b128 v[172:175], v148 offset:38912
	s_setprio 1
	s_waitcnt lgkmcnt(3)
	v_mfma_f32_16x16x32_bf16 v[126:129], v[136:139], v[160:163], v[126:129]
	v_mfma_f32_16x16x32_bf16 v[122:125], v[140:143], v[160:163], v[122:125]
	v_mfma_f32_16x16x32_bf16 v[118:121], v[152:155], v[160:163], v[118:121]
	v_mfma_f32_16x16x32_bf16 v[114:117], v[156:159], v[160:163], v[114:117]
	s_waitcnt lgkmcnt(2)
	v_mfma_f32_16x16x32_bf16 v[110:113], v[136:139], v[164:167], v[110:113]
	v_mfma_f32_16x16x32_bf16 v[106:109], v[140:143], v[164:167], v[106:109]
	v_mfma_f32_16x16x32_bf16 v[102:105], v[152:155], v[164:167], v[102:105]
	v_mfma_f32_16x16x32_bf16 v[98:101], v[156:159], v[164:167], v[98:101]
	s_waitcnt lgkmcnt(1)
	v_mfma_f32_16x16x32_bf16 v[94:97], v[136:139], v[168:171], v[94:97]
	v_mfma_f32_16x16x32_bf16 v[90:93], v[140:143], v[168:171], v[90:93]
	v_mfma_f32_16x16x32_bf16 v[86:89], v[152:155], v[168:171], v[86:89]
	v_mfma_f32_16x16x32_bf16 v[82:85], v[156:159], v[168:171], v[82:85]
	s_waitcnt lgkmcnt(0)
	v_mfma_f32_16x16x32_bf16 v[78:81], v[136:139], v[172:175], v[78:81]
	v_mfma_f32_16x16x32_bf16 v[74:77], v[140:143], v[172:175], v[74:77]
	v_mfma_f32_16x16x32_bf16 v[70:73], v[152:155], v[172:175], v[70:73]
	v_mfma_f32_16x16x32_bf16 v[66:69], v[156:159], v[172:175], v[66:69]
	s_setprio 0
	ds_read_b128 v[160:163], v148 offset:40960
	ds_read_b128 v[164:167], v148 offset:43008
	ds_read_b128 v[168:171], v148 offset:45056
	ds_read_b128 v[172:175], v148 offset:47104
	s_setprio 1
	s_waitcnt lgkmcnt(3)
	v_mfma_f32_16x16x32_bf16 v[62:65], v[136:139], v[160:163], v[62:65]
	v_mfma_f32_16x16x32_bf16 v[58:61], v[140:143], v[160:163], v[58:61]
	v_mfma_f32_16x16x32_bf16 v[54:57], v[152:155], v[160:163], v[54:57]
	v_mfma_f32_16x16x32_bf16 v[50:53], v[156:159], v[160:163], v[50:53]
	s_waitcnt lgkmcnt(2)
	v_mfma_f32_16x16x32_bf16 v[46:49], v[136:139], v[164:167], v[46:49]
	v_mfma_f32_16x16x32_bf16 v[42:45], v[140:143], v[164:167], v[42:45]
	v_mfma_f32_16x16x32_bf16 v[38:41], v[152:155], v[164:167], v[38:41]
	v_mfma_f32_16x16x32_bf16 v[34:37], v[156:159], v[164:167], v[34:37]
	s_waitcnt lgkmcnt(1)
	v_mfma_f32_16x16x32_bf16 v[30:33], v[136:139], v[168:171], v[30:33]
	v_mfma_f32_16x16x32_bf16 v[26:29], v[140:143], v[168:171], v[26:29]
	v_mfma_f32_16x16x32_bf16 v[22:25], v[152:155], v[168:171], v[22:25]
	v_mfma_f32_16x16x32_bf16 v[18:21], v[156:159], v[168:171], v[18:21]
	s_waitcnt lgkmcnt(0)
	v_mfma_f32_16x16x32_bf16 v[14:17], v[136:139], v[172:175], v[14:17]
	v_mfma_f32_16x16x32_bf16 v[10:13], v[140:143], v[172:175], v[10:13]
	v_mfma_f32_16x16x32_bf16 v[6:9], v[152:155], v[172:175], v[6:9]
	v_mfma_f32_16x16x32_bf16 v[2:5], v[156:159], v[172:175], v[2:5]
	s_setprio 0
	ds_read_b128 v[136:139], v217 offset:32768
	ds_read_b128 v[140:143], v217 offset:34816
	ds_read_b128 v[152:155], v217 offset:36864
	ds_read_b128 v[156:159], v217 offset:38912
	ds_read_b128 v[160:163], v216 offset:32768
	ds_read_b128 v[164:167], v216 offset:34816
	ds_read_b128 v[168:171], v216 offset:36864
	ds_read_b128 v[172:175], v216 offset:38912
	s_setprio 1
	s_waitcnt lgkmcnt(3)
	v_mfma_f32_16x16x32_bf16 v[126:129], v[136:139], v[160:163], v[126:129]
	v_mfma_f32_16x16x32_bf16 v[122:125], v[140:143], v[160:163], v[122:125]
	v_mfma_f32_16x16x32_bf16 v[118:121], v[152:155], v[160:163], v[118:121]
	v_mfma_f32_16x16x32_bf16 v[114:117], v[156:159], v[160:163], v[114:117]
	s_waitcnt lgkmcnt(2)
	v_mfma_f32_16x16x32_bf16 v[110:113], v[136:139], v[164:167], v[110:113]
	v_mfma_f32_16x16x32_bf16 v[106:109], v[140:143], v[164:167], v[106:109]
	v_mfma_f32_16x16x32_bf16 v[102:105], v[152:155], v[164:167], v[102:105]
	v_mfma_f32_16x16x32_bf16 v[98:101], v[156:159], v[164:167], v[98:101]
	s_waitcnt lgkmcnt(1)
	v_mfma_f32_16x16x32_bf16 v[94:97], v[136:139], v[168:171], v[94:97]
	v_mfma_f32_16x16x32_bf16 v[90:93], v[140:143], v[168:171], v[90:93]
	v_mfma_f32_16x16x32_bf16 v[86:89], v[152:155], v[168:171], v[86:89]
	v_mfma_f32_16x16x32_bf16 v[82:85], v[156:159], v[168:171], v[82:85]
	s_waitcnt lgkmcnt(0)
	v_mfma_f32_16x16x32_bf16 v[78:81], v[136:139], v[172:175], v[78:81]
	v_mfma_f32_16x16x32_bf16 v[74:77], v[140:143], v[172:175], v[74:77]
	v_mfma_f32_16x16x32_bf16 v[70:73], v[152:155], v[172:175], v[70:73]
	v_mfma_f32_16x16x32_bf16 v[66:69], v[156:159], v[172:175], v[66:69]
	s_setprio 0
	ds_read_b128 v[160:163], v216 offset:40960
	ds_read_b128 v[164:167], v216 offset:43008
	ds_read_b128 v[168:171], v216 offset:45056
	ds_read_b128 v[172:175], v216 offset:47104
	s_setprio 1
	s_waitcnt lgkmcnt(3)
	v_mfma_f32_16x16x32_bf16 v[62:65], v[136:139], v[160:163], v[62:65]
	v_mfma_f32_16x16x32_bf16 v[58:61], v[140:143], v[160:163], v[58:61]
	v_mfma_f32_16x16x32_bf16 v[54:57], v[152:155], v[160:163], v[54:57]
	v_mfma_f32_16x16x32_bf16 v[50:53], v[156:159], v[160:163], v[50:53]
	s_waitcnt lgkmcnt(2)
	v_mfma_f32_16x16x32_bf16 v[46:49], v[136:139], v[164:167], v[46:49]
	v_mfma_f32_16x16x32_bf16 v[42:45], v[140:143], v[164:167], v[42:45]
	v_mfma_f32_16x16x32_bf16 v[38:41], v[152:155], v[164:167], v[38:41]
	v_mfma_f32_16x16x32_bf16 v[34:37], v[156:159], v[164:167], v[34:37]
	s_waitcnt lgkmcnt(1)
	v_mfma_f32_16x16x32_bf16 v[30:33], v[136:139], v[168:171], v[30:33]
	v_mfma_f32_16x16x32_bf16 v[26:29], v[140:143], v[168:171], v[26:29]
	v_mfma_f32_16x16x32_bf16 v[22:25], v[152:155], v[168:171], v[22:25]
	v_mfma_f32_16x16x32_bf16 v[18:21], v[156:159], v[168:171], v[18:21]
	s_waitcnt lgkmcnt(0)
	v_mfma_f32_16x16x32_bf16 v[14:17], v[136:139], v[172:175], v[14:17]
	v_mfma_f32_16x16x32_bf16 v[10:13], v[140:143], v[172:175], v[10:13]
	v_mfma_f32_16x16x32_bf16 v[6:9], v[152:155], v[172:175], v[6:9]
	v_mfma_f32_16x16x32_bf16 v[2:5], v[156:159], v[172:175], v[2:5]
	s_setprio 0
	v_add_u32_e32 v152, s56, v150
	v_mul_hi_i32 v136, v152, s43
	v_lshrrev_b32_e32 v137, 31, v136
	v_ashrrev_i32_e32 v136, 11, v136
	v_add_u32_e32 v139, v136, v137
	v_mad_i32_i24 v142, v139, s44, v152
	v_lshlrev_b32_e32 v141, 13, v139
	v_cmp_lt_i32_e32 vcc, s45, v142
	v_mov_b64_e32 v[136:137], s[40:41]
	v_add3_u32 v138, v141, v142, s46
	s_barrier
	s_and_saveexec_b64 s[8:9], vcc
	s_xor_b64 s[8:9], exec, s[8:9]
	s_cbranch_execz .LBB0_252
	v_add3_u32 v140, v141, v142, s46
	v_mov_b64_e32 v[136:137], s[36:37]
	s_or_saveexec_b64 s[8:9], s[8:9]
	v_lshl_add_u32 v141, v139, 8, v142
	s_xor_b64 exec, exec, s[8:9]
	s_branch .LBB0_253

.LBB0_354:
	s_mul_hi_i32 s0, s3, 0x2e8ba2e9
	s_lshr_b32 s1, s0, 31
	s_ashr_i32 s0, s0, 4
	s_add_i32 s40, s0, s1
	s_lshl_b32 s0, s40, 2
	s_sub_i32 s1, 33, s0
	s_min_u32 s1, s1, 4
	v_cvt_f32_ubyte0_e32 v2, s1
	v_rcp_iflag_f32_e32 v2, v2
	s_sub_i32 s41, 0, s1
	s_mul_i32 s37, s40, 0xffffffa8
	s_add_i32 s37, s37, s3
	v_mul_f32_e32 v2, 0x4f7ffffe, v2
	v_cvt_u32_f32_e32 v2, v2
	s_abs_i32 s39, s37
	s_ashr_i32 s38, s37, 31
	s_mulk_i32 s40, 0x54
	v_readfirstlane_b32 s42, v2
	s_mul_i32 s41, s41, s42
	s_mul_hi_u32 s41, s42, s41
	s_add_i32 s42, s42, s41
	s_mul_hi_u32 s41, s39, s42
	s_mul_i32 s42, s41, s1
	s_sub_i32 s39, s39, s42
	s_add_i32 s42, s41, 1
	s_sub_i32 s43, s39, s1
	s_cmp_ge_u32 s39, s1
	s_cselect_b32 s41, s42, s41
	s_cselect_b32 s39, s43, s39
	s_add_i32 s42, s41, 1
	s_cmp_ge_u32 s39, s1
	s_cselect_b32 s39, s42, s41
	s_xor_b32 s39, s39, s38
	s_sub_i32 s38, s39, s38
	s_add_i32 s0, s0, s6
	s_mul_i32 s41, s1, s38
	s_add_i32 s0, s0, s37
	s_sub_i32 s0, s0, s41
	s_lshl_b32 s37, s0, 8
	v_or_b32_e32 v2, s37, v1
	v_ashrrev_i32_e32 v3, 31, v2
	v_lshlrev_b64 v[2:3], 11, v[2:3]
	v_lshl_add_u64 v[2:3], v[132:133], 0, v[2:3]
	v_add_co_u32_e32 v6, vcc, s9, v2
	s_lshl_b32 s38, s38, 8
	s_nop 0
	v_addc_co_u32_e32 v7, vcc, 0, v3, vcc
	v_or_b32_e32 v4, s38, v1
	global_load_dwordx4 v[20:23], v[2:3], off
	global_load_dwordx4 v[24:27], v[6:7], off
	v_add_co_u32_e32 v6, vcc, s10, v2
	v_ashrrev_i32_e32 v5, 31, v4
	s_nop 0
	v_addc_co_u32_e32 v7, vcc, 0, v3, vcc
	v_lshlrev_b64 v[52:53], 11, v[4:5]
	v_add_co_u32_e32 v2, vcc, s11, v2
	v_lshl_add_u64 v[4:5], v[134:135], 0, v[52:53]
	s_nop 0
	v_addc_co_u32_e32 v3, vcc, 0, v3, vcc
	global_load_dwordx4 v[28:31], v[6:7], off
	global_load_dwordx4 v[32:35], v[2:3], off
	v_add_co_u32_e32 v2, vcc, s9, v4
	s_waitcnt vmcnt(63) expcnt(7) lgkmcnt(15)
	s_nop 0
	v_addc_co_u32_e32 v3, vcc, 0, v5, vcc
	s_barrier
	global_load_dwordx4 v[36:39], v[4:5], off
	global_load_dwordx4 v[40:43], v[2:3], off
	v_add_co_u32_e32 v2, vcc, s10, v4
	s_sub_i32 s41, s8, s41
	s_nop 0
	v_addc_co_u32_e32 v3, vcc, 0, v5, vcc
	v_add_co_u32_e32 v4, vcc, s11, v4
	s_sub_i32 s40, s41, s40
	s_nop 0
	v_addc_co_u32_e32 v5, vcc, 0, v5, vcc
	global_load_dwordx4 v[44:47], v[2:3], off
	global_load_dwordx4 v[48:51], v[4:5], off
	v_lshl_add_u32 v54, s40, 8, v1
	v_ashrrev_i32_e32 v55, 31, v54
	v_lshl_add_u64 v[140:141], v[138:139], 0, v[52:53]
	v_lshlrev_b64 v[52:53], 11, v[54:55]
	s_mov_b64 s[0:1], 0
	s_mov_b32 s39, 0
	v_mov_b32_e32 v2, 0
	v_mov_b32_e32 v3, v131
	v_mov_b32_e32 v4, v131
	v_mov_b32_e32 v5, v131
	v_mov_b32_e32 v6, 0
	v_mov_b32_e32 v7, v131
	v_mov_b32_e32 v8, v131
	v_mov_b32_e32 v9, v131
	v_mov_b32_e32 v10, 0
	v_mov_b32_e32 v11, v131
	v_mov_b32_e32 v12, v131
	v_mov_b32_e32 v13, v131
	v_mov_b32_e32 v14, 0
	v_mov_b32_e32 v15, v131
	v_mov_b32_e32 v16, v131
	v_mov_b32_e32 v17, v131
	v_mov_b32_e32 v18, 0
	v_lshl_add_u64 v[142:143], v[138:139], 0, v[52:53]
	v_mov_b32_e32 v19, v131
	v_mov_b32_e32 v52, v131
	v_mov_b32_e32 v53, v131
	v_mov_b32_e32 v54, 0
	v_mov_b32_e32 v55, v131
	v_mov_b32_e32 v56, v131
	v_mov_b32_e32 v57, v131
	v_mov_b32_e32 v58, 0
	v_mov_b32_e32 v59, v131
	v_mov_b32_e32 v60, v131
	v_mov_b32_e32 v61, v131
	v_mov_b32_e32 v62, 0
	v_mov_b32_e32 v63, v131
	v_mov_b32_e32 v64, v131
	v_mov_b32_e32 v65, v131
	v_mov_b32_e32 v66, 0
	v_mov_b32_e32 v67, v131
	v_mov_b32_e32 v68, v131
	v_mov_b32_e32 v69, v131
	v_mov_b32_e32 v70, 0
	v_mov_b32_e32 v71, v131
	v_mov_b32_e32 v72, v131
	v_mov_b32_e32 v73, v131
	v_mov_b32_e32 v74, 0
	s_waitcnt vmcnt(7)
	ds_write_b128 v144, v[20:23]
	s_waitcnt vmcnt(6)
	ds_write_b128 v144, v[24:27] offset:8192
	s_waitcnt vmcnt(5)
	ds_write_b128 v144, v[28:31] offset:16384
	s_waitcnt vmcnt(4)
	ds_write_b128 v144, v[32:35] offset:24576
	s_waitcnt vmcnt(3)
	ds_write_b128 v145, v[36:39]
	s_waitcnt vmcnt(2)
	ds_write_b128 v145, v[40:43] offset:8192
	s_waitcnt vmcnt(1)
	ds_write_b128 v145, v[44:47] offset:16384
	s_waitcnt vmcnt(0)
	ds_write_b128 v145, v[48:51] offset:24576
	v_mov_b32_e32 v20, v131
	v_mov_b32_e32 v21, v131
	v_mov_b32_e32 v22, 0
	v_mov_b32_e32 v23, v131
	v_mov_b32_e32 v24, v131
	v_mov_b32_e32 v25, v131
	v_mov_b32_e32 v26, 0
	v_mov_b32_e32 v27, v131
	v_mov_b32_e32 v28, v131
	v_mov_b32_e32 v29, v131
	v_mov_b32_e32 v30, 0
	v_mov_b32_e32 v31, v131
	v_mov_b32_e32 v32, v131
	v_mov_b32_e32 v33, v131
	v_mov_b32_e32 v34, 0
	v_mov_b32_e32 v35, v131
	v_mov_b32_e32 v36, v131
	v_mov_b32_e32 v37, v131
	v_mov_b32_e32 v38, 0
	v_mov_b32_e32 v39, v131
	v_mov_b32_e32 v40, v131
	v_mov_b32_e32 v41, v131
	v_mov_b32_e32 v42, 0
	v_mov_b32_e32 v43, v131
	v_mov_b32_e32 v44, v131
	v_mov_b32_e32 v45, v131
	v_mov_b32_e32 v46, 0
	v_mov_b32_e32 v47, v131
	v_mov_b32_e32 v48, v131
	v_mov_b32_e32 v49, v131
	v_mov_b32_e32 v50, 0
	v_mov_b32_e32 v51, v131
	v_mov_b32_e32 v75, v131
	v_mov_b32_e32 v76, v131
	v_mov_b32_e32 v77, v131
	v_mov_b32_e32 v78, 0
	v_mov_b32_e32 v79, v131
	v_mov_b32_e32 v80, v131
	v_mov_b32_e32 v81, v131
	v_mov_b32_e32 v82, 0
	v_mov_b32_e32 v83, v131
	v_mov_b32_e32 v84, v131
	v_mov_b32_e32 v85, v131
	v_mov_b32_e32 v86, 0
	v_mov_b32_e32 v87, v131
	v_mov_b32_e32 v88, v131
	v_mov_b32_e32 v89, v131
	v_mov_b32_e32 v90, 0
	v_mov_b32_e32 v91, v131
	v_mov_b32_e32 v92, v131
	v_mov_b32_e32 v93, v131
	v_mov_b32_e32 v94, 0
	v_mov_b32_e32 v95, v131
	v_mov_b32_e32 v96, v131
	v_mov_b32_e32 v97, v131
	v_mov_b32_e32 v98, 0
	v_mov_b32_e32 v99, v131
	v_mov_b32_e32 v100, v131
	v_mov_b32_e32 v101, v131
	v_mov_b32_e32 v102, 0
	v_mov_b32_e32 v103, v131
	v_mov_b32_e32 v104, v131
	v_mov_b32_e32 v105, v131
	v_mov_b32_e32 v106, 0
	v_mov_b32_e32 v107, v131
	v_mov_b32_e32 v108, v131
	v_mov_b32_e32 v109, v131
	v_mov_b32_e32 v110, 0
	v_mov_b32_e32 v111, v131
	v_mov_b32_e32 v112, v131
	v_mov_b32_e32 v113, v131
	v_mov_b32_e32 v114, 0
	v_mov_b32_e32 v115, v131
	v_mov_b32_e32 v116, v131
	v_mov_b32_e32 v117, v131
	v_mov_b32_e32 v118, 0
	v_mov_b32_e32 v119, v131
	v_mov_b32_e32 v120, v131
	v_mov_b32_e32 v121, v131
	v_mov_b32_e32 v122, 0
	v_mov_b32_e32 v123, v131
	v_mov_b32_e32 v124, v131
	v_mov_b32_e32 v125, v131
	v_mov_b32_e32 v126, 0
	v_mov_b32_e32 v127, v131
	v_mov_b32_e32 v128, v131
	v_mov_b32_e32 v129, v131
	s_waitcnt lgkmcnt(0)
	s_barrier
	v_readfirstlane_b32 s98, v142
	v_readfirstlane_b32 s99, v143
	v_subrev_u32_e32 v215, s98, v142
	s_add_u32 s98, s98, s0
	s_addc_u32 s99, s99, s1
	v_readfirstlane_b32 s100, v140
	v_readfirstlane_b32 s101, v141
	v_subrev_u32_e32 v252, s100, v140
	s_add_u32 s100, s100, s0
	s_addc_u32 s101, s101, s1
	v_add_u32_e32 v152, s12, v215
	v_add_u32_e32 v154, s13, v215
	v_add_u32_e32 v158, s14, v215
	v_add_u32_e32 v162, s15, v215
	global_load_dwordx4 v[150:153], v152, s[98:99] offset:128
	global_load_dwordx4 v[154:157], v154, s[98:99] offset:128
	global_load_dwordx4 v[158:161], v158, s[98:99] offset:128
	global_load_dwordx4 v[162:165], v162, s[98:99] offset:128
	v_add_u32_e32 v166, s16, v252
	v_add_u32_e32 v170, s17, v252
	v_add_u32_e32 v176, s28, v252
	v_add_u32_e32 v178, s29, v252
	global_load_dwordx4 v[166:169], v166, s[100:101] offset:128
	global_load_dwordx4 v[170:173], v170, s[100:101] offset:128
	global_load_dwordx4 v[174:177], v176, s[100:101] offset:128
	global_load_dwordx4 v[178:181], v178, s[100:101] offset:128
	v_mov_b32_e32 v214, v146
	v_mov_b32_e32 v223, v147
	v_xor_b32_e32 v253, 0x8000, v144
	v_xor_b32_e32 v254, 0x8000, v145
	ds_read_b128 v[182:185], v214
	ds_read_b128 v[186:189], v214 offset:2048
	ds_read_b128 v[190:193], v214 offset:4096
	ds_read_b128 v[194:197], v214 offset:6144
	ds_read_b128 v[218:221], v223
	ds_read_b128 v[224:227], v223 offset:2048
	ds_read_b128 v[228:231], v223 offset:4096
	ds_read_b128 v[232:235], v223 offset:6144
.Lg2_p6_loop:
	ds_read_b128 v[198:201], v214 offset:8192
	ds_read_b128 v[202:205], v214 offset:10240
	ds_read_b128 v[206:209], v214 offset:12288
	ds_read_b128 v[210:213], v214 offset:14336
	s_waitcnt lgkmcnt(4)
	v_mfma_f32_16x16x32_bf16 v[126:129], v[218:221], v[182:185], v[126:129]
	v_mfma_f32_16x16x32_bf16 v[122:125], v[224:227], v[182:185], v[122:125]
	v_mfma_f32_16x16x32_bf16 v[118:121], v[228:231], v[182:185], v[118:121]
	v_mfma_f32_16x16x32_bf16 v[114:117], v[232:235], v[182:185], v[114:117]
	v_mfma_f32_16x16x32_bf16 v[110:113], v[218:221], v[186:189], v[110:113]
	v_mfma_f32_16x16x32_bf16 v[106:109], v[224:227], v[186:189], v[106:109]
	v_mfma_f32_16x16x32_bf16 v[102:105], v[228:231], v[186:189], v[102:105]
	v_mfma_f32_16x16x32_bf16 v[98:101], v[232:235], v[186:189], v[98:101]
	v_mfma_f32_16x16x32_bf16 v[94:97], v[218:221], v[190:193], v[94:97]
	v_mfma_f32_16x16x32_bf16 v[90:93], v[224:227], v[190:193], v[90:93]
	v_mfma_f32_16x16x32_bf16 v[86:89], v[228:231], v[190:193], v[86:89]
	v_mfma_f32_16x16x32_bf16 v[82:85], v[232:235], v[190:193], v[82:85]
	v_mfma_f32_16x16x32_bf16 v[78:81], v[218:221], v[194:197], v[78:81]
	v_mfma_f32_16x16x32_bf16 v[74:77], v[224:227], v[194:197], v[74:77]
	v_mfma_f32_16x16x32_bf16 v[70:73], v[228:231], v[194:197], v[70:73]
	v_mfma_f32_16x16x32_bf16 v[66:69], v[232:235], v[194:197], v[66:69]
	ds_read_b128 v[182:185], v216
	ds_read_b128 v[186:189], v216 offset:2048
	ds_read_b128 v[190:193], v216 offset:4096
	ds_read_b128 v[194:197], v216 offset:6144
	ds_read_b128 v[236:239], v217
	ds_read_b128 v[240:243], v217 offset:2048
	ds_read_b128 v[244:247], v217 offset:4096
	ds_read_b128 v[248:251], v217 offset:6144
	s_waitcnt lgkmcnt(8)
	v_mfma_f32_16x16x32_bf16 v[62:65], v[218:221], v[198:201], v[62:65]
	v_mfma_f32_16x16x32_bf16 v[58:61], v[224:227], v[198:201], v[58:61]
	v_mfma_f32_16x16x32_bf16 v[54:57], v[228:231], v[198:201], v[54:57]
	v_mfma_f32_16x16x32_bf16 v[50:53], v[232:235], v[198:201], v[50:53]
	v_mfma_f32_16x16x32_bf16 v[46:49], v[218:221], v[202:205], v[46:49]
	v_mfma_f32_16x16x32_bf16 v[42:45], v[224:227], v[202:205], v[42:45]
	v_mfma_f32_16x16x32_bf16 v[38:41], v[228:231], v[202:205], v[38:41]
	v_mfma_f32_16x16x32_bf16 v[34:37], v[232:235], v[202:205], v[34:37]
	v_mfma_f32_16x16x32_bf16 v[30:33], v[218:221], v[206:209], v[30:33]
	v_mfma_f32_16x16x32_bf16 v[26:29], v[224:227], v[206:209], v[26:29]
	v_mfma_f32_16x16x32_bf16 v[22:25], v[228:231], v[206:209], v[22:25]
	v_mfma_f32_16x16x32_bf16 v[18:21], v[232:235], v[206:209], v[18:21]
	v_mfma_f32_16x16x32_bf16 v[14:17], v[218:221], v[210:213], v[14:17]
	v_mfma_f32_16x16x32_bf16 v[10:13], v[224:227], v[210:213], v[10:13]
	v_mfma_f32_16x16x32_bf16 v[6:9], v[228:231], v[210:213], v[6:9]
	v_mfma_f32_16x16x32_bf16 v[2:5], v[232:235], v[210:213], v[2:5]
	ds_read_b128 v[198:201], v216 offset:8192
	ds_read_b128 v[202:205], v216 offset:10240
	ds_read_b128 v[206:209], v216 offset:12288
	ds_read_b128 v[210:213], v216 offset:14336
	s_waitcnt lgkmcnt(4)
	v_mfma_f32_16x16x32_bf16 v[126:129], v[236:239], v[182:185], v[126:129]
	v_mfma_f32_16x16x32_bf16 v[122:125], v[240:243], v[182:185], v[122:125]
	s_waitcnt vmcnt(7)
	ds_write_b128 v253, v[150:153]
	v_mfma_f32_16x16x32_bf16 v[118:121], v[244:247], v[182:185], v[118:121]
	v_mfma_f32_16x16x32_bf16 v[114:117], v[248:251], v[182:185], v[114:117]
	s_waitcnt vmcnt(6)
	ds_write_b128 v253, v[154:157] offset:8192
	v_mfma_f32_16x16x32_bf16 v[110:113], v[236:239], v[186:189], v[110:113]
	v_mfma_f32_16x16x32_bf16 v[106:109], v[240:243], v[186:189], v[106:109]
	s_waitcnt vmcnt(5)
	ds_write_b128 v253, v[158:161] offset:16384
	v_mfma_f32_16x16x32_bf16 v[102:105], v[244:247], v[186:189], v[102:105]
	v_mfma_f32_16x16x32_bf16 v[98:101], v[248:251], v[186:189], v[98:101]
	s_waitcnt vmcnt(4)
	ds_write_b128 v253, v[162:165] offset:24576
	v_mfma_f32_16x16x32_bf16 v[94:97], v[236:239], v[190:193], v[94:97]
	v_mfma_f32_16x16x32_bf16 v[90:93], v[240:243], v[190:193], v[90:93]
	s_waitcnt vmcnt(3)
	ds_write_b128 v254, v[166:169]
	v_mfma_f32_16x16x32_bf16 v[86:89], v[244:247], v[190:193], v[86:89]
	v_mfma_f32_16x16x32_bf16 v[82:85], v[248:251], v[190:193], v[82:85]
	s_waitcnt vmcnt(2)
	ds_write_b128 v254, v[170:173] offset:8192
	v_mfma_f32_16x16x32_bf16 v[78:81], v[236:239], v[194:197], v[78:81]
	v_mfma_f32_16x16x32_bf16 v[74:77], v[240:243], v[194:197], v[74:77]
	s_waitcnt vmcnt(1)
	ds_write_b128 v254, v[174:177] offset:16384
	v_mfma_f32_16x16x32_bf16 v[70:73], v[244:247], v[194:197], v[70:73]
	v_mfma_f32_16x16x32_bf16 v[66:69], v[248:251], v[194:197], v[66:69]
	s_waitcnt vmcnt(0)
	ds_write_b128 v254, v[178:181] offset:24576
	s_waitcnt lgkmcnt(0)
	s_barrier
	s_add_u32 s0, s0, 0x80
	s_addc_u32 s1, s1, 0
	s_add_u32 s98, s98, 0x80
	s_addc_u32 s99, s99, 0
	s_add_u32 s100, s100, 0x80
	s_addc_u32 s101, s101, 0
	s_cmpk_eq_i32 s0, 0x780
	s_cbranch_scc1 .Lg2_p6_tail
	v_xor_b32_e32 v214, 0x8000, v214
	v_xor_b32_e32 v223, 0x8000, v223
	v_xor_b32_e32 v216, 0x8000, v216
	v_xor_b32_e32 v217, 0x8000, v217
	v_xor_b32_e32 v253, 0x8000, v253
	v_xor_b32_e32 v254, 0x8000, v254
	ds_read_b128 v[182:185], v214
	ds_read_b128 v[186:189], v214 offset:2048
	ds_read_b128 v[190:193], v214 offset:4096
	ds_read_b128 v[194:197], v214 offset:6144
	ds_read_b128 v[218:221], v223
	ds_read_b128 v[224:227], v223 offset:2048
	ds_read_b128 v[228:231], v223 offset:4096
	ds_read_b128 v[232:235], v223 offset:6144
	v_mfma_f32_16x16x32_bf16 v[62:65], v[236:239], v[198:201], v[62:65]
	v_add_u32_e32 v152, s12, v215
	v_mfma_f32_16x16x32_bf16 v[58:61], v[240:243], v[198:201], v[58:61]
	v_add_u32_e32 v154, s13, v215
	v_mfma_f32_16x16x32_bf16 v[54:57], v[244:247], v[198:201], v[54:57]
	v_add_u32_e32 v158, s14, v215
	v_mfma_f32_16x16x32_bf16 v[50:53], v[248:251], v[198:201], v[50:53]
	v_add_u32_e32 v162, s15, v215
	v_mfma_f32_16x16x32_bf16 v[46:49], v[236:239], v[202:205], v[46:49]
	global_load_dwordx4 v[150:153], v152, s[98:99] offset:128
	v_mfma_f32_16x16x32_bf16 v[42:45], v[240:243], v[202:205], v[42:45]
	global_load_dwordx4 v[154:157], v154, s[98:99] offset:128
	v_mfma_f32_16x16x32_bf16 v[38:41], v[244:247], v[202:205], v[38:41]
	global_load_dwordx4 v[158:161], v158, s[98:99] offset:128
	v_mfma_f32_16x16x32_bf16 v[34:37], v[248:251], v[202:205], v[34:37]
	global_load_dwordx4 v[162:165], v162, s[98:99] offset:128
	v_mfma_f32_16x16x32_bf16 v[30:33], v[236:239], v[206:209], v[30:33]
	v_add_u32_e32 v166, s16, v252
	v_mfma_f32_16x16x32_bf16 v[26:29], v[240:243], v[206:209], v[26:29]
	v_add_u32_e32 v170, s17, v252
	v_mfma_f32_16x16x32_bf16 v[22:25], v[244:247], v[206:209], v[22:25]
	v_add_u32_e32 v176, s28, v252
	v_mfma_f32_16x16x32_bf16 v[18:21], v[248:251], v[206:209], v[18:21]
	v_add_u32_e32 v178, s29, v252
	v_mfma_f32_16x16x32_bf16 v[14:17], v[236:239], v[210:213], v[14:17]
	global_load_dwordx4 v[166:169], v166, s[100:101] offset:128
	v_mfma_f32_16x16x32_bf16 v[10:13], v[240:243], v[210:213], v[10:13]
	global_load_dwordx4 v[170:173], v170, s[100:101] offset:128
	v_mfma_f32_16x16x32_bf16 v[6:9], v[244:247], v[210:213], v[6:9]
	global_load_dwordx4 v[174:177], v176, s[100:101] offset:128
	v_mfma_f32_16x16x32_bf16 v[2:5], v[248:251], v[210:213], v[2:5]
	global_load_dwordx4 v[178:181], v178, s[100:101] offset:128
	s_branch .Lg2_p6_loop
.Lg2_p6_tail:
	v_xor_b32_e32 v216, 64, v146
	v_xor_b32_e32 v217, 64, v147
	v_mfma_f32_16x16x32_bf16 v[62:65], v[236:239], v[198:201], v[62:65]
	v_mfma_f32_16x16x32_bf16 v[58:61], v[240:243], v[198:201], v[58:61]
	v_mfma_f32_16x16x32_bf16 v[54:57], v[244:247], v[198:201], v[54:57]
	v_mfma_f32_16x16x32_bf16 v[50:53], v[248:251], v[198:201], v[50:53]
	v_mfma_f32_16x16x32_bf16 v[46:49], v[236:239], v[202:205], v[46:49]
	v_mfma_f32_16x16x32_bf16 v[42:45], v[240:243], v[202:205], v[42:45]
	v_mfma_f32_16x16x32_bf16 v[38:41], v[244:247], v[202:205], v[38:41]
	v_mfma_f32_16x16x32_bf16 v[34:37], v[248:251], v[202:205], v[34:37]
	v_mfma_f32_16x16x32_bf16 v[30:33], v[236:239], v[206:209], v[30:33]
	v_mfma_f32_16x16x32_bf16 v[26:29], v[240:243], v[206:209], v[26:29]
	v_mfma_f32_16x16x32_bf16 v[22:25], v[244:247], v[206:209], v[22:25]
	v_mfma_f32_16x16x32_bf16 v[18:21], v[248:251], v[206:209], v[18:21]
	v_mfma_f32_16x16x32_bf16 v[14:17], v[236:239], v[210:213], v[14:17]
	v_mfma_f32_16x16x32_bf16 v[10:13], v[240:243], v[210:213], v[10:13]
	v_mfma_f32_16x16x32_bf16 v[6:9], v[244:247], v[210:213], v[6:9]
	v_mfma_f32_16x16x32_bf16 v[2:5], v[248:251], v[210:213], v[2:5]
	ds_read_b128 v[140:143], v147 offset:32768
	ds_read_b128 v[150:153], v147 offset:34816
	ds_read_b128 v[154:157], v147 offset:36864
	ds_read_b128 v[158:161], v147 offset:38912
	ds_read_b128 v[162:165], v146 offset:32768
	ds_read_b128 v[166:169], v146 offset:34816
	ds_read_b128 v[170:173], v146 offset:36864
	ds_read_b128 v[174:177], v146 offset:38912
	s_setprio 1
	s_waitcnt lgkmcnt(3)
	v_mfma_f32_16x16x32_bf16 v[126:129], v[140:143], v[162:165], v[126:129]
	v_mfma_f32_16x16x32_bf16 v[122:125], v[150:153], v[162:165], v[122:125]
	v_mfma_f32_16x16x32_bf16 v[118:121], v[154:157], v[162:165], v[118:121]
	v_mfma_f32_16x16x32_bf16 v[114:117], v[158:161], v[162:165], v[114:117]
	s_waitcnt lgkmcnt(2)
	v_mfma_f32_16x16x32_bf16 v[110:113], v[140:143], v[166:169], v[110:113]
	v_mfma_f32_16x16x32_bf16 v[106:109], v[150:153], v[166:169], v[106:109]
	v_mfma_f32_16x16x32_bf16 v[102:105], v[154:157], v[166:169], v[102:105]
	v_mfma_f32_16x16x32_bf16 v[98:101], v[158:161], v[166:169], v[98:101]
	s_waitcnt lgkmcnt(1)
	v_mfma_f32_16x16x32_bf16 v[94:97], v[140:143], v[170:173], v[94:97]
	v_mfma_f32_16x16x32_bf16 v[90:93], v[150:153], v[170:173], v[90:93]
	v_mfma_f32_16x16x32_bf16 v[86:89], v[154:157], v[170:173], v[86:89]
	v_mfma_f32_16x16x32_bf16 v[82:85], v[158:161], v[170:173], v[82:85]
	s_waitcnt lgkmcnt(0)
	v_mfma_f32_16x16x32_bf16 v[78:81], v[140:143], v[174:177], v[78:81]
	v_mfma_f32_16x16x32_bf16 v[74:77], v[150:153], v[174:177], v[74:77]
	v_mfma_f32_16x16x32_bf16 v[70:73], v[154:157], v[174:177], v[70:73]
	v_mfma_f32_16x16x32_bf16 v[66:69], v[158:161], v[174:177], v[66:69]
	s_setprio 0
	ds_read_b128 v[162:165], v146 offset:40960
	ds_read_b128 v[166:169], v146 offset:43008
	ds_read_b128 v[170:173], v146 offset:45056
	ds_read_b128 v[174:177], v146 offset:47104
	s_setprio 1
	s_waitcnt lgkmcnt(3)
	v_mfma_f32_16x16x32_bf16 v[62:65], v[140:143], v[162:165], v[62:65]
	v_mfma_f32_16x16x32_bf16 v[58:61], v[150:153], v[162:165], v[58:61]
	v_mfma_f32_16x16x32_bf16 v[54:57], v[154:157], v[162:165], v[54:57]
	v_mfma_f32_16x16x32_bf16 v[50:53], v[158:161], v[162:165], v[50:53]
	s_waitcnt lgkmcnt(2)
	v_mfma_f32_16x16x32_bf16 v[46:49], v[140:143], v[166:169], v[46:49]
	v_mfma_f32_16x16x32_bf16 v[42:45], v[150:153], v[166:169], v[42:45]
	v_mfma_f32_16x16x32_bf16 v[38:41], v[154:157], v[166:169], v[38:41]
	v_mfma_f32_16x16x32_bf16 v[34:37], v[158:161], v[166:169], v[34:37]
	s_waitcnt lgkmcnt(1)
	v_mfma_f32_16x16x32_bf16 v[30:33], v[140:143], v[170:173], v[30:33]
	v_mfma_f32_16x16x32_bf16 v[26:29], v[150:153], v[170:173], v[26:29]
	v_mfma_f32_16x16x32_bf16 v[22:25], v[154:157], v[170:173], v[22:25]
	v_mfma_f32_16x16x32_bf16 v[18:21], v[158:161], v[170:173], v[18:21]
	s_waitcnt lgkmcnt(0)
	v_mfma_f32_16x16x32_bf16 v[14:17], v[140:143], v[174:177], v[14:17]
	v_mfma_f32_16x16x32_bf16 v[10:13], v[150:153], v[174:177], v[10:13]
	v_mfma_f32_16x16x32_bf16 v[6:9], v[154:157], v[174:177], v[6:9]
	v_mfma_f32_16x16x32_bf16 v[2:5], v[158:161], v[174:177], v[2:5]
	s_setprio 0
	ds_read_b128 v[140:143], v217 offset:32768
	ds_read_b128 v[150:153], v217 offset:34816
	ds_read_b128 v[154:157], v217 offset:36864
	ds_read_b128 v[158:161], v217 offset:38912
	ds_read_b128 v[162:165], v216 offset:32768
	ds_read_b128 v[166:169], v216 offset:34816
	ds_read_b128 v[170:173], v216 offset:36864
	ds_read_b128 v[174:177], v216 offset:38912
	s_setprio 1
	s_waitcnt lgkmcnt(3)
	v_mfma_f32_16x16x32_bf16 v[126:129], v[140:143], v[162:165], v[126:129]
	v_mfma_f32_16x16x32_bf16 v[122:125], v[150:153], v[162:165], v[122:125]
	v_mfma_f32_16x16x32_bf16 v[118:121], v[154:157], v[162:165], v[118:121]
	v_mfma_f32_16x16x32_bf16 v[114:117], v[158:161], v[162:165], v[114:117]
	s_waitcnt lgkmcnt(2)
	v_mfma_f32_16x16x32_bf16 v[110:113], v[140:143], v[166:169], v[110:113]
	v_mfma_f32_16x16x32_bf16 v[106:109], v[150:153], v[166:169], v[106:109]
	v_mfma_f32_16x16x32_bf16 v[102:105], v[154:157], v[166:169], v[102:105]
	v_mfma_f32_16x16x32_bf16 v[98:101], v[158:161], v[166:169], v[98:101]
	s_waitcnt lgkmcnt(1)
	v_mfma_f32_16x16x32_bf16 v[94:97], v[140:143], v[170:173], v[94:97]
	v_mfma_f32_16x16x32_bf16 v[162:165], v[150:153], v[170:173], v[90:93]
	v_mfma_f32_16x16x32_bf16 v[86:89], v[154:157], v[170:173], v[86:89]
	v_mfma_f32_16x16x32_bf16 v[82:85], v[158:161], v[170:173], v[82:85]
	s_waitcnt lgkmcnt(0)
	v_mfma_f32_16x16x32_bf16 v[78:81], v[140:143], v[174:177], v[78:81]
	v_mfma_f32_16x16x32_bf16 v[74:77], v[150:153], v[174:177], v[74:77]
	v_mfma_f32_16x16x32_bf16 v[70:73], v[154:157], v[174:177], v[70:73]
	v_mfma_f32_16x16x32_bf16 v[66:69], v[158:161], v[174:177], v[66:69]
	s_setprio 0
	ds_read_b128 v[90:93], v216 offset:40960
	ds_read_b128 v[166:169], v216 offset:43008
	ds_read_b128 v[170:173], v216 offset:45056
	ds_read_b128 v[174:177], v216 offset:47104
	s_setprio 1
	s_waitcnt lgkmcnt(3)
	v_mfma_f32_16x16x32_bf16 v[62:65], v[140:143], v[90:93], v[62:65]
	v_mfma_f32_16x16x32_bf16 v[58:61], v[150:153], v[90:93], v[58:61]
	v_mfma_f32_16x16x32_bf16 v[54:57], v[154:157], v[90:93], v[54:57]
	v_mfma_f32_16x16x32_bf16 v[50:53], v[158:161], v[90:93], v[50:53]
	s_waitcnt lgkmcnt(2)
	v_mfma_f32_16x16x32_bf16 v[46:49], v[140:143], v[166:169], v[46:49]
	v_mfma_f32_16x16x32_bf16 v[42:45], v[150:153], v[166:169], v[42:45]
	v_mfma_f32_16x16x32_bf16 v[38:41], v[154:157], v[166:169], v[38:41]
	v_mfma_f32_16x16x32_bf16 v[34:37], v[158:161], v[166:169], v[34:37]
	s_waitcnt lgkmcnt(1)
	v_mfma_f32_16x16x32_bf16 v[30:33], v[140:143], v[170:173], v[30:33]
	v_mfma_f32_16x16x32_bf16 v[26:29], v[150:153], v[170:173], v[26:29]
	v_mfma_f32_16x16x32_bf16 v[22:25], v[154:157], v[170:173], v[22:25]
	v_mfma_f32_16x16x32_bf16 v[18:21], v[158:161], v[170:173], v[18:21]
	s_waitcnt lgkmcnt(0)
	v_mfma_f32_16x16x32_bf16 v[14:17], v[140:143], v[174:177], v[14:17]
	v_mfma_f32_16x16x32_bf16 v[10:13], v[150:153], v[174:177], v[10:13]
	v_mfma_f32_16x16x32_bf16 v[6:9], v[154:157], v[174:177], v[6:9]
	v_mfma_f32_16x16x32_bf16 v[2:5], v[158:161], v[174:177], v[2:5]
	s_setprio 0
	v_mul_f32_e32 v93, 0xbfb8aa3b, v126
	v_exp_f32_e32 v93, v93
	v_mul_f32_e32 v130, 0xbfb8aa3b, v127
	v_exp_f32_e32 v130, v130
	v_mul_f32_e32 v141, 0xbfb8aa3b, v129
	v_add_f32_e32 v93, 1.0, v93
	v_rcp_f32_e32 v140, v93
	v_add_f32_e32 v93, 1.0, v130
	v_mul_f32_e32 v130, 0xbfb8aa3b, v128
	v_exp_f32_e32 v130, v130
	v_exp_f32_e32 v143, v141
	v_rcp_f32_e32 v141, v93
	v_or_b32_e32 v90, s38, v148
	v_add_f32_e32 v93, 1.0, v130
	v_rcp_f32_e32 v142, v93
	v_add_f32_e32 v93, 1.0, v143
	v_rcp_f32_e32 v143, v93
	v_pk_mul_f32 v[126:127], v[126:127], v[140:141]
	v_mul_f32_e32 v93, 0xbfb8aa3b, v118
	v_pk_mul_f32 v[122:123], v[122:123], v[126:127]
	v_pk_mul_f32 v[126:127], v[128:129], v[142:143]
	v_cvt_pk_bf16_f32 v122, v122, v123
	v_exp_f32_e32 v93, v93
	v_mul_f32_e32 v123, 0xbfb8aa3b, v119
	v_pk_mul_f32 v[124:125], v[124:125], v[126:127]
	v_exp_f32_e32 v126, v123
	v_cvt_pk_bf16_f32 v123, v124, v125
	v_add_f32_e32 v93, 1.0, v93
	v_mul_f32_e32 v125, 0xbfb8aa3b, v120
	v_rcp_f32_e32 v124, v93
	v_add_f32_e32 v93, 1.0, v126
	v_exp_f32_e32 v126, v125
	v_mul_f32_e32 v125, 0xbfb8aa3b, v121
	v_exp_f32_e32 v127, v125
	v_rcp_f32_e32 v125, v93
	v_add_f32_e32 v93, 1.0, v126
	v_rcp_f32_e32 v126, v93
	v_add_f32_e32 v93, 1.0, v127
	v_rcp_f32_e32 v127, v93
	v_ashrrev_i32_e32 v90, 1, v90
	v_pk_mul_f32 v[118:119], v[118:119], v[124:125]
	v_ashrrev_i32_e32 v91, 31, v90
	v_pk_mul_f32 v[114:115], v[114:115], v[118:119]
	v_pk_mul_f32 v[118:119], v[120:121], v[126:127]
	v_add_u32_e32 v92, s37, v149
	v_lshl_add_u64 v[90:91], v[90:91], 1, v[136:137]
	v_pk_mul_f32 v[116:117], v[116:117], v[118:119]
	v_mad_i64_i32 v[150:151], s[0:1], v92, s36, v[90:91]
	v_cvt_pk_bf16_f32 v114, v114, v115
	v_cvt_pk_bf16_f32 v115, v116, v117
	v_mul_f32_e32 v93, 0xbfb8aa3b, v110
	s_barrier
	global_store_dwordx2 v[150:151], v[114:115], off offset:32
	v_exp_f32_e32 v93, v93
	v_mul_f32_e32 v114, 0xbfb8aa3b, v111
	v_exp_f32_e32 v115, v114
	v_or_b32_e32 v118, 16, v92
	v_add_f32_e32 v93, 1.0, v93
	v_rcp_f32_e32 v114, v93
	v_add_f32_e32 v93, 1.0, v115
	v_mul_f32_e32 v115, 0xbfb8aa3b, v112
	v_exp_f32_e32 v116, v115
	v_mul_f32_e32 v115, 0xbfb8aa3b, v113
	v_exp_f32_e32 v117, v115
	v_rcp_f32_e32 v115, v93
	v_add_f32_e32 v93, 1.0, v116
	v_rcp_f32_e32 v116, v93
	v_add_f32_e32 v93, 1.0, v117
	v_rcp_f32_e32 v117, v93
	v_pk_mul_f32 v[110:111], v[110:111], v[114:115]
	v_mul_f32_e32 v93, 0xbfb8aa3b, v102
	v_pk_mul_f32 v[106:107], v[106:107], v[110:111]
	v_pk_mul_f32 v[110:111], v[112:113], v[116:117]
	v_cvt_pk_bf16_f32 v106, v106, v107
	v_exp_f32_e32 v93, v93
	v_mul_f32_e32 v107, 0xbfb8aa3b, v103
	v_pk_mul_f32 v[108:109], v[108:109], v[110:111]
	v_exp_f32_e32 v110, v107
	v_cvt_pk_bf16_f32 v107, v108, v109
	v_add_f32_e32 v93, 1.0, v93
	v_mul_f32_e32 v109, 0xbfb8aa3b, v104
	v_rcp_f32_e32 v108, v93
	v_add_f32_e32 v93, 1.0, v110
	v_exp_f32_e32 v110, v109
	v_mul_f32_e32 v109, 0xbfb8aa3b, v105
	v_exp_f32_e32 v111, v109
	v_rcp_f32_e32 v109, v93
	v_add_f32_e32 v93, 1.0, v110
	v_rcp_f32_e32 v110, v93
	v_add_f32_e32 v93, 1.0, v111
	v_rcp_f32_e32 v111, v93
	v_pk_mul_f32 v[102:103], v[102:103], v[108:109]
	v_mad_i64_i32 v[118:119], s[0:1], v118, s36, v[90:91]
	v_pk_mul_f32 v[98:99], v[98:99], v[102:103]
	v_pk_mul_f32 v[102:103], v[104:105], v[110:111]
	v_cvt_pk_bf16_f32 v98, v98, v99
	v_pk_mul_f32 v[100:101], v[100:101], v[102:103]
	v_mul_f32_e32 v93, 0xbfb8aa3b, v94
	v_cvt_pk_bf16_f32 v99, v100, v101
	global_store_dwordx2 v[118:119], v[98:99], off offset:32
	v_exp_f32_e32 v93, v93
	v_mul_f32_e32 v98, 0xbfb8aa3b, v95
	v_exp_f32_e32 v99, v98
	v_or_b32_e32 v102, 32, v92
	v_add_f32_e32 v93, 1.0, v93
	v_rcp_f32_e32 v98, v93
	v_add_f32_e32 v93, 1.0, v99
	v_mul_f32_e32 v99, 0xbfb8aa3b, v96
	v_exp_f32_e32 v100, v99
	v_mul_f32_e32 v99, 0xbfb8aa3b, v97
	v_exp_f32_e32 v101, v99
	v_rcp_f32_e32 v99, v93
	v_add_f32_e32 v93, 1.0, v100
	v_rcp_f32_e32 v100, v93
	v_add_f32_e32 v93, 1.0, v101
	v_rcp_f32_e32 v101, v93
	v_pk_mul_f32 v[94:95], v[94:95], v[98:99]
	v_mul_f32_e32 v93, 0xbfb8aa3b, v86
	v_pk_mul_f32 v[94:95], v[162:163], v[94:95]
	v_exp_f32_e32 v93, v93
	v_cvt_pk_bf16_f32 v94, v94, v95
	v_mul_f32_e32 v95, 0xbfb8aa3b, v87
	v_exp_f32_e32 v98, v95
	v_pk_mul_f32 v[96:97], v[96:97], v[100:101]
	v_add_f32_e32 v93, 1.0, v93
	v_pk_mul_f32 v[96:97], v[164:165], v[96:97]
	v_mad_i64_i32 v[102:103], s[0:1], v102, s36, v[90:91]
	v_cvt_pk_bf16_f32 v95, v96, v97
	v_mul_f32_e32 v97, 0xbfb8aa3b, v88
	v_rcp_f32_e32 v96, v93
	v_add_f32_e32 v93, 1.0, v98
	v_exp_f32_e32 v98, v97
	v_mul_f32_e32 v97, 0xbfb8aa3b, v89
	v_exp_f32_e32 v99, v97
	v_rcp_f32_e32 v97, v93
	v_add_f32_e32 v93, 1.0, v98
	v_rcp_f32_e32 v98, v93
	v_add_f32_e32 v93, 1.0, v99
	v_rcp_f32_e32 v99, v93
	v_pk_mul_f32 v[86:87], v[86:87], v[96:97]
	s_add_i32 s3, s3, s7
	v_pk_mul_f32 v[82:83], v[82:83], v[86:87]
	v_pk_mul_f32 v[86:87], v[88:89], v[98:99]
	v_cvt_pk_bf16_f32 v82, v82, v83
	v_pk_mul_f32 v[84:85], v[84:85], v[86:87]
	v_or_b32_e32 v86, 48, v92
	v_cvt_pk_bf16_f32 v83, v84, v85
	global_store_dwordx2 v[102:103], v[82:83], off offset:32
	v_mul_f32_e32 v82, 0xbfb8aa3b, v78
	v_mul_f32_e32 v83, 0xbfb8aa3b, v79
	v_exp_f32_e32 v82, v82
	v_exp_f32_e32 v83, v83
	v_mul_f32_e32 v84, 0xbfb8aa3b, v80
	v_mul_f32_e32 v85, 0xbfb8aa3b, v81
	v_exp_f32_e32 v84, v84
	v_exp_f32_e32 v85, v85
	v_add_f32_e32 v82, 1.0, v82
	v_add_f32_e32 v83, 1.0, v83
	v_rcp_f32_e32 v82, v82
	v_rcp_f32_e32 v83, v83
	v_add_f32_e32 v84, 1.0, v84
	v_add_f32_e32 v85, 1.0, v85
	v_rcp_f32_e32 v84, v84
	v_rcp_f32_e32 v85, v85
	v_pk_mul_f32 v[78:79], v[78:79], v[82:83]
	v_mad_i64_i32 v[86:87], s[0:1], v86, s36, v[90:91]
	v_pk_mul_f32 v[74:75], v[74:75], v[78:79]
	v_pk_mul_f32 v[78:79], v[80:81], v[84:85]
	v_cvt_pk_bf16_f32 v74, v74, v75
	v_mul_f32_e32 v75, 0xbfb8aa3b, v70
	v_pk_mul_f32 v[76:77], v[76:77], v[78:79]
	v_exp_f32_e32 v78, v75
	v_mul_f32_e32 v75, 0xbfb8aa3b, v71
	v_exp_f32_e32 v79, v75
	v_cvt_pk_bf16_f32 v75, v76, v77
	v_add_f32_e32 v76, 1.0, v78
	v_mul_f32_e32 v78, 0xbfb8aa3b, v72
	v_add_f32_e32 v77, 1.0, v79
	v_mul_f32_e32 v79, 0xbfb8aa3b, v73
	v_exp_f32_e32 v78, v78
	v_exp_f32_e32 v79, v79
	v_rcp_f32_e32 v76, v76
	v_rcp_f32_e32 v77, v77
	v_add_f32_e32 v78, 1.0, v78
	v_add_f32_e32 v79, 1.0, v79
	v_rcp_f32_e32 v78, v78
	v_rcp_f32_e32 v79, v79
	v_pk_mul_f32 v[70:71], v[70:71], v[76:77]
	s_add_i32 s8, s8, s7
	v_pk_mul_f32 v[66:67], v[66:67], v[70:71]
	v_pk_mul_f32 v[70:71], v[72:73], v[78:79]
	v_cvt_pk_bf16_f32 v66, v66, v67
	v_pk_mul_f32 v[68:69], v[68:69], v[70:71]
	v_or_b32_e32 v70, 64, v92
	v_cvt_pk_bf16_f32 v67, v68, v69
	global_store_dwordx2 v[86:87], v[66:67], off offset:32
	v_mul_f32_e32 v66, 0xbfb8aa3b, v62
	v_mul_f32_e32 v67, 0xbfb8aa3b, v63
	v_exp_f32_e32 v66, v66
	v_exp_f32_e32 v67, v67
	v_mul_f32_e32 v68, 0xbfb8aa3b, v64
	v_mul_f32_e32 v69, 0xbfb8aa3b, v65
	v_exp_f32_e32 v68, v68
	v_exp_f32_e32 v69, v69
	v_add_f32_e32 v66, 1.0, v66
	v_add_f32_e32 v67, 1.0, v67
	v_rcp_f32_e32 v66, v66
	v_rcp_f32_e32 v67, v67
	v_add_f32_e32 v68, 1.0, v68
	v_add_f32_e32 v69, 1.0, v69
	v_rcp_f32_e32 v68, v68
	v_rcp_f32_e32 v69, v69
	v_pk_mul_f32 v[62:63], v[62:63], v[66:67]
	v_mad_i64_i32 v[70:71], s[0:1], v70, s36, v[90:91]
	v_pk_mul_f32 v[58:59], v[58:59], v[62:63]
	v_pk_mul_f32 v[62:63], v[64:65], v[68:69]
	v_cvt_pk_bf16_f32 v58, v58, v59
	v_mul_f32_e32 v59, 0xbfb8aa3b, v54
	v_pk_mul_f32 v[60:61], v[60:61], v[62:63]
	v_exp_f32_e32 v62, v59
	v_mul_f32_e32 v59, 0xbfb8aa3b, v55
	v_exp_f32_e32 v63, v59
	v_cvt_pk_bf16_f32 v59, v60, v61
	v_add_f32_e32 v60, 1.0, v62
	v_mul_f32_e32 v62, 0xbfb8aa3b, v56
	v_add_f32_e32 v61, 1.0, v63
	v_mul_f32_e32 v63, 0xbfb8aa3b, v57
	v_exp_f32_e32 v62, v62
	v_exp_f32_e32 v63, v63
	v_rcp_f32_e32 v60, v60
	v_rcp_f32_e32 v61, v61
	v_add_f32_e32 v62, 1.0, v62
	v_add_f32_e32 v63, 1.0, v63
	v_rcp_f32_e32 v62, v62
	v_rcp_f32_e32 v63, v63
	v_pk_mul_f32 v[54:55], v[54:55], v[60:61]
	s_cmpk_gt_i32 s3, 0x2d5
	v_pk_mul_f32 v[50:51], v[50:51], v[54:55]
	v_pk_mul_f32 v[54:55], v[56:57], v[62:63]
	v_cvt_pk_bf16_f32 v50, v50, v51
	v_pk_mul_f32 v[52:53], v[52:53], v[54:55]
	v_or_b32_e32 v54, 0x50, v92
	v_cvt_pk_bf16_f32 v51, v52, v53
	global_store_dwordx2 v[70:71], v[50:51], off offset:32
	v_mul_f32_e32 v50, 0xbfb8aa3b, v46
	v_mul_f32_e32 v51, 0xbfb8aa3b, v47
	v_exp_f32_e32 v50, v50
	v_exp_f32_e32 v51, v51
	v_mul_f32_e32 v52, 0xbfb8aa3b, v48
	v_mul_f32_e32 v53, 0xbfb8aa3b, v49
	v_exp_f32_e32 v52, v52
	v_exp_f32_e32 v53, v53
	v_add_f32_e32 v50, 1.0, v50
	v_add_f32_e32 v51, 1.0, v51
	v_rcp_f32_e32 v50, v50
	v_rcp_f32_e32 v51, v51
	v_add_f32_e32 v52, 1.0, v52
	v_add_f32_e32 v53, 1.0, v53
	v_rcp_f32_e32 v52, v52
	v_rcp_f32_e32 v53, v53
	v_pk_mul_f32 v[46:47], v[46:47], v[50:51]
	v_mad_i64_i32 v[54:55], s[0:1], v54, s36, v[90:91]
	v_pk_mul_f32 v[42:43], v[42:43], v[46:47]
	v_pk_mul_f32 v[46:47], v[48:49], v[52:53]
	v_cvt_pk_bf16_f32 v42, v42, v43
	v_mul_f32_e32 v43, 0xbfb8aa3b, v38
	v_pk_mul_f32 v[44:45], v[44:45], v[46:47]
	v_exp_f32_e32 v46, v43
	v_mul_f32_e32 v43, 0xbfb8aa3b, v39
	v_exp_f32_e32 v47, v43
	v_cvt_pk_bf16_f32 v43, v44, v45
	v_add_f32_e32 v44, 1.0, v46
	v_mul_f32_e32 v46, 0xbfb8aa3b, v40
	v_add_f32_e32 v45, 1.0, v47
	v_mul_f32_e32 v47, 0xbfb8aa3b, v41
	v_exp_f32_e32 v46, v46
	v_exp_f32_e32 v47, v47
	v_rcp_f32_e32 v44, v44
	v_rcp_f32_e32 v45, v45
	v_add_f32_e32 v46, 1.0, v46
	v_add_f32_e32 v47, 1.0, v47
	v_rcp_f32_e32 v46, v46
	v_rcp_f32_e32 v47, v47
	v_pk_mul_f32 v[38:39], v[38:39], v[44:45]
	global_store_dwordx2 v[150:151], v[122:123], off
	v_pk_mul_f32 v[34:35], v[34:35], v[38:39]
	v_pk_mul_f32 v[38:39], v[40:41], v[46:47]
	v_cvt_pk_bf16_f32 v34, v34, v35
	v_pk_mul_f32 v[36:37], v[36:37], v[38:39]
	v_or_b32_e32 v38, 0x60, v92
	v_cvt_pk_bf16_f32 v35, v36, v37
	global_store_dwordx2 v[54:55], v[34:35], off offset:32
	v_mul_f32_e32 v34, 0xbfb8aa3b, v30
	v_mul_f32_e32 v35, 0xbfb8aa3b, v31
	v_exp_f32_e32 v34, v34
	v_exp_f32_e32 v35, v35
	v_mul_f32_e32 v36, 0xbfb8aa3b, v32
	v_mul_f32_e32 v37, 0xbfb8aa3b, v33
	v_exp_f32_e32 v36, v36
	v_exp_f32_e32 v37, v37
	v_add_f32_e32 v34, 1.0, v34
	v_add_f32_e32 v35, 1.0, v35
	v_rcp_f32_e32 v34, v34
	v_rcp_f32_e32 v35, v35
	v_add_f32_e32 v36, 1.0, v36
	v_add_f32_e32 v37, 1.0, v37
	v_rcp_f32_e32 v36, v36
	v_rcp_f32_e32 v37, v37
	v_pk_mul_f32 v[30:31], v[30:31], v[34:35]
	v_mad_i64_i32 v[38:39], s[0:1], v38, s36, v[90:91]
	v_pk_mul_f32 v[26:27], v[26:27], v[30:31]
	v_pk_mul_f32 v[30:31], v[32:33], v[36:37]
	v_cvt_pk_bf16_f32 v26, v26, v27
	v_mul_f32_e32 v27, 0xbfb8aa3b, v22
	v_pk_mul_f32 v[28:29], v[28:29], v[30:31]
	v_exp_f32_e32 v30, v27
	v_mul_f32_e32 v27, 0xbfb8aa3b, v23
	v_exp_f32_e32 v31, v27
	v_cvt_pk_bf16_f32 v27, v28, v29
	v_add_f32_e32 v28, 1.0, v30
	v_mul_f32_e32 v30, 0xbfb8aa3b, v24
	v_add_f32_e32 v29, 1.0, v31
	v_mul_f32_e32 v31, 0xbfb8aa3b, v25
	v_exp_f32_e32 v30, v30
	v_exp_f32_e32 v31, v31
	v_rcp_f32_e32 v28, v28
	v_rcp_f32_e32 v29, v29
	v_add_f32_e32 v30, 1.0, v30
	v_add_f32_e32 v31, 1.0, v31
	v_rcp_f32_e32 v30, v30
	v_rcp_f32_e32 v31, v31
	v_pk_mul_f32 v[22:23], v[22:23], v[28:29]
	global_store_dwordx2 v[118:119], v[106:107], off
	v_pk_mul_f32 v[18:19], v[18:19], v[22:23]
	v_pk_mul_f32 v[22:23], v[24:25], v[30:31]
	v_cvt_pk_bf16_f32 v18, v18, v19
	v_pk_mul_f32 v[20:21], v[20:21], v[22:23]
	v_or_b32_e32 v22, 0x70, v92
	v_cvt_pk_bf16_f32 v19, v20, v21
	global_store_dwordx2 v[38:39], v[18:19], off offset:32
	v_mul_f32_e32 v18, 0xbfb8aa3b, v14
	v_mul_f32_e32 v19, 0xbfb8aa3b, v15
	v_exp_f32_e32 v18, v18
	v_exp_f32_e32 v19, v19
	v_mul_f32_e32 v20, 0xbfb8aa3b, v16
	v_mul_f32_e32 v21, 0xbfb8aa3b, v17
	v_exp_f32_e32 v20, v20
	v_exp_f32_e32 v21, v21
	v_add_f32_e32 v18, 1.0, v18
	v_add_f32_e32 v19, 1.0, v19
	v_rcp_f32_e32 v18, v18
	v_rcp_f32_e32 v19, v19
	v_add_f32_e32 v20, 1.0, v20
	v_add_f32_e32 v21, 1.0, v21
	v_rcp_f32_e32 v20, v20
	v_rcp_f32_e32 v21, v21
	v_pk_mul_f32 v[14:15], v[14:15], v[18:19]
	v_mad_i64_i32 v[22:23], s[0:1], v22, s36, v[90:91]
	v_pk_mul_f32 v[10:11], v[10:11], v[14:15]
	v_pk_mul_f32 v[14:15], v[16:17], v[20:21]
	v_cvt_pk_bf16_f32 v10, v10, v11
	v_mul_f32_e32 v11, 0xbfb8aa3b, v6
	v_pk_mul_f32 v[12:13], v[12:13], v[14:15]
	v_exp_f32_e32 v14, v11
	v_mul_f32_e32 v11, 0xbfb8aa3b, v7
	v_exp_f32_e32 v15, v11
	v_cvt_pk_bf16_f32 v11, v12, v13
	v_add_f32_e32 v12, 1.0, v14
	v_mul_f32_e32 v14, 0xbfb8aa3b, v8
	v_add_f32_e32 v13, 1.0, v15
	v_mul_f32_e32 v15, 0xbfb8aa3b, v9
	v_exp_f32_e32 v14, v14
	v_exp_f32_e32 v15, v15
	v_rcp_f32_e32 v12, v12
	v_rcp_f32_e32 v13, v13
	v_add_f32_e32 v14, 1.0, v14
	v_add_f32_e32 v15, 1.0, v15
	v_rcp_f32_e32 v14, v14
	v_rcp_f32_e32 v15, v15
	v_pk_mul_f32 v[6:7], v[6:7], v[12:13]
	global_store_dwordx2 v[102:103], v[94:95], off
	v_pk_mul_f32 v[2:3], v[2:3], v[6:7]
	v_pk_mul_f32 v[6:7], v[8:9], v[14:15]
	v_cvt_pk_bf16_f32 v2, v2, v3
	v_pk_mul_f32 v[4:5], v[4:5], v[6:7]
	global_store_dwordx2 v[86:87], v[74:75], off
	v_cvt_pk_bf16_f32 v3, v4, v5
	global_store_dwordx2 v[70:71], v[58:59], off
	global_store_dwordx2 v[54:55], v[42:43], off
	global_store_dwordx2 v[38:39], v[26:27], off
	global_store_dwordx2 v[22:23], v[10:11], off
	global_store_dwordx2 v[22:23], v[2:3], off offset:32
	s_cbranch_scc0 .LBB0_354

.LBB0_378:
	s_lshl_b32 s47, s45, 8
	v_or_b32_e32 v27, s47, v1
	v_mad_i64_i32 v[2:3], s[8:9], v27, s12, v[130:131]
	v_add_co_u32_e32 v6, vcc, 0x58000, v2
	s_lshl_b32 s46, s44, 8
	s_nop 0
	v_addc_co_u32_e32 v7, vcc, 0, v3, vcc
	global_load_dwordx4 v[28:31], v[2:3], off
	global_load_dwordx4 v[32:35], v[6:7], off
	v_add_co_u32_e32 v6, vcc, 0xb0000, v2
	v_or_b32_e32 v60, s46, v1
	s_nop 0
	v_addc_co_u32_e32 v7, vcc, 0, v3, vcc
	v_add_co_u32_e32 v2, vcc, 0x108000, v2
	v_mad_i64_i32 v[4:5], s[8:9], v60, s12, v[132:133]
	s_nop 0
	v_addc_co_u32_e32 v3, vcc, 0, v3, vcc
	global_load_dwordx4 v[36:39], v[6:7], off
	global_load_dwordx4 v[40:43], v[2:3], off
	v_add_co_u32_e32 v2, vcc, s13, v4
	s_waitcnt vmcnt(63) expcnt(7) lgkmcnt(15)
	s_nop 0
	v_addc_co_u32_e32 v3, vcc, 0, v5, vcc
	s_barrier
	global_load_dwordx4 v[44:47], v[4:5], off
	global_load_dwordx4 v[48:51], v[2:3], off
	v_add_co_u32_e32 v2, vcc, s14, v4
	s_mov_b32 s52, 0
	s_nop 0
	v_addc_co_u32_e32 v3, vcc, 0, v5, vcc
	v_add_co_u32_e32 v4, vcc, s15, v4
	s_mov_b64 s[8:9], 0
	s_nop 0
	v_addc_co_u32_e32 v5, vcc, 0, v5, vcc
	global_load_dwordx4 v[52:55], v[2:3], off
	global_load_dwordx4 v[56:59], v[4:5], off
	v_mov_b32_e32 v2, 0
	v_mov_b32_e32 v3, v2
	v_mov_b32_e32 v4, v2
	v_mov_b32_e32 v5, v2
	v_mov_b32_e32 v6, v2
	v_mov_b32_e32 v7, v2
	v_mov_b32_e32 v8, v2
	v_mov_b32_e32 v9, v2
	v_mov_b32_e32 v10, v2
	v_mov_b32_e32 v11, v2
	v_mov_b32_e32 v12, v2
	v_mov_b32_e32 v13, v2
	v_mov_b32_e32 v14, v2
	v_mov_b32_e32 v15, v2
	v_mov_b32_e32 v16, v2
	v_mov_b32_e32 v17, v2
	v_mov_b32_e32 v18, v2
	v_mov_b32_e32 v19, v2
	v_mov_b32_e32 v20, v2
	v_mov_b32_e32 v21, v2
	v_mov_b32_e32 v22, v2
	v_mov_b32_e32 v23, v2
	v_mov_b32_e32 v24, v2
	v_mov_b32_e32 v25, v2
	v_mov_b32_e32 v26, v2
	v_mad_i64_i32 v[136:137], s[56:57], v27, s12, v[134:135]
	v_mad_i64_i32 v[138:139], s[56:57], v60, s12, v[134:135]
	v_mov_b32_e32 v27, v2
	v_mov_b32_e32 v60, v2
	v_mov_b32_e32 v61, v2
	v_mov_b32_e32 v62, v2
	v_mov_b32_e32 v63, v2
	v_mov_b32_e32 v64, v2
	v_mov_b32_e32 v65, v2
	v_mov_b32_e32 v66, v2
	v_mov_b32_e32 v67, v2
	v_mov_b32_e32 v68, v2
	v_mov_b32_e32 v69, v2
	v_mov_b32_e32 v70, v2
	v_mov_b32_e32 v71, v2
	v_mov_b32_e32 v72, v2
	v_mov_b32_e32 v73, v2
	v_mov_b32_e32 v74, v2
	v_mov_b32_e32 v75, v2
	v_mov_b32_e32 v76, v2
	v_mov_b32_e32 v77, v2
	v_mov_b32_e32 v78, v2
	v_mov_b32_e32 v79, v2
	v_mov_b32_e32 v80, v2
	v_mov_b32_e32 v81, v2
	v_mov_b32_e32 v82, v2
	s_waitcnt vmcnt(7)
	ds_write_b128 v146, v[28:31]
	s_waitcnt vmcnt(6)
	ds_write_b128 v146, v[32:35] offset:8192
	s_waitcnt vmcnt(5)
	ds_write_b128 v146, v[36:39] offset:16384
	s_waitcnt vmcnt(4)
	ds_write_b128 v146, v[40:43] offset:24576
	s_waitcnt vmcnt(3)
	ds_write_b128 v147, v[44:47]
	s_waitcnt vmcnt(2)
	ds_write_b128 v147, v[48:51] offset:8192
	s_waitcnt vmcnt(1)
	ds_write_b128 v147, v[52:55] offset:16384
	s_waitcnt vmcnt(0)
	ds_write_b128 v147, v[56:59] offset:24576
	v_mov_b32_e32 v28, v2
	v_mov_b32_e32 v29, v2
	v_mov_b32_e32 v30, v2
	v_mov_b32_e32 v31, v2
	v_mov_b32_e32 v32, v2
	v_mov_b32_e32 v33, v2
	v_mov_b32_e32 v34, v2
	v_mov_b32_e32 v35, v2
	v_mov_b32_e32 v36, v2
	v_mov_b32_e32 v37, v2
	v_mov_b32_e32 v38, v2
	v_mov_b32_e32 v39, v2
	v_mov_b32_e32 v40, v2
	v_mov_b32_e32 v41, v2
	v_mov_b32_e32 v42, v2
	v_mov_b32_e32 v43, v2
	v_mov_b32_e32 v44, v2
	v_mov_b32_e32 v45, v2
	v_mov_b32_e32 v46, v2
	v_mov_b32_e32 v47, v2
	v_mov_b32_e32 v48, v2
	v_mov_b32_e32 v49, v2
	v_mov_b32_e32 v50, v2
	v_mov_b32_e32 v51, v2
	v_mov_b32_e32 v52, v2
	v_mov_b32_e32 v53, v2
	v_mov_b32_e32 v54, v2
	v_mov_b32_e32 v55, v2
	v_mov_b32_e32 v56, v2
	v_mov_b32_e32 v57, v2
	v_mov_b32_e32 v58, v2
	v_mov_b32_e32 v59, v2
	v_mov_b32_e32 v83, v2
	v_mov_b32_e32 v84, v2
	v_mov_b32_e32 v85, v2
	v_mov_b32_e32 v86, v2
	v_mov_b32_e32 v87, v2
	v_mov_b32_e32 v88, v2
	v_mov_b32_e32 v89, v2
	v_mov_b32_e32 v90, v2
	v_mov_b32_e32 v91, v2
	v_mov_b32_e32 v92, v2
	v_mov_b32_e32 v93, v2
	v_mov_b32_e32 v94, v2
	v_mov_b32_e32 v95, v2
	v_mov_b32_e32 v96, v2
	v_mov_b32_e32 v97, v2
	v_mov_b32_e32 v98, v2
	v_mov_b32_e32 v99, v2
	v_mov_b32_e32 v100, v2
	v_mov_b32_e32 v101, v2
	v_mov_b32_e32 v102, v2
	v_mov_b32_e32 v103, v2
	v_mov_b32_e32 v104, v2
	v_mov_b32_e32 v105, v2
	v_mov_b32_e32 v106, v2
	v_mov_b32_e32 v107, v2
	v_mov_b32_e32 v108, v2
	v_mov_b32_e32 v109, v2
	v_mov_b32_e32 v110, v2
	v_mov_b32_e32 v111, v2
	v_mov_b32_e32 v112, v2
	v_mov_b32_e32 v113, v2
	v_mov_b32_e32 v114, v2
	v_mov_b32_e32 v115, v2
	v_mov_b32_e32 v116, v2
	v_mov_b32_e32 v117, v2
	v_mov_b32_e32 v118, v2
	v_mov_b32_e32 v119, v2
	v_mov_b32_e32 v120, v2
	v_mov_b32_e32 v121, v2
	v_mov_b32_e32 v122, v2
	v_mov_b32_e32 v123, v2
	v_mov_b32_e32 v124, v2
	v_mov_b32_e32 v125, v2
	v_mov_b32_e32 v126, v2
	v_mov_b32_e32 v127, v2
	v_mov_b32_e32 v128, v2
	v_mov_b32_e32 v129, v2
	s_waitcnt lgkmcnt(0)
	s_barrier
	v_readfirstlane_b32 s98, v136
	v_readfirstlane_b32 s99, v137
	v_subrev_u32_e32 v248, s98, v136
	s_add_u32 s98, s98, s8
	s_addc_u32 s99, s99, s9
	v_readfirstlane_b32 s100, v138
	v_readfirstlane_b32 s101, v139
	v_subrev_u32_e32 v250, s100, v138
	s_add_u32 s100, s100, s8
	s_addc_u32 s101, s101, s9
	v_add_u32_e32 v142, s16, v248
	v_add_u32_e32 v144, s17, v248
	v_add_u32_e32 v156, s28, v248
	v_add_u32_e32 v160, s29, v248
	global_load_dwordx4 v[140:143], v142, s[98:99] offset:128
	global_load_dwordx4 v[152:155], v144, s[98:99] offset:128
	global_load_dwordx4 v[156:159], v156, s[98:99] offset:128
	global_load_dwordx4 v[160:163], v160, s[98:99] offset:128
	v_add_u32_e32 v164, s36, v250
	v_add_u32_e32 v168, s37, v250
	v_add_u32_e32 v172, s38, v250
	v_add_u32_e32 v144, s39, v250
	global_load_dwordx4 v[164:167], v164, s[100:101] offset:128
	global_load_dwordx4 v[168:171], v168, s[100:101] offset:128
	global_load_dwordx4 v[172:175], v172, s[100:101] offset:128
	global_load_dwordx4 v[176:179], v144, s[100:101] offset:128
	v_mov_b32_e32 v223, v148
	v_mov_b32_e32 v249, v149
	v_xor_b32_e32 v251, 0x8000, v146
	v_xor_b32_e32 v252, 0x8000, v147
	ds_read_b128 v[180:183], v223
	ds_read_b128 v[184:187], v223 offset:2048
	ds_read_b128 v[188:191], v223 offset:4096
	ds_read_b128 v[192:195], v223 offset:6144
	ds_read_b128 v[212:215], v249
	ds_read_b128 v[218:221], v249 offset:2048
	ds_read_b128 v[224:227], v249 offset:4096
	ds_read_b128 v[228:231], v249 offset:6144
.Lg2_p7_loop:
	ds_read_b128 v[196:199], v223 offset:8192
	ds_read_b128 v[200:203], v223 offset:10240
	ds_read_b128 v[204:207], v223 offset:12288
	ds_read_b128 v[208:211], v223 offset:14336
	s_waitcnt lgkmcnt(4)
	v_mfma_f32_16x16x32_bf16 v[126:129], v[212:215], v[180:183], v[126:129]
	v_mfma_f32_16x16x32_bf16 v[122:125], v[218:221], v[180:183], v[122:125]
	v_mfma_f32_16x16x32_bf16 v[118:121], v[224:227], v[180:183], v[118:121]
	v_mfma_f32_16x16x32_bf16 v[114:117], v[228:231], v[180:183], v[114:117]
	v_mfma_f32_16x16x32_bf16 v[110:113], v[212:215], v[184:187], v[110:113]
	v_mfma_f32_16x16x32_bf16 v[106:109], v[218:221], v[184:187], v[106:109]
	v_mfma_f32_16x16x32_bf16 v[102:105], v[224:227], v[184:187], v[102:105]
	v_mfma_f32_16x16x32_bf16 v[98:101], v[228:231], v[184:187], v[98:101]
	v_mfma_f32_16x16x32_bf16 v[94:97], v[212:215], v[188:191], v[94:97]
	v_mfma_f32_16x16x32_bf16 v[90:93], v[218:221], v[188:191], v[90:93]
	v_mfma_f32_16x16x32_bf16 v[86:89], v[224:227], v[188:191], v[86:89]
	v_mfma_f32_16x16x32_bf16 v[82:85], v[228:231], v[188:191], v[82:85]
	v_mfma_f32_16x16x32_bf16 v[78:81], v[212:215], v[192:195], v[78:81]
	v_mfma_f32_16x16x32_bf16 v[74:77], v[218:221], v[192:195], v[74:77]
	v_mfma_f32_16x16x32_bf16 v[70:73], v[224:227], v[192:195], v[70:73]
	v_mfma_f32_16x16x32_bf16 v[66:69], v[228:231], v[192:195], v[66:69]
	ds_read_b128 v[180:183], v216
	ds_read_b128 v[184:187], v216 offset:2048
	ds_read_b128 v[188:191], v216 offset:4096
	ds_read_b128 v[192:195], v216 offset:6144
	ds_read_b128 v[232:235], v217
	ds_read_b128 v[236:239], v217 offset:2048
	ds_read_b128 v[240:243], v217 offset:4096
	ds_read_b128 v[244:247], v217 offset:6144
	s_waitcnt lgkmcnt(8)
	v_mfma_f32_16x16x32_bf16 v[62:65], v[212:215], v[196:199], v[62:65]
	v_mfma_f32_16x16x32_bf16 v[58:61], v[218:221], v[196:199], v[58:61]
	v_mfma_f32_16x16x32_bf16 v[54:57], v[224:227], v[196:199], v[54:57]
	v_mfma_f32_16x16x32_bf16 v[50:53], v[228:231], v[196:199], v[50:53]
	v_mfma_f32_16x16x32_bf16 v[46:49], v[212:215], v[200:203], v[46:49]
	v_mfma_f32_16x16x32_bf16 v[42:45], v[218:221], v[200:203], v[42:45]
	v_mfma_f32_16x16x32_bf16 v[38:41], v[224:227], v[200:203], v[38:41]
	v_mfma_f32_16x16x32_bf16 v[34:37], v[228:231], v[200:203], v[34:37]
	v_mfma_f32_16x16x32_bf16 v[30:33], v[212:215], v[204:207], v[30:33]
	v_mfma_f32_16x16x32_bf16 v[26:29], v[218:221], v[204:207], v[26:29]
	v_mfma_f32_16x16x32_bf16 v[22:25], v[224:227], v[204:207], v[22:25]
	v_mfma_f32_16x16x32_bf16 v[18:21], v[228:231], v[204:207], v[18:21]
	v_mfma_f32_16x16x32_bf16 v[14:17], v[212:215], v[208:211], v[14:17]
	v_mfma_f32_16x16x32_bf16 v[10:13], v[218:221], v[208:211], v[10:13]
	v_mfma_f32_16x16x32_bf16 v[6:9], v[224:227], v[208:211], v[6:9]
	v_mfma_f32_16x16x32_bf16 v[2:5], v[228:231], v[208:211], v[2:5]
	ds_read_b128 v[196:199], v216 offset:8192
	ds_read_b128 v[200:203], v216 offset:10240
	ds_read_b128 v[204:207], v216 offset:12288
	ds_read_b128 v[208:211], v216 offset:14336
	s_waitcnt lgkmcnt(4)
	v_mfma_f32_16x16x32_bf16 v[126:129], v[232:235], v[180:183], v[126:129]
	v_mfma_f32_16x16x32_bf16 v[122:125], v[236:239], v[180:183], v[122:125]
	s_waitcnt vmcnt(7)
	ds_write_b128 v251, v[140:143]
	v_mfma_f32_16x16x32_bf16 v[118:121], v[240:243], v[180:183], v[118:121]
	v_mfma_f32_16x16x32_bf16 v[114:117], v[244:247], v[180:183], v[114:117]
	s_waitcnt vmcnt(6)
	ds_write_b128 v251, v[152:155] offset:8192
	v_mfma_f32_16x16x32_bf16 v[110:113], v[232:235], v[184:187], v[110:113]
	v_mfma_f32_16x16x32_bf16 v[106:109], v[236:239], v[184:187], v[106:109]
	s_waitcnt vmcnt(5)
	ds_write_b128 v251, v[156:159] offset:16384
	v_mfma_f32_16x16x32_bf16 v[102:105], v[240:243], v[184:187], v[102:105]
	v_mfma_f32_16x16x32_bf16 v[98:101], v[244:247], v[184:187], v[98:101]
	s_waitcnt vmcnt(4)
	ds_write_b128 v251, v[160:163] offset:24576
	v_mfma_f32_16x16x32_bf16 v[94:97], v[232:235], v[188:191], v[94:97]
	v_mfma_f32_16x16x32_bf16 v[90:93], v[236:239], v[188:191], v[90:93]
	s_waitcnt vmcnt(3)
	ds_write_b128 v252, v[164:167]
	v_mfma_f32_16x16x32_bf16 v[86:89], v[240:243], v[188:191], v[86:89]
	v_mfma_f32_16x16x32_bf16 v[82:85], v[244:247], v[188:191], v[82:85]
	s_waitcnt vmcnt(2)
	ds_write_b128 v252, v[168:171] offset:8192
	v_mfma_f32_16x16x32_bf16 v[78:81], v[232:235], v[192:195], v[78:81]
	v_mfma_f32_16x16x32_bf16 v[74:77], v[236:239], v[192:195], v[74:77]
	s_waitcnt vmcnt(1)
	ds_write_b128 v252, v[172:175] offset:16384
	v_mfma_f32_16x16x32_bf16 v[70:73], v[240:243], v[192:195], v[70:73]
	v_mfma_f32_16x16x32_bf16 v[66:69], v[244:247], v[192:195], v[66:69]
	s_waitcnt vmcnt(0)
	ds_write_b128 v252, v[176:179] offset:24576
	s_waitcnt lgkmcnt(0)
	s_barrier
	s_add_u32 s8, s8, 0x80
	s_addc_u32 s9, s9, 0
	s_add_u32 s98, s98, 0x80
	s_addc_u32 s99, s99, 0
	s_add_u32 s100, s100, 0x80
	s_addc_u32 s101, s101, 0
	s_cmpk_eq_i32 s8, 0x1580
	s_cbranch_scc1 .Lg2_p7_tail
	v_xor_b32_e32 v223, 0x8000, v223
	v_xor_b32_e32 v249, 0x8000, v249
	v_xor_b32_e32 v216, 0x8000, v216
	v_xor_b32_e32 v217, 0x8000, v217
	v_xor_b32_e32 v251, 0x8000, v251
	v_xor_b32_e32 v252, 0x8000, v252
	ds_read_b128 v[180:183], v223
	ds_read_b128 v[184:187], v223 offset:2048
	ds_read_b128 v[188:191], v223 offset:4096
	ds_read_b128 v[192:195], v223 offset:6144
	ds_read_b128 v[212:215], v249
	ds_read_b128 v[218:221], v249 offset:2048
	ds_read_b128 v[224:227], v249 offset:4096
	ds_read_b128 v[228:231], v249 offset:6144
	v_mfma_f32_16x16x32_bf16 v[62:65], v[232:235], v[196:199], v[62:65]
	v_add_u32_e32 v142, s16, v248
	v_mfma_f32_16x16x32_bf16 v[58:61], v[236:239], v[196:199], v[58:61]
	v_add_u32_e32 v144, s17, v248
	v_mfma_f32_16x16x32_bf16 v[54:57], v[240:243], v[196:199], v[54:57]
	v_add_u32_e32 v156, s28, v248
	v_mfma_f32_16x16x32_bf16 v[50:53], v[244:247], v[196:199], v[50:53]
	v_add_u32_e32 v160, s29, v248
	v_mfma_f32_16x16x32_bf16 v[46:49], v[232:235], v[200:203], v[46:49]
	global_load_dwordx4 v[140:143], v142, s[98:99] offset:128
	v_mfma_f32_16x16x32_bf16 v[42:45], v[236:239], v[200:203], v[42:45]
	global_load_dwordx4 v[152:155], v144, s[98:99] offset:128
	v_mfma_f32_16x16x32_bf16 v[38:41], v[240:243], v[200:203], v[38:41]
	global_load_dwordx4 v[156:159], v156, s[98:99] offset:128
	v_mfma_f32_16x16x32_bf16 v[34:37], v[244:247], v[200:203], v[34:37]
	global_load_dwordx4 v[160:163], v160, s[98:99] offset:128
	v_mfma_f32_16x16x32_bf16 v[30:33], v[232:235], v[204:207], v[30:33]
	v_add_u32_e32 v164, s36, v250
	v_mfma_f32_16x16x32_bf16 v[26:29], v[236:239], v[204:207], v[26:29]
	v_add_u32_e32 v168, s37, v250
	v_mfma_f32_16x16x32_bf16 v[22:25], v[240:243], v[204:207], v[22:25]
	v_add_u32_e32 v172, s38, v250
	v_mfma_f32_16x16x32_bf16 v[18:21], v[244:247], v[204:207], v[18:21]
	v_add_u32_e32 v144, s39, v250
	v_mfma_f32_16x16x32_bf16 v[14:17], v[232:235], v[208:211], v[14:17]
	global_load_dwordx4 v[164:167], v164, s[100:101] offset:128
	v_mfma_f32_16x16x32_bf16 v[10:13], v[236:239], v[208:211], v[10:13]
	global_load_dwordx4 v[168:171], v168, s[100:101] offset:128
	v_mfma_f32_16x16x32_bf16 v[6:9], v[240:243], v[208:211], v[6:9]
	global_load_dwordx4 v[172:175], v172, s[100:101] offset:128
	v_mfma_f32_16x16x32_bf16 v[2:5], v[244:247], v[208:211], v[2:5]
	global_load_dwordx4 v[176:179], v144, s[100:101] offset:128
	s_branch .Lg2_p7_loop
.Lg2_p7_tail:
	v_xor_b32_e32 v216, 64, v148
	v_xor_b32_e32 v217, 64, v149
	v_mfma_f32_16x16x32_bf16 v[62:65], v[232:235], v[196:199], v[62:65]
	v_mfma_f32_16x16x32_bf16 v[58:61], v[236:239], v[196:199], v[58:61]
	v_mfma_f32_16x16x32_bf16 v[54:57], v[240:243], v[196:199], v[54:57]
	v_mfma_f32_16x16x32_bf16 v[50:53], v[244:247], v[196:199], v[50:53]
	v_mfma_f32_16x16x32_bf16 v[46:49], v[232:235], v[200:203], v[46:49]
	v_mfma_f32_16x16x32_bf16 v[42:45], v[236:239], v[200:203], v[42:45]
	v_mfma_f32_16x16x32_bf16 v[38:41], v[240:243], v[200:203], v[38:41]
	v_mfma_f32_16x16x32_bf16 v[34:37], v[244:247], v[200:203], v[34:37]
	v_mfma_f32_16x16x32_bf16 v[30:33], v[232:235], v[204:207], v[30:33]
	v_mfma_f32_16x16x32_bf16 v[26:29], v[236:239], v[204:207], v[26:29]
	v_mfma_f32_16x16x32_bf16 v[22:25], v[240:243], v[204:207], v[22:25]
	v_mfma_f32_16x16x32_bf16 v[18:21], v[244:247], v[204:207], v[18:21]
	v_mfma_f32_16x16x32_bf16 v[14:17], v[232:235], v[208:211], v[14:17]
	v_mfma_f32_16x16x32_bf16 v[10:13], v[236:239], v[208:211], v[10:13]
	v_mfma_f32_16x16x32_bf16 v[6:9], v[240:243], v[208:211], v[6:9]
	v_mfma_f32_16x16x32_bf16 v[2:5], v[244:247], v[208:211], v[2:5]
	ds_read_b128 v[136:139], v149 offset:32768
	ds_read_b128 v[140:143], v149 offset:34816
	ds_read_b128 v[152:155], v149 offset:36864
	ds_read_b128 v[156:159], v149 offset:38912
	ds_read_b128 v[160:163], v148 offset:32768
	ds_read_b128 v[164:167], v148 offset:34816
	ds_read_b128 v[168:171], v148 offset:36864
	ds_read_b128 v[172:175], v148 offset:38912
	s_setprio 1
	s_waitcnt lgkmcnt(3)
	v_mfma_f32_16x16x32_bf16 v[126:129], v[136:139], v[160:163], v[126:129]
	v_mfma_f32_16x16x32_bf16 v[122:125], v[140:143], v[160:163], v[122:125]
	v_mfma_f32_16x16x32_bf16 v[118:121], v[152:155], v[160:163], v[118:121]
	v_mfma_f32_16x16x32_bf16 v[114:117], v[156:159], v[160:163], v[114:117]
	s_waitcnt lgkmcnt(2)
	v_mfma_f32_16x16x32_bf16 v[110:113], v[136:139], v[164:167], v[110:113]
	v_mfma_f32_16x16x32_bf16 v[106:109], v[140:143], v[164:167], v[106:109]
	v_mfma_f32_16x16x32_bf16 v[102:105], v[152:155], v[164:167], v[102:105]
	v_mfma_f32_16x16x32_bf16 v[98:101], v[156:159], v[164:167], v[98:101]
	s_waitcnt lgkmcnt(1)
	v_mfma_f32_16x16x32_bf16 v[94:97], v[136:139], v[168:171], v[94:97]
	v_mfma_f32_16x16x32_bf16 v[90:93], v[140:143], v[168:171], v[90:93]
	v_mfma_f32_16x16x32_bf16 v[86:89], v[152:155], v[168:171], v[86:89]
	v_mfma_f32_16x16x32_bf16 v[82:85], v[156:159], v[168:171], v[82:85]
	s_waitcnt lgkmcnt(0)
	v_mfma_f32_16x16x32_bf16 v[78:81], v[136:139], v[172:175], v[78:81]
	v_mfma_f32_16x16x32_bf16 v[74:77], v[140:143], v[172:175], v[74:77]
	v_mfma_f32_16x16x32_bf16 v[70:73], v[152:155], v[172:175], v[70:73]
	v_mfma_f32_16x16x32_bf16 v[66:69], v[156:159], v[172:175], v[66:69]
	s_setprio 0
	ds_read_b128 v[160:163], v148 offset:40960
	ds_read_b128 v[164:167], v148 offset:43008
	ds_read_b128 v[168:171], v148 offset:45056
	ds_read_b128 v[172:175], v148 offset:47104
	s_setprio 1
	s_waitcnt lgkmcnt(3)
	v_mfma_f32_16x16x32_bf16 v[62:65], v[136:139], v[160:163], v[62:65]
	v_mfma_f32_16x16x32_bf16 v[58:61], v[140:143], v[160:163], v[58:61]
	v_mfma_f32_16x16x32_bf16 v[54:57], v[152:155], v[160:163], v[54:57]
	v_mfma_f32_16x16x32_bf16 v[50:53], v[156:159], v[160:163], v[50:53]
	s_waitcnt lgkmcnt(2)
	v_mfma_f32_16x16x32_bf16 v[46:49], v[136:139], v[164:167], v[46:49]
	v_mfma_f32_16x16x32_bf16 v[42:45], v[140:143], v[164:167], v[42:45]
	v_mfma_f32_16x16x32_bf16 v[38:41], v[152:155], v[164:167], v[38:41]
	v_mfma_f32_16x16x32_bf16 v[34:37], v[156:159], v[164:167], v[34:37]
	s_waitcnt lgkmcnt(1)
	v_mfma_f32_16x16x32_bf16 v[30:33], v[136:139], v[168:171], v[30:33]
	v_mfma_f32_16x16x32_bf16 v[26:29], v[140:143], v[168:171], v[26:29]
	v_mfma_f32_16x16x32_bf16 v[22:25], v[152:155], v[168:171], v[22:25]
	v_mfma_f32_16x16x32_bf16 v[18:21], v[156:159], v[168:171], v[18:21]
	s_waitcnt lgkmcnt(0)
	v_mfma_f32_16x16x32_bf16 v[14:17], v[136:139], v[172:175], v[14:17]
	v_mfma_f32_16x16x32_bf16 v[10:13], v[140:143], v[172:175], v[10:13]
	v_mfma_f32_16x16x32_bf16 v[6:9], v[152:155], v[172:175], v[6:9]
	v_mfma_f32_16x16x32_bf16 v[2:5], v[156:159], v[172:175], v[2:5]
	s_setprio 0
	ds_read_b128 v[136:139], v217 offset:32768
	ds_read_b128 v[140:143], v217 offset:34816
	ds_read_b128 v[152:155], v217 offset:36864
	ds_read_b128 v[156:159], v217 offset:38912
	ds_read_b128 v[160:163], v216 offset:32768
	ds_read_b128 v[164:167], v216 offset:34816
	ds_read_b128 v[168:171], v216 offset:36864
	ds_read_b128 v[172:175], v216 offset:38912
	s_setprio 1
	s_waitcnt lgkmcnt(3)
	v_mfma_f32_16x16x32_bf16 v[126:129], v[136:139], v[160:163], v[126:129]
	v_mfma_f32_16x16x32_bf16 v[122:125], v[140:143], v[160:163], v[122:125]
	v_mfma_f32_16x16x32_bf16 v[118:121], v[152:155], v[160:163], v[118:121]
	v_mfma_f32_16x16x32_bf16 v[114:117], v[156:159], v[160:163], v[114:117]
	s_waitcnt lgkmcnt(2)
	v_mfma_f32_16x16x32_bf16 v[110:113], v[136:139], v[164:167], v[110:113]
	v_mfma_f32_16x16x32_bf16 v[106:109], v[140:143], v[164:167], v[106:109]
	v_mfma_f32_16x16x32_bf16 v[102:105], v[152:155], v[164:167], v[102:105]
	v_mfma_f32_16x16x32_bf16 v[98:101], v[156:159], v[164:167], v[98:101]
	s_waitcnt lgkmcnt(1)
	v_mfma_f32_16x16x32_bf16 v[94:97], v[136:139], v[168:171], v[94:97]
	v_mfma_f32_16x16x32_bf16 v[90:93], v[140:143], v[168:171], v[90:93]
	v_mfma_f32_16x16x32_bf16 v[86:89], v[152:155], v[168:171], v[86:89]
	v_mfma_f32_16x16x32_bf16 v[82:85], v[156:159], v[168:171], v[82:85]
	s_waitcnt lgkmcnt(0)
	v_mfma_f32_16x16x32_bf16 v[78:81], v[136:139], v[172:175], v[78:81]
	v_mfma_f32_16x16x32_bf16 v[74:77], v[140:143], v[172:175], v[74:77]
	v_mfma_f32_16x16x32_bf16 v[70:73], v[152:155], v[172:175], v[70:73]
	v_mfma_f32_16x16x32_bf16 v[66:69], v[156:159], v[172:175], v[66:69]
	s_setprio 0
	ds_read_b128 v[160:163], v216 offset:40960
	ds_read_b128 v[164:167], v216 offset:43008
	ds_read_b128 v[168:171], v216 offset:45056
	ds_read_b128 v[172:175], v216 offset:47104
	s_setprio 1
	s_waitcnt lgkmcnt(3)
	v_mfma_f32_16x16x32_bf16 v[62:65], v[136:139], v[160:163], v[62:65]
	v_mfma_f32_16x16x32_bf16 v[58:61], v[140:143], v[160:163], v[58:61]
	v_mfma_f32_16x16x32_bf16 v[54:57], v[152:155], v[160:163], v[54:57]
	v_mfma_f32_16x16x32_bf16 v[50:53], v[156:159], v[160:163], v[50:53]
	s_waitcnt lgkmcnt(2)
	v_mfma_f32_16x16x32_bf16 v[46:49], v[136:139], v[164:167], v[46:49]
	v_mfma_f32_16x16x32_bf16 v[42:45], v[140:143], v[164:167], v[42:45]
	v_mfma_f32_16x16x32_bf16 v[38:41], v[152:155], v[164:167], v[38:41]
	v_mfma_f32_16x16x32_bf16 v[34:37], v[156:159], v[164:167], v[34:37]
	s_waitcnt lgkmcnt(1)
	v_mfma_f32_16x16x32_bf16 v[30:33], v[136:139], v[168:171], v[30:33]
	v_mfma_f32_16x16x32_bf16 v[26:29], v[140:143], v[168:171], v[26:29]
	v_mfma_f32_16x16x32_bf16 v[22:25], v[152:155], v[168:171], v[22:25]
	v_mfma_f32_16x16x32_bf16 v[18:21], v[156:159], v[168:171], v[18:21]
	s_waitcnt lgkmcnt(0)
	v_mfma_f32_16x16x32_bf16 v[14:17], v[136:139], v[172:175], v[14:17]
	v_mfma_f32_16x16x32_bf16 v[10:13], v[140:143], v[172:175], v[10:13]
	v_mfma_f32_16x16x32_bf16 v[6:9], v[152:155], v[172:175], v[6:9]
	v_mfma_f32_16x16x32_bf16 v[2:5], v[156:159], v[172:175], v[2:5]
	s_setprio 0
	v_add_u32_e32 v152, s47, v150
	v_mul_hi_i32 v136, v152, s40
	v_lshrrev_b32_e32 v137, 31, v136
	v_ashrrev_i32_e32 v136, 11, v136
	v_add_u32_e32 v137, v136, v137
	v_mad_i32_i24 v142, v137, s41, v152
	v_lshlrev_b32_e32 v139, 13, v137
	v_cmp_lt_i32_e32 vcc, s42, v142
	v_add3_u32 v138, v139, v142, s43
	s_barrier
	s_and_saveexec_b64 s[8:9], vcc
	s_xor_b64 s[8:9], exec, s[8:9]
	v_add3_u32 v136, v139, v142, s43
	s_or_saveexec_b64 s[8:9], s[8:9]
	v_mov_b64_e32 v[140:141], s[84:85]
	v_lshl_add_u32 v139, v137, 8, v142
	s_xor_b64 exec, exec, s[8:9]
	v_lshl_add_u32 v136, v137, 8, v142
	v_mov_b64_e32 v[140:141], s[4:5]
	s_or_b64 exec, exec, s[8:9]
	s_and_saveexec_b64 s[8:9], vcc
	s_xor_b64 s[8:9], exec, s[8:9]
	s_cbranch_execz .LBB0_386
	v_mul_hi_i32_i24_e32 v143, 0x6000, v137
	v_mul_i32_i24_e32 v142, 0x6000, v137
	s_or_saveexec_b64 s[8:9], s[8:9]
	v_mov_b64_e32 v[144:145], s[84:85]
	s_xor_b64 exec, exec, s[8:9]
	s_cbranch_execnz .LBB0_387
	s_branch .LBB0_388

.LBB0_645:
	s_lshl_b32 s36, s28, 8
	v_or_b32_e32 v2, s36, v1
	v_ashrrev_i32_e32 v3, 31, v2
	v_lshlrev_b64 v[62:63], 11, v[2:3]
	v_lshl_add_u64 v[2:3], v[130:131], 0, v[62:63]
	v_add_co_u32_e32 v6, vcc, 0x20000, v2
	s_lshl_b32 s29, s27, 8
	s_nop 0
	v_addc_co_u32_e32 v7, vcc, 0, v3, vcc
	v_or_b32_e32 v4, s29, v1
	global_load_dwordx4 v[30:33], v[2:3], off
	global_load_dwordx4 v[34:37], v[6:7], off
	v_add_co_u32_e32 v6, vcc, 0x40000, v2
	v_ashrrev_i32_e32 v5, 31, v4
	s_nop 0
	v_addc_co_u32_e32 v7, vcc, 0, v3, vcc
	v_lshlrev_b64 v[64:65], 11, v[4:5]
	v_add_co_u32_e32 v2, vcc, 0x60000, v2
	v_lshl_add_u64 v[4:5], v[132:133], 0, v[64:65]
	s_nop 0
	v_addc_co_u32_e32 v3, vcc, 0, v3, vcc
	global_load_dwordx4 v[38:41], v[6:7], off
	global_load_dwordx4 v[42:45], v[2:3], off
	v_add_co_u32_e32 v2, vcc, s12, v4
	s_waitcnt vmcnt(63) expcnt(7) lgkmcnt(15)
	s_nop 0
	v_addc_co_u32_e32 v3, vcc, 0, v5, vcc
	s_barrier
	global_load_dwordx4 v[46:49], v[4:5], off
	global_load_dwordx4 v[50:53], v[2:3], off
	v_add_co_u32_e32 v2, vcc, s13, v4
	s_mov_b32 s37, 0
	s_nop 0
	v_addc_co_u32_e32 v3, vcc, 0, v5, vcc
	v_add_co_u32_e32 v4, vcc, s14, v4
	s_mov_b64 s[8:9], 0
	s_nop 0
	v_addc_co_u32_e32 v5, vcc, 0, v5, vcc
	global_load_dwordx4 v[54:57], v[2:3], off
	global_load_dwordx4 v[58:61], v[4:5], off
	v_mov_b32_e32 v2, 0
	v_mov_b32_e32 v3, v2
	v_mov_b32_e32 v4, v2
	v_mov_b32_e32 v5, v2
	v_mov_b32_e32 v6, v2
	v_mov_b32_e32 v7, v2
	v_mov_b32_e32 v8, v2
	v_mov_b32_e32 v9, v2
	v_mov_b32_e32 v10, v2
	v_mov_b32_e32 v11, v2
	v_mov_b32_e32 v12, v2
	v_mov_b32_e32 v13, v2
	v_mov_b32_e32 v14, v2
	v_mov_b32_e32 v15, v2
	v_mov_b32_e32 v16, v2
	v_mov_b32_e32 v17, v2
	v_mov_b32_e32 v18, v2
	v_mov_b32_e32 v19, v2
	v_mov_b32_e32 v20, v2
	v_mov_b32_e32 v21, v2
	v_mov_b32_e32 v22, v2
	v_mov_b32_e32 v23, v2
	v_mov_b32_e32 v24, v2
	v_mov_b32_e32 v25, v2
	v_mov_b32_e32 v26, v2
	v_mov_b32_e32 v27, v2
	v_mov_b32_e32 v28, v2
	v_lshl_add_u64 v[136:137], v[134:135], 0, v[62:63]
	v_lshl_add_u64 v[138:139], v[134:135], 0, v[64:65]
	v_mov_b32_e32 v29, v2
	v_mov_b32_e32 v62, v2
	v_mov_b32_e32 v63, v2
	v_mov_b32_e32 v64, v2
	v_mov_b32_e32 v65, v2
	v_mov_b32_e32 v66, v2
	v_mov_b32_e32 v67, v2
	v_mov_b32_e32 v68, v2
	v_mov_b32_e32 v69, v2
	v_mov_b32_e32 v70, v2
	v_mov_b32_e32 v71, v2
	v_mov_b32_e32 v72, v2
	v_mov_b32_e32 v73, v2
	v_mov_b32_e32 v74, v2
	v_mov_b32_e32 v75, v2
	v_mov_b32_e32 v76, v2
	v_mov_b32_e32 v77, v2
	v_mov_b32_e32 v78, v2
	v_mov_b32_e32 v79, v2
	v_mov_b32_e32 v80, v2
	v_mov_b32_e32 v81, v2
	v_mov_b32_e32 v82, v2
	v_mov_b32_e32 v83, v2
	v_mov_b32_e32 v84, v2
	s_waitcnt vmcnt(7)
	ds_write_b128 v146, v[30:33]
	s_waitcnt vmcnt(6)
	ds_write_b128 v146, v[34:37] offset:8192
	s_waitcnt vmcnt(5)
	ds_write_b128 v146, v[38:41] offset:16384
	s_waitcnt vmcnt(4)
	ds_write_b128 v146, v[42:45] offset:24576
	s_waitcnt vmcnt(3)
	ds_write_b128 v147, v[46:49]
	s_waitcnt vmcnt(2)
	ds_write_b128 v147, v[50:53] offset:8192
	s_waitcnt vmcnt(1)
	ds_write_b128 v147, v[54:57] offset:16384
	s_waitcnt vmcnt(0)
	ds_write_b128 v147, v[58:61] offset:24576
	v_mov_b32_e32 v30, v2
	v_mov_b32_e32 v31, v2
	v_mov_b32_e32 v32, v2
	v_mov_b32_e32 v33, v2
	v_mov_b32_e32 v34, v2
	v_mov_b32_e32 v35, v2
	v_mov_b32_e32 v36, v2
	v_mov_b32_e32 v37, v2
	v_mov_b32_e32 v38, v2
	v_mov_b32_e32 v39, v2
	v_mov_b32_e32 v40, v2
	v_mov_b32_e32 v41, v2
	v_mov_b32_e32 v42, v2
	v_mov_b32_e32 v43, v2
	v_mov_b32_e32 v44, v2
	v_mov_b32_e32 v45, v2
	v_mov_b32_e32 v46, v2
	v_mov_b32_e32 v47, v2
	v_mov_b32_e32 v48, v2
	v_mov_b32_e32 v49, v2
	v_mov_b32_e32 v50, v2
	v_mov_b32_e32 v51, v2
	v_mov_b32_e32 v52, v2
	v_mov_b32_e32 v53, v2
	v_mov_b32_e32 v54, v2
	v_mov_b32_e32 v55, v2
	v_mov_b32_e32 v56, v2
	v_mov_b32_e32 v57, v2
	v_mov_b32_e32 v58, v2
	v_mov_b32_e32 v59, v2
	v_mov_b32_e32 v60, v2
	v_mov_b32_e32 v61, v2
	v_mov_b32_e32 v85, v2
	v_mov_b32_e32 v86, v2
	v_mov_b32_e32 v87, v2
	v_mov_b32_e32 v88, v2
	v_mov_b32_e32 v89, v2
	v_mov_b32_e32 v90, v2
	v_mov_b32_e32 v91, v2
	v_mov_b32_e32 v92, v2
	v_mov_b32_e32 v93, v2
	v_mov_b32_e32 v94, v2
	v_mov_b32_e32 v95, v2
	v_mov_b32_e32 v96, v2
	v_mov_b32_e32 v97, v2
	v_mov_b32_e32 v98, v2
	v_mov_b32_e32 v99, v2
	v_mov_b32_e32 v100, v2
	v_mov_b32_e32 v101, v2
	v_mov_b32_e32 v102, v2
	v_mov_b32_e32 v103, v2
	v_mov_b32_e32 v104, v2
	v_mov_b32_e32 v105, v2
	v_mov_b32_e32 v106, v2
	v_mov_b32_e32 v107, v2
	v_mov_b32_e32 v108, v2
	v_mov_b32_e32 v109, v2
	v_mov_b32_e32 v110, v2
	v_mov_b32_e32 v111, v2
	v_mov_b32_e32 v112, v2
	v_mov_b32_e32 v113, v2
	v_mov_b32_e32 v114, v2
	v_mov_b32_e32 v115, v2
	v_mov_b32_e32 v116, v2
	v_mov_b32_e32 v117, v2
	v_mov_b32_e32 v118, v2
	v_mov_b32_e32 v119, v2
	v_mov_b32_e32 v120, v2
	v_mov_b32_e32 v121, v2
	v_mov_b32_e32 v122, v2
	v_mov_b32_e32 v123, v2
	v_mov_b32_e32 v124, v2
	v_mov_b32_e32 v125, v2
	v_mov_b32_e32 v126, v2
	v_mov_b32_e32 v127, v2
	v_mov_b32_e32 v128, v2
	v_mov_b32_e32 v129, v2
	s_waitcnt lgkmcnt(0)
	s_barrier
	v_readfirstlane_b32 s98, v136
	v_readfirstlane_b32 s99, v137
	v_subrev_u32_e32 v248, s98, v136
	s_add_u32 s98, s98, s8
	s_addc_u32 s99, s99, s9
	v_readfirstlane_b32 s100, v138
	v_readfirstlane_b32 s101, v139
	v_subrev_u32_e32 v250, s100, v138
	s_add_u32 s100, s100, s8
	s_addc_u32 s101, s101, s9
	v_add_u32_e32 v142, s15, v248
	v_add_u32_e32 v144, s16, v248
	v_add_u32_e32 v156, s17, v248
	v_add_u32_e32 v160, s18, v248
	global_load_dwordx4 v[140:143], v142, s[98:99] offset:128
	global_load_dwordx4 v[152:155], v144, s[98:99] offset:128
	global_load_dwordx4 v[156:159], v156, s[98:99] offset:128
	global_load_dwordx4 v[160:163], v160, s[98:99] offset:128
	v_add_u32_e32 v164, s19, v250
	v_add_u32_e32 v168, s20, v250
	v_add_u32_e32 v172, s21, v250
	v_add_u32_e32 v144, s22, v250
	global_load_dwordx4 v[164:167], v164, s[100:101] offset:128
	global_load_dwordx4 v[168:171], v168, s[100:101] offset:128
	global_load_dwordx4 v[172:175], v172, s[100:101] offset:128
	global_load_dwordx4 v[176:179], v144, s[100:101] offset:128
	v_mov_b32_e32 v223, v148
	v_mov_b32_e32 v249, v149
	v_xor_b32_e32 v251, 0x8000, v146
	v_xor_b32_e32 v252, 0x8000, v147
	ds_read_b128 v[180:183], v223
	ds_read_b128 v[184:187], v223 offset:2048
	ds_read_b128 v[188:191], v223 offset:4096
	ds_read_b128 v[192:195], v223 offset:6144
	ds_read_b128 v[212:215], v249
	ds_read_b128 v[218:221], v249 offset:2048
	ds_read_b128 v[224:227], v249 offset:4096
	ds_read_b128 v[228:231], v249 offset:6144
.Lg2_p12_loop:
	ds_read_b128 v[196:199], v223 offset:8192
	ds_read_b128 v[200:203], v223 offset:10240
	ds_read_b128 v[204:207], v223 offset:12288
	ds_read_b128 v[208:211], v223 offset:14336
	s_waitcnt lgkmcnt(4)
	v_mfma_f32_16x16x32_bf16 v[126:129], v[212:215], v[180:183], v[126:129]
	v_mfma_f32_16x16x32_bf16 v[122:125], v[218:221], v[180:183], v[122:125]
	v_mfma_f32_16x16x32_bf16 v[118:121], v[224:227], v[180:183], v[118:121]
	v_mfma_f32_16x16x32_bf16 v[114:117], v[228:231], v[180:183], v[114:117]
	v_mfma_f32_16x16x32_bf16 v[110:113], v[212:215], v[184:187], v[110:113]
	v_mfma_f32_16x16x32_bf16 v[106:109], v[218:221], v[184:187], v[106:109]
	v_mfma_f32_16x16x32_bf16 v[102:105], v[224:227], v[184:187], v[102:105]
	v_mfma_f32_16x16x32_bf16 v[98:101], v[228:231], v[184:187], v[98:101]
	v_mfma_f32_16x16x32_bf16 v[94:97], v[212:215], v[188:191], v[94:97]
	v_mfma_f32_16x16x32_bf16 v[90:93], v[218:221], v[188:191], v[90:93]
	v_mfma_f32_16x16x32_bf16 v[86:89], v[224:227], v[188:191], v[86:89]
	v_mfma_f32_16x16x32_bf16 v[82:85], v[228:231], v[188:191], v[82:85]
	v_mfma_f32_16x16x32_bf16 v[78:81], v[212:215], v[192:195], v[78:81]
	v_mfma_f32_16x16x32_bf16 v[74:77], v[218:221], v[192:195], v[74:77]
	v_mfma_f32_16x16x32_bf16 v[70:73], v[224:227], v[192:195], v[70:73]
	v_mfma_f32_16x16x32_bf16 v[66:69], v[228:231], v[192:195], v[66:69]
	ds_read_b128 v[180:183], v216
	ds_read_b128 v[184:187], v216 offset:2048
	ds_read_b128 v[188:191], v216 offset:4096
	ds_read_b128 v[192:195], v216 offset:6144
	ds_read_b128 v[232:235], v217
	ds_read_b128 v[236:239], v217 offset:2048
	ds_read_b128 v[240:243], v217 offset:4096
	ds_read_b128 v[244:247], v217 offset:6144
	s_waitcnt lgkmcnt(8)
	v_mfma_f32_16x16x32_bf16 v[62:65], v[212:215], v[196:199], v[62:65]
	v_mfma_f32_16x16x32_bf16 v[58:61], v[218:221], v[196:199], v[58:61]
	v_mfma_f32_16x16x32_bf16 v[54:57], v[224:227], v[196:199], v[54:57]
	v_mfma_f32_16x16x32_bf16 v[50:53], v[228:231], v[196:199], v[50:53]
	v_mfma_f32_16x16x32_bf16 v[46:49], v[212:215], v[200:203], v[46:49]
	v_mfma_f32_16x16x32_bf16 v[42:45], v[218:221], v[200:203], v[42:45]
	v_mfma_f32_16x16x32_bf16 v[38:41], v[224:227], v[200:203], v[38:41]
	v_mfma_f32_16x16x32_bf16 v[34:37], v[228:231], v[200:203], v[34:37]
	v_mfma_f32_16x16x32_bf16 v[30:33], v[212:215], v[204:207], v[30:33]
	v_mfma_f32_16x16x32_bf16 v[26:29], v[218:221], v[204:207], v[26:29]
	v_mfma_f32_16x16x32_bf16 v[22:25], v[224:227], v[204:207], v[22:25]
	v_mfma_f32_16x16x32_bf16 v[18:21], v[228:231], v[204:207], v[18:21]
	v_mfma_f32_16x16x32_bf16 v[14:17], v[212:215], v[208:211], v[14:17]
	v_mfma_f32_16x16x32_bf16 v[10:13], v[218:221], v[208:211], v[10:13]
	v_mfma_f32_16x16x32_bf16 v[6:9], v[224:227], v[208:211], v[6:9]
	v_mfma_f32_16x16x32_bf16 v[2:5], v[228:231], v[208:211], v[2:5]
	ds_read_b128 v[196:199], v216 offset:8192
	ds_read_b128 v[200:203], v216 offset:10240
	ds_read_b128 v[204:207], v216 offset:12288
	ds_read_b128 v[208:211], v216 offset:14336
	s_waitcnt lgkmcnt(4)
	v_mfma_f32_16x16x32_bf16 v[126:129], v[232:235], v[180:183], v[126:129]
	v_mfma_f32_16x16x32_bf16 v[122:125], v[236:239], v[180:183], v[122:125]
	s_waitcnt vmcnt(7)
	ds_write_b128 v251, v[140:143]
	v_mfma_f32_16x16x32_bf16 v[118:121], v[240:243], v[180:183], v[118:121]
	v_mfma_f32_16x16x32_bf16 v[114:117], v[244:247], v[180:183], v[114:117]
	s_waitcnt vmcnt(6)
	ds_write_b128 v251, v[152:155] offset:8192
	v_mfma_f32_16x16x32_bf16 v[110:113], v[232:235], v[184:187], v[110:113]
	v_mfma_f32_16x16x32_bf16 v[106:109], v[236:239], v[184:187], v[106:109]
	s_waitcnt vmcnt(5)
	ds_write_b128 v251, v[156:159] offset:16384
	v_mfma_f32_16x16x32_bf16 v[102:105], v[240:243], v[184:187], v[102:105]
	v_mfma_f32_16x16x32_bf16 v[98:101], v[244:247], v[184:187], v[98:101]
	s_waitcnt vmcnt(4)
	ds_write_b128 v251, v[160:163] offset:24576
	v_mfma_f32_16x16x32_bf16 v[94:97], v[232:235], v[188:191], v[94:97]
	v_mfma_f32_16x16x32_bf16 v[90:93], v[236:239], v[188:191], v[90:93]
	s_waitcnt vmcnt(3)
	ds_write_b128 v252, v[164:167]
	v_mfma_f32_16x16x32_bf16 v[86:89], v[240:243], v[188:191], v[86:89]
	v_mfma_f32_16x16x32_bf16 v[82:85], v[244:247], v[188:191], v[82:85]
	s_waitcnt vmcnt(2)
	ds_write_b128 v252, v[168:171] offset:8192
	v_mfma_f32_16x16x32_bf16 v[78:81], v[232:235], v[192:195], v[78:81]
	v_mfma_f32_16x16x32_bf16 v[74:77], v[236:239], v[192:195], v[74:77]
	s_waitcnt vmcnt(1)
	ds_write_b128 v252, v[172:175] offset:16384
	v_mfma_f32_16x16x32_bf16 v[70:73], v[240:243], v[192:195], v[70:73]
	v_mfma_f32_16x16x32_bf16 v[66:69], v[244:247], v[192:195], v[66:69]
	s_waitcnt vmcnt(0)
	ds_write_b128 v252, v[176:179] offset:24576
	s_waitcnt lgkmcnt(0)
	s_barrier
	s_add_u32 s8, s8, 0x80
	s_addc_u32 s9, s9, 0
	s_add_u32 s98, s98, 0x80
	s_addc_u32 s99, s99, 0
	s_add_u32 s100, s100, 0x80
	s_addc_u32 s101, s101, 0
	s_cmpk_eq_i32 s8, 0x780
	s_cbranch_scc1 .Lg2_p12_tail
	v_xor_b32_e32 v223, 0x8000, v223
	v_xor_b32_e32 v249, 0x8000, v249
	v_xor_b32_e32 v216, 0x8000, v216
	v_xor_b32_e32 v217, 0x8000, v217
	v_xor_b32_e32 v251, 0x8000, v251
	v_xor_b32_e32 v252, 0x8000, v252
	ds_read_b128 v[180:183], v223
	ds_read_b128 v[184:187], v223 offset:2048
	ds_read_b128 v[188:191], v223 offset:4096
	ds_read_b128 v[192:195], v223 offset:6144
	ds_read_b128 v[212:215], v249
	ds_read_b128 v[218:221], v249 offset:2048
	ds_read_b128 v[224:227], v249 offset:4096
	ds_read_b128 v[228:231], v249 offset:6144
	v_mfma_f32_16x16x32_bf16 v[62:65], v[232:235], v[196:199], v[62:65]
	v_add_u32_e32 v142, s15, v248
	v_mfma_f32_16x16x32_bf16 v[58:61], v[236:239], v[196:199], v[58:61]
	v_add_u32_e32 v144, s16, v248
	v_mfma_f32_16x16x32_bf16 v[54:57], v[240:243], v[196:199], v[54:57]
	v_add_u32_e32 v156, s17, v248
	v_mfma_f32_16x16x32_bf16 v[50:53], v[244:247], v[196:199], v[50:53]
	v_add_u32_e32 v160, s18, v248
	v_mfma_f32_16x16x32_bf16 v[46:49], v[232:235], v[200:203], v[46:49]
	global_load_dwordx4 v[140:143], v142, s[98:99] offset:128
	v_mfma_f32_16x16x32_bf16 v[42:45], v[236:239], v[200:203], v[42:45]
	global_load_dwordx4 v[152:155], v144, s[98:99] offset:128
	v_mfma_f32_16x16x32_bf16 v[38:41], v[240:243], v[200:203], v[38:41]
	global_load_dwordx4 v[156:159], v156, s[98:99] offset:128
	v_mfma_f32_16x16x32_bf16 v[34:37], v[244:247], v[200:203], v[34:37]
	global_load_dwordx4 v[160:163], v160, s[98:99] offset:128
	v_mfma_f32_16x16x32_bf16 v[30:33], v[232:235], v[204:207], v[30:33]
	v_add_u32_e32 v164, s19, v250
	v_mfma_f32_16x16x32_bf16 v[26:29], v[236:239], v[204:207], v[26:29]
	v_add_u32_e32 v168, s20, v250
	v_mfma_f32_16x16x32_bf16 v[22:25], v[240:243], v[204:207], v[22:25]
	v_add_u32_e32 v172, s21, v250
	v_mfma_f32_16x16x32_bf16 v[18:21], v[244:247], v[204:207], v[18:21]
	v_add_u32_e32 v144, s22, v250
	v_mfma_f32_16x16x32_bf16 v[14:17], v[232:235], v[208:211], v[14:17]
	global_load_dwordx4 v[164:167], v164, s[100:101] offset:128
	v_mfma_f32_16x16x32_bf16 v[10:13], v[236:239], v[208:211], v[10:13]
	global_load_dwordx4 v[168:171], v168, s[100:101] offset:128
	v_mfma_f32_16x16x32_bf16 v[6:9], v[240:243], v[208:211], v[6:9]
	global_load_dwordx4 v[172:175], v172, s[100:101] offset:128
	v_mfma_f32_16x16x32_bf16 v[2:5], v[244:247], v[208:211], v[2:5]
	global_load_dwordx4 v[176:179], v144, s[100:101] offset:128
	s_branch .Lg2_p12_loop
.Lg2_p12_tail:
	v_xor_b32_e32 v216, 64, v148
	v_xor_b32_e32 v217, 64, v149
	v_mfma_f32_16x16x32_bf16 v[62:65], v[232:235], v[196:199], v[62:65]
	v_mfma_f32_16x16x32_bf16 v[58:61], v[236:239], v[196:199], v[58:61]
	v_mfma_f32_16x16x32_bf16 v[54:57], v[240:243], v[196:199], v[54:57]
	v_mfma_f32_16x16x32_bf16 v[50:53], v[244:247], v[196:199], v[50:53]
	v_mfma_f32_16x16x32_bf16 v[46:49], v[232:235], v[200:203], v[46:49]
	v_mfma_f32_16x16x32_bf16 v[42:45], v[236:239], v[200:203], v[42:45]
	v_mfma_f32_16x16x32_bf16 v[38:41], v[240:243], v[200:203], v[38:41]
	v_mfma_f32_16x16x32_bf16 v[34:37], v[244:247], v[200:203], v[34:37]
	v_mfma_f32_16x16x32_bf16 v[30:33], v[232:235], v[204:207], v[30:33]
	v_mfma_f32_16x16x32_bf16 v[26:29], v[236:239], v[204:207], v[26:29]
	v_mfma_f32_16x16x32_bf16 v[22:25], v[240:243], v[204:207], v[22:25]
	v_mfma_f32_16x16x32_bf16 v[18:21], v[244:247], v[204:207], v[18:21]
	v_mfma_f32_16x16x32_bf16 v[14:17], v[232:235], v[208:211], v[14:17]
	v_mfma_f32_16x16x32_bf16 v[10:13], v[236:239], v[208:211], v[10:13]
	v_mfma_f32_16x16x32_bf16 v[6:9], v[240:243], v[208:211], v[6:9]
	v_mfma_f32_16x16x32_bf16 v[2:5], v[244:247], v[208:211], v[2:5]
	ds_read_b128 v[136:139], v149 offset:32768
	ds_read_b128 v[140:143], v149 offset:34816
	ds_read_b128 v[152:155], v149 offset:36864
	ds_read_b128 v[156:159], v149 offset:38912
	ds_read_b128 v[160:163], v148 offset:32768
	ds_read_b128 v[164:167], v148 offset:34816
	ds_read_b128 v[168:171], v148 offset:36864
	ds_read_b128 v[172:175], v148 offset:38912
	s_setprio 1
	s_waitcnt lgkmcnt(3)
	v_mfma_f32_16x16x32_bf16 v[126:129], v[136:139], v[160:163], v[126:129]
	v_mfma_f32_16x16x32_bf16 v[122:125], v[140:143], v[160:163], v[122:125]
	v_mfma_f32_16x16x32_bf16 v[118:121], v[152:155], v[160:163], v[118:121]
	v_mfma_f32_16x16x32_bf16 v[114:117], v[156:159], v[160:163], v[114:117]
	s_waitcnt lgkmcnt(2)
	v_mfma_f32_16x16x32_bf16 v[110:113], v[136:139], v[164:167], v[110:113]
	v_mfma_f32_16x16x32_bf16 v[106:109], v[140:143], v[164:167], v[106:109]
	v_mfma_f32_16x16x32_bf16 v[102:105], v[152:155], v[164:167], v[102:105]
	v_mfma_f32_16x16x32_bf16 v[98:101], v[156:159], v[164:167], v[98:101]
	s_waitcnt lgkmcnt(1)
	v_mfma_f32_16x16x32_bf16 v[94:97], v[136:139], v[168:171], v[94:97]
	v_mfma_f32_16x16x32_bf16 v[90:93], v[140:143], v[168:171], v[90:93]
	v_mfma_f32_16x16x32_bf16 v[86:89], v[152:155], v[168:171], v[86:89]
	v_mfma_f32_16x16x32_bf16 v[82:85], v[156:159], v[168:171], v[82:85]
	s_waitcnt lgkmcnt(0)
	v_mfma_f32_16x16x32_bf16 v[78:81], v[136:139], v[172:175], v[78:81]
	v_mfma_f32_16x16x32_bf16 v[74:77], v[140:143], v[172:175], v[74:77]
	v_mfma_f32_16x16x32_bf16 v[70:73], v[152:155], v[172:175], v[70:73]
	v_mfma_f32_16x16x32_bf16 v[66:69], v[156:159], v[172:175], v[66:69]
	s_setprio 0
	ds_read_b128 v[160:163], v148 offset:40960
	ds_read_b128 v[164:167], v148 offset:43008
	ds_read_b128 v[168:171], v148 offset:45056
	ds_read_b128 v[172:175], v148 offset:47104
	s_setprio 1
	s_waitcnt lgkmcnt(3)
	v_mfma_f32_16x16x32_bf16 v[62:65], v[136:139], v[160:163], v[62:65]
	v_mfma_f32_16x16x32_bf16 v[58:61], v[140:143], v[160:163], v[58:61]
	v_mfma_f32_16x16x32_bf16 v[54:57], v[152:155], v[160:163], v[54:57]
	v_mfma_f32_16x16x32_bf16 v[50:53], v[156:159], v[160:163], v[50:53]
	s_waitcnt lgkmcnt(2)
	v_mfma_f32_16x16x32_bf16 v[46:49], v[136:139], v[164:167], v[46:49]
	v_mfma_f32_16x16x32_bf16 v[42:45], v[140:143], v[164:167], v[42:45]
	v_mfma_f32_16x16x32_bf16 v[38:41], v[152:155], v[164:167], v[38:41]
	v_mfma_f32_16x16x32_bf16 v[34:37], v[156:159], v[164:167], v[34:37]
	s_waitcnt lgkmcnt(1)
	v_mfma_f32_16x16x32_bf16 v[30:33], v[136:139], v[168:171], v[30:33]
	v_mfma_f32_16x16x32_bf16 v[26:29], v[140:143], v[168:171], v[26:29]
	v_mfma_f32_16x16x32_bf16 v[22:25], v[152:155], v[168:171], v[22:25]
	v_mfma_f32_16x16x32_bf16 v[18:21], v[156:159], v[168:171], v[18:21]
	s_waitcnt lgkmcnt(0)
	v_mfma_f32_16x16x32_bf16 v[14:17], v[136:139], v[172:175], v[14:17]
	v_mfma_f32_16x16x32_bf16 v[10:13], v[140:143], v[172:175], v[10:13]
	v_mfma_f32_16x16x32_bf16 v[6:9], v[152:155], v[172:175], v[6:9]
	v_mfma_f32_16x16x32_bf16 v[2:5], v[156:159], v[172:175], v[2:5]
	s_setprio 0
	ds_read_b128 v[136:139], v217 offset:32768
	ds_read_b128 v[140:143], v217 offset:34816
	ds_read_b128 v[152:155], v217 offset:36864
	ds_read_b128 v[156:159], v217 offset:38912
	ds_read_b128 v[160:163], v216 offset:32768
	ds_read_b128 v[164:167], v216 offset:34816
	ds_read_b128 v[168:171], v216 offset:36864
	ds_read_b128 v[172:175], v216 offset:38912
	s_setprio 1
	s_waitcnt lgkmcnt(3)
	v_mfma_f32_16x16x32_bf16 v[126:129], v[136:139], v[160:163], v[126:129]
	v_mfma_f32_16x16x32_bf16 v[122:125], v[140:143], v[160:163], v[122:125]
	v_mfma_f32_16x16x32_bf16 v[118:121], v[152:155], v[160:163], v[118:121]
	v_mfma_f32_16x16x32_bf16 v[114:117], v[156:159], v[160:163], v[114:117]
	s_waitcnt lgkmcnt(2)
	v_mfma_f32_16x16x32_bf16 v[110:113], v[136:139], v[164:167], v[110:113]
	v_mfma_f32_16x16x32_bf16 v[106:109], v[140:143], v[164:167], v[106:109]
	v_mfma_f32_16x16x32_bf16 v[102:105], v[152:155], v[164:167], v[102:105]
	v_mfma_f32_16x16x32_bf16 v[98:101], v[156:159], v[164:167], v[98:101]
	s_waitcnt lgkmcnt(1)
	v_mfma_f32_16x16x32_bf16 v[94:97], v[136:139], v[168:171], v[94:97]
	v_mfma_f32_16x16x32_bf16 v[90:93], v[140:143], v[168:171], v[90:93]
	v_mfma_f32_16x16x32_bf16 v[86:89], v[152:155], v[168:171], v[86:89]
	v_mfma_f32_16x16x32_bf16 v[82:85], v[156:159], v[168:171], v[82:85]
	s_waitcnt lgkmcnt(0)
	v_mfma_f32_16x16x32_bf16 v[78:81], v[136:139], v[172:175], v[78:81]
	v_mfma_f32_16x16x32_bf16 v[74:77], v[140:143], v[172:175], v[74:77]
	v_mfma_f32_16x16x32_bf16 v[70:73], v[152:155], v[172:175], v[70:73]
	v_mfma_f32_16x16x32_bf16 v[66:69], v[156:159], v[172:175], v[66:69]
	s_setprio 0
	ds_read_b128 v[160:163], v216 offset:40960
	ds_read_b128 v[164:167], v216 offset:43008
	ds_read_b128 v[168:171], v216 offset:45056
	ds_read_b128 v[172:175], v216 offset:47104
	s_setprio 1
	s_waitcnt lgkmcnt(3)
	v_mfma_f32_16x16x32_bf16 v[62:65], v[136:139], v[160:163], v[62:65]
	v_mfma_f32_16x16x32_bf16 v[58:61], v[140:143], v[160:163], v[58:61]
	v_mfma_f32_16x16x32_bf16 v[54:57], v[152:155], v[160:163], v[54:57]
	v_mfma_f32_16x16x32_bf16 v[50:53], v[156:159], v[160:163], v[50:53]
	s_waitcnt lgkmcnt(2)
	v_mfma_f32_16x16x32_bf16 v[46:49], v[136:139], v[164:167], v[46:49]
	v_mfma_f32_16x16x32_bf16 v[42:45], v[140:143], v[164:167], v[42:45]
	v_mfma_f32_16x16x32_bf16 v[38:41], v[152:155], v[164:167], v[38:41]
	v_mfma_f32_16x16x32_bf16 v[34:37], v[156:159], v[164:167], v[34:37]
	s_waitcnt lgkmcnt(1)
	v_mfma_f32_16x16x32_bf16 v[30:33], v[136:139], v[168:171], v[30:33]
	v_mfma_f32_16x16x32_bf16 v[26:29], v[140:143], v[168:171], v[26:29]
	v_mfma_f32_16x16x32_bf16 v[22:25], v[152:155], v[168:171], v[22:25]
	v_mfma_f32_16x16x32_bf16 v[18:21], v[156:159], v[168:171], v[18:21]
	s_waitcnt lgkmcnt(0)
	v_mfma_f32_16x16x32_bf16 v[14:17], v[136:139], v[172:175], v[14:17]
	v_mfma_f32_16x16x32_bf16 v[10:13], v[140:143], v[172:175], v[10:13]
	v_mfma_f32_16x16x32_bf16 v[6:9], v[152:155], v[172:175], v[6:9]
	v_mfma_f32_16x16x32_bf16 v[2:5], v[156:159], v[172:175], v[2:5]
	s_setprio 0
	v_add_u32_e32 v152, s36, v150
	v_mul_hi_i32 v136, v152, s23
	v_lshrrev_b32_e32 v137, 31, v136
	v_ashrrev_i32_e32 v136, 11, v136
	v_add_u32_e32 v137, v136, v137
	v_mad_i32_i24 v142, v137, s24, v152
	v_lshlrev_b32_e32 v139, 13, v137
	v_cmp_lt_i32_e32 vcc, s25, v142
	v_add3_u32 v138, v139, v142, s26
	s_barrier
	s_and_saveexec_b64 s[8:9], vcc
	s_xor_b64 s[8:9], exec, s[8:9]
	v_add3_u32 v136, v139, v142, s26
	s_or_saveexec_b64 s[8:9], s[8:9]
	v_mov_b64_e32 v[140:141], s[84:85]
	v_lshl_add_u32 v139, v137, 8, v142
	s_xor_b64 exec, exec, s[8:9]
	v_lshl_add_u32 v136, v137, 8, v142
	v_mov_b64_e32 v[140:141], s[0:1]
	s_or_b64 exec, exec, s[8:9]
	s_and_saveexec_b64 s[8:9], vcc
	s_xor_b64 s[8:9], exec, s[8:9]
	s_cbranch_execz .LBB0_653
	v_mul_hi_i32_i24_e32 v143, 0x6000, v137
	v_mul_i32_i24_e32 v142, 0x6000, v137
	s_or_saveexec_b64 s[8:9], s[8:9]
	v_mov_b64_e32 v[144:145], s[84:85]
	s_xor_b64 exec, exec, s[8:9]
	s_cbranch_execnz .LBB0_654
	s_branch .LBB0_655

.LBB0_749:
	s_mul_hi_i32 s0, s3, 0x2e8ba2e9
	s_lshr_b32 s1, s0, 31
	s_ashr_i32 s0, s0, 4
	s_add_i32 s24, s0, s1
	s_mul_i32 s1, s24, 0xffffffa8
	s_add_i32 s1, s1, s3
	s_ashr_i32 s21, s1, 31
	s_lshl_b32 s0, s24, 2
	s_lshr_b32 s21, s21, 30
	s_add_i32 s21, s1, s21
	s_add_i32 s0, s6, s0
	s_ashr_i32 s22, s21, 2
	s_add_i32 s0, s0, s1
	s_lshl_b32 s25, s22, 10
	s_lshl_b32 s0, s0, 8
	s_sub_i32 s21, s0, s25
	v_or_b32_e32 v2, s21, v1
	v_ashrrev_i32_e32 v3, 31, v2
	v_lshlrev_b64 v[2:3], 11, v[2:3]
	v_lshl_add_u64 v[2:3], v[132:133], 0, v[2:3]
	v_add_co_u32_e32 v6, vcc, s9, v2
	s_lshl_b32 s22, s22, 8
	s_nop 0
	v_addc_co_u32_e32 v7, vcc, 0, v3, vcc
	v_or_b32_e32 v4, s22, v1
	global_load_dwordx4 v[20:23], v[2:3], off
	global_load_dwordx4 v[24:27], v[6:7], off
	v_add_co_u32_e32 v6, vcc, s10, v2
	v_ashrrev_i32_e32 v5, 31, v4
	s_nop 0
	v_addc_co_u32_e32 v7, vcc, 0, v3, vcc
	v_lshlrev_b64 v[52:53], 11, v[4:5]
	v_add_co_u32_e32 v2, vcc, s11, v2
	v_lshl_add_u64 v[4:5], v[134:135], 0, v[52:53]
	s_nop 0
	v_addc_co_u32_e32 v3, vcc, 0, v3, vcc
	global_load_dwordx4 v[28:31], v[6:7], off
	global_load_dwordx4 v[32:35], v[2:3], off
	v_add_co_u32_e32 v2, vcc, s9, v4
	s_waitcnt vmcnt(63) expcnt(7) lgkmcnt(15)
	s_nop 0
	v_addc_co_u32_e32 v3, vcc, 0, v5, vcc
	s_barrier
	global_load_dwordx4 v[36:39], v[4:5], off
	global_load_dwordx4 v[40:43], v[2:3], off
	v_add_co_u32_e32 v2, vcc, s10, v4
	s_mulk_i32 s24, 0x5400
	s_nop 0
	v_addc_co_u32_e32 v3, vcc, 0, v5, vcc
	v_add_co_u32_e32 v4, vcc, s11, v4
	v_subrev_u32_e32 v19, s25, v130
	s_nop 0
	v_addc_co_u32_e32 v5, vcc, 0, v5, vcc
	global_load_dwordx4 v[44:47], v[2:3], off
	global_load_dwordx4 v[48:51], v[4:5], off
	v_subrev_u32_e32 v54, s24, v19
	v_ashrrev_i32_e32 v55, 31, v54
	v_lshlrev_b64 v[54:55], 11, v[54:55]
	s_mov_b64 s[0:1], 0
	s_mov_b32 s23, 0
	v_mov_b32_e32 v2, 0
	v_mov_b32_e32 v3, v131
	v_mov_b32_e32 v4, v131
	v_mov_b32_e32 v5, v131
	v_mov_b32_e32 v6, 0
	v_mov_b32_e32 v7, v131
	v_mov_b32_e32 v8, v131
	v_mov_b32_e32 v9, v131
	v_mov_b32_e32 v10, 0
	v_mov_b32_e32 v11, v131
	v_mov_b32_e32 v12, v131
	v_mov_b32_e32 v13, v131
	v_mov_b32_e32 v14, 0
	v_mov_b32_e32 v15, v131
	v_mov_b32_e32 v16, v131
	v_mov_b32_e32 v17, v131
	v_mov_b32_e32 v18, 0
	v_lshl_add_u64 v[140:141], v[138:139], 0, v[52:53]
	v_lshl_add_u64 v[142:143], v[138:139], 0, v[54:55]
	v_mov_b32_e32 v19, v131
	v_mov_b32_e32 v52, v131
	v_mov_b32_e32 v53, v131
	v_mov_b32_e32 v54, 0
	v_mov_b32_e32 v55, v131
	v_mov_b32_e32 v56, v131
	v_mov_b32_e32 v57, v131
	v_mov_b32_e32 v58, 0
	v_mov_b32_e32 v59, v131
	v_mov_b32_e32 v60, v131
	v_mov_b32_e32 v61, v131
	v_mov_b32_e32 v62, 0
	v_mov_b32_e32 v63, v131
	v_mov_b32_e32 v64, v131
	v_mov_b32_e32 v65, v131
	v_mov_b32_e32 v66, 0
	v_mov_b32_e32 v67, v131
	v_mov_b32_e32 v68, v131
	v_mov_b32_e32 v69, v131
	v_mov_b32_e32 v70, 0
	v_mov_b32_e32 v71, v131
	v_mov_b32_e32 v72, v131
	v_mov_b32_e32 v73, v131
	v_mov_b32_e32 v74, 0
	s_waitcnt vmcnt(7)
	ds_write_b128 v144, v[20:23]
	s_waitcnt vmcnt(6)
	ds_write_b128 v144, v[24:27] offset:8192
	s_waitcnt vmcnt(5)
	ds_write_b128 v144, v[28:31] offset:16384
	s_waitcnt vmcnt(4)
	ds_write_b128 v144, v[32:35] offset:24576
	s_waitcnt vmcnt(3)
	ds_write_b128 v145, v[36:39]
	s_waitcnt vmcnt(2)
	ds_write_b128 v145, v[40:43] offset:8192
	s_waitcnt vmcnt(1)
	ds_write_b128 v145, v[44:47] offset:16384
	s_waitcnt vmcnt(0)
	ds_write_b128 v145, v[48:51] offset:24576
	v_mov_b32_e32 v20, v131
	v_mov_b32_e32 v21, v131
	v_mov_b32_e32 v22, 0
	v_mov_b32_e32 v23, v131
	v_mov_b32_e32 v24, v131
	v_mov_b32_e32 v25, v131
	v_mov_b32_e32 v26, 0
	v_mov_b32_e32 v27, v131
	v_mov_b32_e32 v28, v131
	v_mov_b32_e32 v29, v131
	v_mov_b32_e32 v30, 0
	v_mov_b32_e32 v31, v131
	v_mov_b32_e32 v32, v131
	v_mov_b32_e32 v33, v131
	v_mov_b32_e32 v34, 0
	v_mov_b32_e32 v35, v131
	v_mov_b32_e32 v36, v131
	v_mov_b32_e32 v37, v131
	v_mov_b32_e32 v38, 0
	v_mov_b32_e32 v39, v131
	v_mov_b32_e32 v40, v131
	v_mov_b32_e32 v41, v131
	v_mov_b32_e32 v42, 0
	v_mov_b32_e32 v43, v131
	v_mov_b32_e32 v44, v131
	v_mov_b32_e32 v45, v131
	v_mov_b32_e32 v46, 0
	v_mov_b32_e32 v47, v131
	v_mov_b32_e32 v48, v131
	v_mov_b32_e32 v49, v131
	v_mov_b32_e32 v50, 0
	v_mov_b32_e32 v51, v131
	v_mov_b32_e32 v75, v131
	v_mov_b32_e32 v76, v131
	v_mov_b32_e32 v77, v131
	v_mov_b32_e32 v78, 0
	v_mov_b32_e32 v79, v131
	v_mov_b32_e32 v80, v131
	v_mov_b32_e32 v81, v131
	v_mov_b32_e32 v82, 0
	v_mov_b32_e32 v83, v131
	v_mov_b32_e32 v84, v131
	v_mov_b32_e32 v85, v131
	v_mov_b32_e32 v86, 0
	v_mov_b32_e32 v87, v131
	v_mov_b32_e32 v88, v131
	v_mov_b32_e32 v89, v131
	v_mov_b32_e32 v90, 0
	v_mov_b32_e32 v91, v131
	v_mov_b32_e32 v92, v131
	v_mov_b32_e32 v93, v131
	v_mov_b32_e32 v94, 0
	v_mov_b32_e32 v95, v131
	v_mov_b32_e32 v96, v131
	v_mov_b32_e32 v97, v131
	v_mov_b32_e32 v98, 0
	v_mov_b32_e32 v99, v131
	v_mov_b32_e32 v100, v131
	v_mov_b32_e32 v101, v131
	v_mov_b32_e32 v102, 0
	v_mov_b32_e32 v103, v131
	v_mov_b32_e32 v104, v131
	v_mov_b32_e32 v105, v131
	v_mov_b32_e32 v106, 0
	v_mov_b32_e32 v107, v131
	v_mov_b32_e32 v108, v131
	v_mov_b32_e32 v109, v131
	v_mov_b32_e32 v110, 0
	v_mov_b32_e32 v111, v131
	v_mov_b32_e32 v112, v131
	v_mov_b32_e32 v113, v131
	v_mov_b32_e32 v114, 0
	v_mov_b32_e32 v115, v131
	v_mov_b32_e32 v116, v131
	v_mov_b32_e32 v117, v131
	v_mov_b32_e32 v118, 0
	v_mov_b32_e32 v119, v131
	v_mov_b32_e32 v120, v131
	v_mov_b32_e32 v121, v131
	v_mov_b32_e32 v122, 0
	v_mov_b32_e32 v123, v131
	v_mov_b32_e32 v124, v131
	v_mov_b32_e32 v125, v131
	v_mov_b32_e32 v126, 0
	v_mov_b32_e32 v127, v131
	v_mov_b32_e32 v128, v131
	v_mov_b32_e32 v129, v131
	s_waitcnt lgkmcnt(0)
	s_barrier
	v_readfirstlane_b32 s98, v142
	v_readfirstlane_b32 s99, v143
	v_subrev_u32_e32 v215, s98, v142
	s_add_u32 s98, s98, s0
	s_addc_u32 s99, s99, s1
	v_readfirstlane_b32 s100, v140
	v_readfirstlane_b32 s101, v141
	v_subrev_u32_e32 v252, s100, v140
	s_add_u32 s100, s100, s0
	s_addc_u32 s101, s101, s1
	v_add_u32_e32 v152, s12, v215
	v_add_u32_e32 v154, s13, v215
	v_add_u32_e32 v158, s14, v215
	v_add_u32_e32 v162, s15, v215
	global_load_dwordx4 v[150:153], v152, s[98:99] offset:128
	global_load_dwordx4 v[154:157], v154, s[98:99] offset:128
	global_load_dwordx4 v[158:161], v158, s[98:99] offset:128
	global_load_dwordx4 v[162:165], v162, s[98:99] offset:128
	v_add_u32_e32 v166, s16, v252
	v_add_u32_e32 v170, s17, v252
	v_add_u32_e32 v176, s18, v252
	v_add_u32_e32 v178, s19, v252
	global_load_dwordx4 v[166:169], v166, s[100:101] offset:128
	global_load_dwordx4 v[170:173], v170, s[100:101] offset:128
	global_load_dwordx4 v[174:177], v176, s[100:101] offset:128
	global_load_dwordx4 v[178:181], v178, s[100:101] offset:128
	v_mov_b32_e32 v214, v146
	v_mov_b32_e32 v223, v147
	v_xor_b32_e32 v253, 0x8000, v144
	v_xor_b32_e32 v254, 0x8000, v145
	ds_read_b128 v[182:185], v214
	ds_read_b128 v[186:189], v214 offset:2048
	ds_read_b128 v[190:193], v214 offset:4096
	ds_read_b128 v[194:197], v214 offset:6144
	ds_read_b128 v[218:221], v223
	ds_read_b128 v[224:227], v223 offset:2048
	ds_read_b128 v[228:231], v223 offset:4096
	ds_read_b128 v[232:235], v223 offset:6144
.Lg2_p14_loop:
	ds_read_b128 v[198:201], v214 offset:8192
	ds_read_b128 v[202:205], v214 offset:10240
	ds_read_b128 v[206:209], v214 offset:12288
	ds_read_b128 v[210:213], v214 offset:14336
	s_waitcnt lgkmcnt(4)
	v_mfma_f32_16x16x32_bf16 v[126:129], v[218:221], v[182:185], v[126:129]
	v_mfma_f32_16x16x32_bf16 v[122:125], v[224:227], v[182:185], v[122:125]
	v_mfma_f32_16x16x32_bf16 v[118:121], v[228:231], v[182:185], v[118:121]
	v_mfma_f32_16x16x32_bf16 v[114:117], v[232:235], v[182:185], v[114:117]
	v_mfma_f32_16x16x32_bf16 v[110:113], v[218:221], v[186:189], v[110:113]
	v_mfma_f32_16x16x32_bf16 v[106:109], v[224:227], v[186:189], v[106:109]
	v_mfma_f32_16x16x32_bf16 v[102:105], v[228:231], v[186:189], v[102:105]
	v_mfma_f32_16x16x32_bf16 v[98:101], v[232:235], v[186:189], v[98:101]
	v_mfma_f32_16x16x32_bf16 v[94:97], v[218:221], v[190:193], v[94:97]
	v_mfma_f32_16x16x32_bf16 v[90:93], v[224:227], v[190:193], v[90:93]
	v_mfma_f32_16x16x32_bf16 v[86:89], v[228:231], v[190:193], v[86:89]
	v_mfma_f32_16x16x32_bf16 v[82:85], v[232:235], v[190:193], v[82:85]
	v_mfma_f32_16x16x32_bf16 v[78:81], v[218:221], v[194:197], v[78:81]
	v_mfma_f32_16x16x32_bf16 v[74:77], v[224:227], v[194:197], v[74:77]
	v_mfma_f32_16x16x32_bf16 v[70:73], v[228:231], v[194:197], v[70:73]
	v_mfma_f32_16x16x32_bf16 v[66:69], v[232:235], v[194:197], v[66:69]
	ds_read_b128 v[182:185], v216
	ds_read_b128 v[186:189], v216 offset:2048
	ds_read_b128 v[190:193], v216 offset:4096
	ds_read_b128 v[194:197], v216 offset:6144
	ds_read_b128 v[236:239], v217
	ds_read_b128 v[240:243], v217 offset:2048
	ds_read_b128 v[244:247], v217 offset:4096
	ds_read_b128 v[248:251], v217 offset:6144
	s_waitcnt lgkmcnt(8)
	v_mfma_f32_16x16x32_bf16 v[62:65], v[218:221], v[198:201], v[62:65]
	v_mfma_f32_16x16x32_bf16 v[58:61], v[224:227], v[198:201], v[58:61]
	v_mfma_f32_16x16x32_bf16 v[54:57], v[228:231], v[198:201], v[54:57]
	v_mfma_f32_16x16x32_bf16 v[50:53], v[232:235], v[198:201], v[50:53]
	v_mfma_f32_16x16x32_bf16 v[46:49], v[218:221], v[202:205], v[46:49]
	v_mfma_f32_16x16x32_bf16 v[42:45], v[224:227], v[202:205], v[42:45]
	v_mfma_f32_16x16x32_bf16 v[38:41], v[228:231], v[202:205], v[38:41]
	v_mfma_f32_16x16x32_bf16 v[34:37], v[232:235], v[202:205], v[34:37]
	v_mfma_f32_16x16x32_bf16 v[30:33], v[218:221], v[206:209], v[30:33]
	v_mfma_f32_16x16x32_bf16 v[26:29], v[224:227], v[206:209], v[26:29]
	v_mfma_f32_16x16x32_bf16 v[22:25], v[228:231], v[206:209], v[22:25]
	v_mfma_f32_16x16x32_bf16 v[18:21], v[232:235], v[206:209], v[18:21]
	v_mfma_f32_16x16x32_bf16 v[14:17], v[218:221], v[210:213], v[14:17]
	v_mfma_f32_16x16x32_bf16 v[10:13], v[224:227], v[210:213], v[10:13]
	v_mfma_f32_16x16x32_bf16 v[6:9], v[228:231], v[210:213], v[6:9]
	v_mfma_f32_16x16x32_bf16 v[2:5], v[232:235], v[210:213], v[2:5]
	ds_read_b128 v[198:201], v216 offset:8192
	ds_read_b128 v[202:205], v216 offset:10240
	ds_read_b128 v[206:209], v216 offset:12288
	ds_read_b128 v[210:213], v216 offset:14336
	s_waitcnt lgkmcnt(4)
	v_mfma_f32_16x16x32_bf16 v[126:129], v[236:239], v[182:185], v[126:129]
	v_mfma_f32_16x16x32_bf16 v[122:125], v[240:243], v[182:185], v[122:125]
	s_waitcnt vmcnt(7)
	ds_write_b128 v253, v[150:153]
	v_mfma_f32_16x16x32_bf16 v[118:121], v[244:247], v[182:185], v[118:121]
	v_mfma_f32_16x16x32_bf16 v[114:117], v[248:251], v[182:185], v[114:117]
	s_waitcnt vmcnt(6)
	ds_write_b128 v253, v[154:157] offset:8192
	v_mfma_f32_16x16x32_bf16 v[110:113], v[236:239], v[186:189], v[110:113]
	v_mfma_f32_16x16x32_bf16 v[106:109], v[240:243], v[186:189], v[106:109]
	s_waitcnt vmcnt(5)
	ds_write_b128 v253, v[158:161] offset:16384
	v_mfma_f32_16x16x32_bf16 v[102:105], v[244:247], v[186:189], v[102:105]
	v_mfma_f32_16x16x32_bf16 v[98:101], v[248:251], v[186:189], v[98:101]
	s_waitcnt vmcnt(4)
	ds_write_b128 v253, v[162:165] offset:24576
	v_mfma_f32_16x16x32_bf16 v[94:97], v[236:239], v[190:193], v[94:97]
	v_mfma_f32_16x16x32_bf16 v[90:93], v[240:243], v[190:193], v[90:93]
	s_waitcnt vmcnt(3)
	ds_write_b128 v254, v[166:169]
	v_mfma_f32_16x16x32_bf16 v[86:89], v[244:247], v[190:193], v[86:89]
	v_mfma_f32_16x16x32_bf16 v[82:85], v[248:251], v[190:193], v[82:85]
	s_waitcnt vmcnt(2)
	ds_write_b128 v254, v[170:173] offset:8192
	v_mfma_f32_16x16x32_bf16 v[78:81], v[236:239], v[194:197], v[78:81]
	v_mfma_f32_16x16x32_bf16 v[74:77], v[240:243], v[194:197], v[74:77]
	s_waitcnt vmcnt(1)
	ds_write_b128 v254, v[174:177] offset:16384
	v_mfma_f32_16x16x32_bf16 v[70:73], v[244:247], v[194:197], v[70:73]
	v_mfma_f32_16x16x32_bf16 v[66:69], v[248:251], v[194:197], v[66:69]
	s_waitcnt vmcnt(0)
	ds_write_b128 v254, v[178:181] offset:24576
	s_waitcnt lgkmcnt(0)
	s_barrier
	s_add_u32 s0, s0, 0x80
	s_addc_u32 s1, s1, 0
	s_add_u32 s98, s98, 0x80
	s_addc_u32 s99, s99, 0
	s_add_u32 s100, s100, 0x80
	s_addc_u32 s101, s101, 0
	s_cmpk_eq_i32 s0, 0x780
	s_cbranch_scc1 .Lg2_p14_tail
	v_xor_b32_e32 v214, 0x8000, v214
	v_xor_b32_e32 v223, 0x8000, v223
	v_xor_b32_e32 v216, 0x8000, v216
	v_xor_b32_e32 v217, 0x8000, v217
	v_xor_b32_e32 v253, 0x8000, v253
	v_xor_b32_e32 v254, 0x8000, v254
	ds_read_b128 v[182:185], v214
	ds_read_b128 v[186:189], v214 offset:2048
	ds_read_b128 v[190:193], v214 offset:4096
	ds_read_b128 v[194:197], v214 offset:6144
	ds_read_b128 v[218:221], v223
	ds_read_b128 v[224:227], v223 offset:2048
	ds_read_b128 v[228:231], v223 offset:4096
	ds_read_b128 v[232:235], v223 offset:6144
	v_mfma_f32_16x16x32_bf16 v[62:65], v[236:239], v[198:201], v[62:65]
	v_add_u32_e32 v152, s12, v215
	v_mfma_f32_16x16x32_bf16 v[58:61], v[240:243], v[198:201], v[58:61]
	v_add_u32_e32 v154, s13, v215
	v_mfma_f32_16x16x32_bf16 v[54:57], v[244:247], v[198:201], v[54:57]
	v_add_u32_e32 v158, s14, v215
	v_mfma_f32_16x16x32_bf16 v[50:53], v[248:251], v[198:201], v[50:53]
	v_add_u32_e32 v162, s15, v215
	v_mfma_f32_16x16x32_bf16 v[46:49], v[236:239], v[202:205], v[46:49]
	global_load_dwordx4 v[150:153], v152, s[98:99] offset:128
	v_mfma_f32_16x16x32_bf16 v[42:45], v[240:243], v[202:205], v[42:45]
	global_load_dwordx4 v[154:157], v154, s[98:99] offset:128
	v_mfma_f32_16x16x32_bf16 v[38:41], v[244:247], v[202:205], v[38:41]
	global_load_dwordx4 v[158:161], v158, s[98:99] offset:128
	v_mfma_f32_16x16x32_bf16 v[34:37], v[248:251], v[202:205], v[34:37]
	global_load_dwordx4 v[162:165], v162, s[98:99] offset:128
	v_mfma_f32_16x16x32_bf16 v[30:33], v[236:239], v[206:209], v[30:33]
	v_add_u32_e32 v166, s16, v252
	v_mfma_f32_16x16x32_bf16 v[26:29], v[240:243], v[206:209], v[26:29]
	v_add_u32_e32 v170, s17, v252
	v_mfma_f32_16x16x32_bf16 v[22:25], v[244:247], v[206:209], v[22:25]
	v_add_u32_e32 v176, s18, v252
	v_mfma_f32_16x16x32_bf16 v[18:21], v[248:251], v[206:209], v[18:21]
	v_add_u32_e32 v178, s19, v252
	v_mfma_f32_16x16x32_bf16 v[14:17], v[236:239], v[210:213], v[14:17]
	global_load_dwordx4 v[166:169], v166, s[100:101] offset:128
	v_mfma_f32_16x16x32_bf16 v[10:13], v[240:243], v[210:213], v[10:13]
	global_load_dwordx4 v[170:173], v170, s[100:101] offset:128
	v_mfma_f32_16x16x32_bf16 v[6:9], v[244:247], v[210:213], v[6:9]
	global_load_dwordx4 v[174:177], v176, s[100:101] offset:128
	v_mfma_f32_16x16x32_bf16 v[2:5], v[248:251], v[210:213], v[2:5]
	global_load_dwordx4 v[178:181], v178, s[100:101] offset:128
	s_branch .Lg2_p14_loop
.Lg2_p14_tail:
	v_xor_b32_e32 v216, 64, v146
	v_xor_b32_e32 v217, 64, v147
	v_mfma_f32_16x16x32_bf16 v[62:65], v[236:239], v[198:201], v[62:65]
	v_mfma_f32_16x16x32_bf16 v[58:61], v[240:243], v[198:201], v[58:61]
	v_mfma_f32_16x16x32_bf16 v[54:57], v[244:247], v[198:201], v[54:57]
	v_mfma_f32_16x16x32_bf16 v[50:53], v[248:251], v[198:201], v[50:53]
	v_mfma_f32_16x16x32_bf16 v[46:49], v[236:239], v[202:205], v[46:49]
	v_mfma_f32_16x16x32_bf16 v[42:45], v[240:243], v[202:205], v[42:45]
	v_mfma_f32_16x16x32_bf16 v[38:41], v[244:247], v[202:205], v[38:41]
	v_mfma_f32_16x16x32_bf16 v[34:37], v[248:251], v[202:205], v[34:37]
	v_mfma_f32_16x16x32_bf16 v[30:33], v[236:239], v[206:209], v[30:33]
	v_mfma_f32_16x16x32_bf16 v[26:29], v[240:243], v[206:209], v[26:29]
	v_mfma_f32_16x16x32_bf16 v[22:25], v[244:247], v[206:209], v[22:25]
	v_mfma_f32_16x16x32_bf16 v[18:21], v[248:251], v[206:209], v[18:21]
	v_mfma_f32_16x16x32_bf16 v[14:17], v[236:239], v[210:213], v[14:17]
	v_mfma_f32_16x16x32_bf16 v[10:13], v[240:243], v[210:213], v[10:13]
	v_mfma_f32_16x16x32_bf16 v[6:9], v[244:247], v[210:213], v[6:9]
	v_mfma_f32_16x16x32_bf16 v[2:5], v[248:251], v[210:213], v[2:5]
	ds_read_b128 v[140:143], v147 offset:32768
	ds_read_b128 v[150:153], v147 offset:34816
	ds_read_b128 v[154:157], v147 offset:36864
	ds_read_b128 v[158:161], v147 offset:38912
	ds_read_b128 v[162:165], v146 offset:32768
	ds_read_b128 v[166:169], v146 offset:34816
	ds_read_b128 v[170:173], v146 offset:36864
	ds_read_b128 v[174:177], v146 offset:38912
	s_setprio 1
	s_waitcnt lgkmcnt(3)
	v_mfma_f32_16x16x32_bf16 v[126:129], v[140:143], v[162:165], v[126:129]
	v_mfma_f32_16x16x32_bf16 v[122:125], v[150:153], v[162:165], v[122:125]
	v_mfma_f32_16x16x32_bf16 v[118:121], v[154:157], v[162:165], v[118:121]
	v_mfma_f32_16x16x32_bf16 v[114:117], v[158:161], v[162:165], v[114:117]
	s_waitcnt lgkmcnt(2)
	v_mfma_f32_16x16x32_bf16 v[110:113], v[140:143], v[166:169], v[110:113]
	v_mfma_f32_16x16x32_bf16 v[106:109], v[150:153], v[166:169], v[106:109]
	v_mfma_f32_16x16x32_bf16 v[102:105], v[154:157], v[166:169], v[102:105]
	v_mfma_f32_16x16x32_bf16 v[98:101], v[158:161], v[166:169], v[98:101]
	s_waitcnt lgkmcnt(1)
	v_mfma_f32_16x16x32_bf16 v[94:97], v[140:143], v[170:173], v[94:97]
	v_mfma_f32_16x16x32_bf16 v[90:93], v[150:153], v[170:173], v[90:93]
	v_mfma_f32_16x16x32_bf16 v[86:89], v[154:157], v[170:173], v[86:89]
	v_mfma_f32_16x16x32_bf16 v[82:85], v[158:161], v[170:173], v[82:85]
	s_waitcnt lgkmcnt(0)
	v_mfma_f32_16x16x32_bf16 v[78:81], v[140:143], v[174:177], v[78:81]
	v_mfma_f32_16x16x32_bf16 v[74:77], v[150:153], v[174:177], v[74:77]
	v_mfma_f32_16x16x32_bf16 v[70:73], v[154:157], v[174:177], v[70:73]
	v_mfma_f32_16x16x32_bf16 v[66:69], v[158:161], v[174:177], v[66:69]
	s_setprio 0
	ds_read_b128 v[162:165], v146 offset:40960
	ds_read_b128 v[166:169], v146 offset:43008
	ds_read_b128 v[170:173], v146 offset:45056
	ds_read_b128 v[174:177], v146 offset:47104
	s_setprio 1
	s_waitcnt lgkmcnt(3)
	v_mfma_f32_16x16x32_bf16 v[62:65], v[140:143], v[162:165], v[62:65]
	v_mfma_f32_16x16x32_bf16 v[58:61], v[150:153], v[162:165], v[58:61]
	v_mfma_f32_16x16x32_bf16 v[54:57], v[154:157], v[162:165], v[54:57]
	v_mfma_f32_16x16x32_bf16 v[50:53], v[158:161], v[162:165], v[50:53]
	s_waitcnt lgkmcnt(2)
	v_mfma_f32_16x16x32_bf16 v[46:49], v[140:143], v[166:169], v[46:49]
	v_mfma_f32_16x16x32_bf16 v[42:45], v[150:153], v[166:169], v[42:45]
	v_mfma_f32_16x16x32_bf16 v[38:41], v[154:157], v[166:169], v[38:41]
	v_mfma_f32_16x16x32_bf16 v[34:37], v[158:161], v[166:169], v[34:37]
	s_waitcnt lgkmcnt(1)
	v_mfma_f32_16x16x32_bf16 v[30:33], v[140:143], v[170:173], v[30:33]
	v_mfma_f32_16x16x32_bf16 v[26:29], v[150:153], v[170:173], v[26:29]
	v_mfma_f32_16x16x32_bf16 v[22:25], v[154:157], v[170:173], v[22:25]
	v_mfma_f32_16x16x32_bf16 v[18:21], v[158:161], v[170:173], v[18:21]
	s_waitcnt lgkmcnt(0)
	v_mfma_f32_16x16x32_bf16 v[14:17], v[140:143], v[174:177], v[14:17]
	v_mfma_f32_16x16x32_bf16 v[10:13], v[150:153], v[174:177], v[10:13]
	v_mfma_f32_16x16x32_bf16 v[6:9], v[154:157], v[174:177], v[6:9]
	v_mfma_f32_16x16x32_bf16 v[2:5], v[158:161], v[174:177], v[2:5]
	s_setprio 0
	ds_read_b128 v[140:143], v217 offset:32768
	ds_read_b128 v[150:153], v217 offset:34816
	ds_read_b128 v[154:157], v217 offset:36864
	ds_read_b128 v[158:161], v217 offset:38912
	ds_read_b128 v[162:165], v216 offset:32768
	ds_read_b128 v[166:169], v216 offset:34816
	ds_read_b128 v[170:173], v216 offset:36864
	ds_read_b128 v[174:177], v216 offset:38912
	s_setprio 1
	s_waitcnt lgkmcnt(3)
	v_mfma_f32_16x16x32_bf16 v[126:129], v[140:143], v[162:165], v[126:129]
	v_mfma_f32_16x16x32_bf16 v[122:125], v[150:153], v[162:165], v[122:125]
	v_mfma_f32_16x16x32_bf16 v[118:121], v[154:157], v[162:165], v[118:121]
	v_mfma_f32_16x16x32_bf16 v[114:117], v[158:161], v[162:165], v[114:117]
	s_waitcnt lgkmcnt(2)
	v_mfma_f32_16x16x32_bf16 v[110:113], v[140:143], v[166:169], v[110:113]
	v_mfma_f32_16x16x32_bf16 v[106:109], v[150:153], v[166:169], v[106:109]
	v_mfma_f32_16x16x32_bf16 v[102:105], v[154:157], v[166:169], v[102:105]
	v_mfma_f32_16x16x32_bf16 v[98:101], v[158:161], v[166:169], v[98:101]
	s_waitcnt lgkmcnt(1)
	v_mfma_f32_16x16x32_bf16 v[94:97], v[140:143], v[170:173], v[94:97]
	v_mfma_f32_16x16x32_bf16 v[162:165], v[150:153], v[170:173], v[90:93]
	v_mfma_f32_16x16x32_bf16 v[86:89], v[154:157], v[170:173], v[86:89]
	v_mfma_f32_16x16x32_bf16 v[82:85], v[158:161], v[170:173], v[82:85]
	s_waitcnt lgkmcnt(0)
	v_mfma_f32_16x16x32_bf16 v[78:81], v[140:143], v[174:177], v[78:81]
	v_mfma_f32_16x16x32_bf16 v[74:77], v[150:153], v[174:177], v[74:77]
	v_mfma_f32_16x16x32_bf16 v[70:73], v[154:157], v[174:177], v[70:73]
	v_mfma_f32_16x16x32_bf16 v[66:69], v[158:161], v[174:177], v[66:69]
	s_setprio 0
	ds_read_b128 v[90:93], v216 offset:40960
	ds_read_b128 v[166:169], v216 offset:43008
	ds_read_b128 v[170:173], v216 offset:45056
	ds_read_b128 v[174:177], v216 offset:47104
	s_setprio 1
	s_waitcnt lgkmcnt(3)
	v_mfma_f32_16x16x32_bf16 v[62:65], v[140:143], v[90:93], v[62:65]
	v_mfma_f32_16x16x32_bf16 v[58:61], v[150:153], v[90:93], v[58:61]
	v_mfma_f32_16x16x32_bf16 v[54:57], v[154:157], v[90:93], v[54:57]
	v_mfma_f32_16x16x32_bf16 v[50:53], v[158:161], v[90:93], v[50:53]
	s_waitcnt lgkmcnt(2)
	v_mfma_f32_16x16x32_bf16 v[46:49], v[140:143], v[166:169], v[46:49]
	v_mfma_f32_16x16x32_bf16 v[42:45], v[150:153], v[166:169], v[42:45]
	v_mfma_f32_16x16x32_bf16 v[38:41], v[154:157], v[166:169], v[38:41]
	v_mfma_f32_16x16x32_bf16 v[34:37], v[158:161], v[166:169], v[34:37]
	s_waitcnt lgkmcnt(1)
	v_mfma_f32_16x16x32_bf16 v[30:33], v[140:143], v[170:173], v[30:33]
	v_mfma_f32_16x16x32_bf16 v[26:29], v[150:153], v[170:173], v[26:29]
	v_mfma_f32_16x16x32_bf16 v[22:25], v[154:157], v[170:173], v[22:25]
	v_mfma_f32_16x16x32_bf16 v[18:21], v[158:161], v[170:173], v[18:21]
	s_waitcnt lgkmcnt(0)
	v_mfma_f32_16x16x32_bf16 v[14:17], v[140:143], v[174:177], v[14:17]
	v_mfma_f32_16x16x32_bf16 v[10:13], v[150:153], v[174:177], v[10:13]
	v_mfma_f32_16x16x32_bf16 v[6:9], v[154:157], v[174:177], v[6:9]
	v_mfma_f32_16x16x32_bf16 v[2:5], v[158:161], v[174:177], v[2:5]
	s_setprio 0
	v_mul_f32_e32 v93, 0xbfb8aa3b, v126
	v_exp_f32_e32 v93, v93
	v_mul_f32_e32 v140, 0xbfb8aa3b, v127
	v_exp_f32_e32 v141, v140
	v_or_b32_e32 v90, s22, v148
	v_add_f32_e32 v93, 1.0, v93
	v_rcp_f32_e32 v140, v93
	v_add_f32_e32 v93, 1.0, v141
	v_mul_f32_e32 v141, 0xbfb8aa3b, v128
	v_exp_f32_e32 v142, v141
	v_mul_f32_e32 v141, 0xbfb8aa3b, v129
	v_exp_f32_e32 v143, v141
	v_rcp_f32_e32 v141, v93
	v_add_f32_e32 v93, 1.0, v142
	v_rcp_f32_e32 v142, v93
	v_add_f32_e32 v93, 1.0, v143
	v_rcp_f32_e32 v143, v93
	v_pk_mul_f32 v[126:127], v[126:127], v[140:141]
	v_mul_f32_e32 v93, 0xbfb8aa3b, v118
	v_pk_mul_f32 v[122:123], v[122:123], v[126:127]
	v_pk_mul_f32 v[126:127], v[128:129], v[142:143]
	v_cvt_pk_bf16_f32 v122, v122, v123
	v_exp_f32_e32 v93, v93
	v_mul_f32_e32 v123, 0xbfb8aa3b, v119
	v_pk_mul_f32 v[124:125], v[124:125], v[126:127]
	v_exp_f32_e32 v126, v123
	v_cvt_pk_bf16_f32 v123, v124, v125
	v_add_f32_e32 v93, 1.0, v93
	v_mul_f32_e32 v125, 0xbfb8aa3b, v120
	v_rcp_f32_e32 v124, v93
	v_add_f32_e32 v93, 1.0, v126
	v_exp_f32_e32 v126, v125
	v_mul_f32_e32 v125, 0xbfb8aa3b, v121
	v_exp_f32_e32 v127, v125
	v_rcp_f32_e32 v125, v93
	v_add_f32_e32 v93, 1.0, v126
	v_rcp_f32_e32 v126, v93
	v_add_f32_e32 v93, 1.0, v127
	v_rcp_f32_e32 v127, v93
	v_ashrrev_i32_e32 v90, 1, v90
	v_pk_mul_f32 v[118:119], v[118:119], v[124:125]
	v_ashrrev_i32_e32 v91, 31, v90
	v_pk_mul_f32 v[114:115], v[114:115], v[118:119]
	v_pk_mul_f32 v[118:119], v[120:121], v[126:127]
	v_add_u32_e32 v92, s21, v149
	v_lshl_add_u64 v[90:91], v[90:91], 1, v[136:137]
	v_pk_mul_f32 v[116:117], v[116:117], v[118:119]
	v_mad_i64_i32 v[150:151], s[0:1], v92, s20, v[90:91]
	v_cvt_pk_bf16_f32 v114, v114, v115
	v_cvt_pk_bf16_f32 v115, v116, v117
	v_mul_f32_e32 v93, 0xbfb8aa3b, v110
	s_barrier
	global_store_dwordx2 v[150:151], v[114:115], off offset:32
	v_exp_f32_e32 v93, v93
	v_mul_f32_e32 v114, 0xbfb8aa3b, v111
	v_exp_f32_e32 v115, v114
	v_or_b32_e32 v118, 16, v92
	v_add_f32_e32 v93, 1.0, v93
	v_rcp_f32_e32 v114, v93
	v_add_f32_e32 v93, 1.0, v115
	v_mul_f32_e32 v115, 0xbfb8aa3b, v112
	v_exp_f32_e32 v116, v115
	v_mul_f32_e32 v115, 0xbfb8aa3b, v113
	v_exp_f32_e32 v117, v115
	v_rcp_f32_e32 v115, v93
	v_add_f32_e32 v93, 1.0, v116
	v_rcp_f32_e32 v116, v93
	v_add_f32_e32 v93, 1.0, v117
	v_rcp_f32_e32 v117, v93
	v_pk_mul_f32 v[110:111], v[110:111], v[114:115]
	v_mul_f32_e32 v93, 0xbfb8aa3b, v102
	v_pk_mul_f32 v[106:107], v[106:107], v[110:111]
	v_pk_mul_f32 v[110:111], v[112:113], v[116:117]
	v_cvt_pk_bf16_f32 v106, v106, v107
	v_exp_f32_e32 v93, v93
	v_mul_f32_e32 v107, 0xbfb8aa3b, v103
	v_pk_mul_f32 v[108:109], v[108:109], v[110:111]
	v_exp_f32_e32 v110, v107
	v_cvt_pk_bf16_f32 v107, v108, v109
	v_add_f32_e32 v93, 1.0, v93
	v_mul_f32_e32 v109, 0xbfb8aa3b, v104
	v_rcp_f32_e32 v108, v93
	v_add_f32_e32 v93, 1.0, v110
	v_exp_f32_e32 v110, v109
	v_mul_f32_e32 v109, 0xbfb8aa3b, v105
	v_exp_f32_e32 v111, v109
	v_rcp_f32_e32 v109, v93
	v_add_f32_e32 v93, 1.0, v110
	v_rcp_f32_e32 v110, v93
	v_add_f32_e32 v93, 1.0, v111
	v_rcp_f32_e32 v111, v93
	v_pk_mul_f32 v[102:103], v[102:103], v[108:109]
	v_mad_i64_i32 v[118:119], s[0:1], v118, s20, v[90:91]
	v_pk_mul_f32 v[98:99], v[98:99], v[102:103]
	v_pk_mul_f32 v[102:103], v[104:105], v[110:111]
	v_cvt_pk_bf16_f32 v98, v98, v99
	v_pk_mul_f32 v[100:101], v[100:101], v[102:103]
	v_mul_f32_e32 v93, 0xbfb8aa3b, v94
	v_cvt_pk_bf16_f32 v99, v100, v101
	global_store_dwordx2 v[118:119], v[98:99], off offset:32
	v_exp_f32_e32 v93, v93
	v_mul_f32_e32 v98, 0xbfb8aa3b, v95
	v_exp_f32_e32 v99, v98
	v_or_b32_e32 v102, 32, v92
	v_add_f32_e32 v93, 1.0, v93
	v_rcp_f32_e32 v98, v93
	v_add_f32_e32 v93, 1.0, v99
	v_mul_f32_e32 v99, 0xbfb8aa3b, v96
	v_exp_f32_e32 v100, v99
	v_mul_f32_e32 v99, 0xbfb8aa3b, v97
	v_exp_f32_e32 v101, v99
	v_rcp_f32_e32 v99, v93
	v_add_f32_e32 v93, 1.0, v100
	v_rcp_f32_e32 v100, v93
	v_add_f32_e32 v93, 1.0, v101
	v_rcp_f32_e32 v101, v93
	v_pk_mul_f32 v[94:95], v[94:95], v[98:99]
	v_mul_f32_e32 v93, 0xbfb8aa3b, v86
	v_pk_mul_f32 v[94:95], v[162:163], v[94:95]
	v_exp_f32_e32 v93, v93
	v_cvt_pk_bf16_f32 v94, v94, v95
	v_mul_f32_e32 v95, 0xbfb8aa3b, v87
	v_exp_f32_e32 v98, v95
	v_pk_mul_f32 v[96:97], v[96:97], v[100:101]
	v_add_f32_e32 v93, 1.0, v93
	v_pk_mul_f32 v[96:97], v[164:165], v[96:97]
	v_mad_i64_i32 v[102:103], s[0:1], v102, s20, v[90:91]
	v_cvt_pk_bf16_f32 v95, v96, v97
	v_mul_f32_e32 v97, 0xbfb8aa3b, v88
	v_rcp_f32_e32 v96, v93
	v_add_f32_e32 v93, 1.0, v98
	v_exp_f32_e32 v98, v97
	v_mul_f32_e32 v97, 0xbfb8aa3b, v89
	v_exp_f32_e32 v99, v97
	v_rcp_f32_e32 v97, v93
	v_add_f32_e32 v93, 1.0, v98
	v_rcp_f32_e32 v98, v93
	v_add_f32_e32 v93, 1.0, v99
	v_rcp_f32_e32 v99, v93
	v_pk_mul_f32 v[86:87], v[86:87], v[96:97]
	s_add_i32 s3, s3, s7
	v_pk_mul_f32 v[82:83], v[82:83], v[86:87]
	v_pk_mul_f32 v[86:87], v[88:89], v[98:99]
	v_cvt_pk_bf16_f32 v82, v82, v83
	v_pk_mul_f32 v[84:85], v[84:85], v[86:87]
	v_or_b32_e32 v86, 48, v92
	v_cvt_pk_bf16_f32 v83, v84, v85
	global_store_dwordx2 v[102:103], v[82:83], off offset:32
	v_mul_f32_e32 v82, 0xbfb8aa3b, v78
	v_mul_f32_e32 v83, 0xbfb8aa3b, v79
	v_exp_f32_e32 v82, v82
	v_exp_f32_e32 v83, v83
	v_mul_f32_e32 v84, 0xbfb8aa3b, v80
	v_mul_f32_e32 v85, 0xbfb8aa3b, v81
	v_exp_f32_e32 v84, v84
	v_exp_f32_e32 v85, v85
	v_add_f32_e32 v82, 1.0, v82
	v_add_f32_e32 v83, 1.0, v83
	v_rcp_f32_e32 v82, v82
	v_rcp_f32_e32 v83, v83
	v_add_f32_e32 v84, 1.0, v84
	v_add_f32_e32 v85, 1.0, v85
	v_rcp_f32_e32 v84, v84
	v_rcp_f32_e32 v85, v85
	v_pk_mul_f32 v[78:79], v[78:79], v[82:83]
	v_mad_i64_i32 v[86:87], s[0:1], v86, s20, v[90:91]
	v_pk_mul_f32 v[74:75], v[74:75], v[78:79]
	v_pk_mul_f32 v[78:79], v[80:81], v[84:85]
	v_cvt_pk_bf16_f32 v74, v74, v75
	v_mul_f32_e32 v75, 0xbfb8aa3b, v70
	v_pk_mul_f32 v[76:77], v[76:77], v[78:79]
	v_exp_f32_e32 v78, v75
	v_mul_f32_e32 v75, 0xbfb8aa3b, v71
	v_exp_f32_e32 v79, v75
	v_cvt_pk_bf16_f32 v75, v76, v77
	v_add_f32_e32 v76, 1.0, v78
	v_mul_f32_e32 v78, 0xbfb8aa3b, v72
	v_add_f32_e32 v77, 1.0, v79
	v_mul_f32_e32 v79, 0xbfb8aa3b, v73
	v_exp_f32_e32 v78, v78
	v_exp_f32_e32 v79, v79
	v_rcp_f32_e32 v76, v76
	v_rcp_f32_e32 v77, v77
	v_add_f32_e32 v78, 1.0, v78
	v_add_f32_e32 v79, 1.0, v79
	v_rcp_f32_e32 v78, v78
	v_rcp_f32_e32 v79, v79
	v_pk_mul_f32 v[70:71], v[70:71], v[76:77]
	s_cmpk_gt_i32 s3, 0x2bf
	v_pk_mul_f32 v[66:67], v[66:67], v[70:71]
	v_pk_mul_f32 v[70:71], v[72:73], v[78:79]
	v_cvt_pk_bf16_f32 v66, v66, v67
	v_pk_mul_f32 v[68:69], v[68:69], v[70:71]
	v_or_b32_e32 v70, 64, v92
	v_cvt_pk_bf16_f32 v67, v68, v69
	global_store_dwordx2 v[86:87], v[66:67], off offset:32
	v_mul_f32_e32 v66, 0xbfb8aa3b, v62
	v_mul_f32_e32 v67, 0xbfb8aa3b, v63
	v_exp_f32_e32 v66, v66
	v_exp_f32_e32 v67, v67
	v_mul_f32_e32 v68, 0xbfb8aa3b, v64
	v_mul_f32_e32 v69, 0xbfb8aa3b, v65
	v_exp_f32_e32 v68, v68
	v_exp_f32_e32 v69, v69
	v_add_f32_e32 v66, 1.0, v66
	v_add_f32_e32 v67, 1.0, v67
	v_rcp_f32_e32 v66, v66
	v_rcp_f32_e32 v67, v67
	v_add_f32_e32 v68, 1.0, v68
	v_add_f32_e32 v69, 1.0, v69
	v_rcp_f32_e32 v68, v68
	v_rcp_f32_e32 v69, v69
	v_pk_mul_f32 v[62:63], v[62:63], v[66:67]
	v_mad_i64_i32 v[70:71], s[0:1], v70, s20, v[90:91]
	v_pk_mul_f32 v[58:59], v[58:59], v[62:63]
	v_pk_mul_f32 v[62:63], v[64:65], v[68:69]
	v_cvt_pk_bf16_f32 v58, v58, v59
	v_mul_f32_e32 v59, 0xbfb8aa3b, v54
	v_pk_mul_f32 v[60:61], v[60:61], v[62:63]
	v_exp_f32_e32 v62, v59
	v_mul_f32_e32 v59, 0xbfb8aa3b, v55
	v_exp_f32_e32 v63, v59
	v_cvt_pk_bf16_f32 v59, v60, v61
	v_add_f32_e32 v60, 1.0, v62
	v_mul_f32_e32 v62, 0xbfb8aa3b, v56
	v_add_f32_e32 v61, 1.0, v63
	v_mul_f32_e32 v63, 0xbfb8aa3b, v57
	v_exp_f32_e32 v62, v62
	v_exp_f32_e32 v63, v63
	v_rcp_f32_e32 v60, v60
	v_rcp_f32_e32 v61, v61
	v_add_f32_e32 v62, 1.0, v62
	v_add_f32_e32 v63, 1.0, v63
	v_rcp_f32_e32 v62, v62
	v_rcp_f32_e32 v63, v63
	v_pk_mul_f32 v[54:55], v[54:55], v[60:61]
	v_add_u32_e32 v130, s8, v130
	v_pk_mul_f32 v[50:51], v[50:51], v[54:55]
	v_pk_mul_f32 v[54:55], v[56:57], v[62:63]
	v_cvt_pk_bf16_f32 v50, v50, v51
	v_pk_mul_f32 v[52:53], v[52:53], v[54:55]
	v_or_b32_e32 v54, 0x50, v92
	v_cvt_pk_bf16_f32 v51, v52, v53
	global_store_dwordx2 v[70:71], v[50:51], off offset:32
	v_mul_f32_e32 v50, 0xbfb8aa3b, v46
	v_mul_f32_e32 v51, 0xbfb8aa3b, v47
	v_exp_f32_e32 v50, v50
	v_exp_f32_e32 v51, v51
	v_mul_f32_e32 v52, 0xbfb8aa3b, v48
	v_mul_f32_e32 v53, 0xbfb8aa3b, v49
	v_exp_f32_e32 v52, v52
	v_exp_f32_e32 v53, v53
	v_add_f32_e32 v50, 1.0, v50
	v_add_f32_e32 v51, 1.0, v51
	v_rcp_f32_e32 v50, v50
	v_rcp_f32_e32 v51, v51
	v_add_f32_e32 v52, 1.0, v52
	v_add_f32_e32 v53, 1.0, v53
	v_rcp_f32_e32 v52, v52
	v_rcp_f32_e32 v53, v53
	v_pk_mul_f32 v[46:47], v[46:47], v[50:51]
	v_mad_i64_i32 v[54:55], s[0:1], v54, s20, v[90:91]
	v_pk_mul_f32 v[42:43], v[42:43], v[46:47]
	v_pk_mul_f32 v[46:47], v[48:49], v[52:53]
	v_cvt_pk_bf16_f32 v42, v42, v43
	v_mul_f32_e32 v43, 0xbfb8aa3b, v38
	v_pk_mul_f32 v[44:45], v[44:45], v[46:47]
	v_exp_f32_e32 v46, v43
	v_mul_f32_e32 v43, 0xbfb8aa3b, v39
	v_exp_f32_e32 v47, v43
	v_cvt_pk_bf16_f32 v43, v44, v45
	v_add_f32_e32 v44, 1.0, v46
	v_mul_f32_e32 v46, 0xbfb8aa3b, v40
	v_add_f32_e32 v45, 1.0, v47
	v_mul_f32_e32 v47, 0xbfb8aa3b, v41
	v_exp_f32_e32 v46, v46
	v_exp_f32_e32 v47, v47
	v_rcp_f32_e32 v44, v44
	v_rcp_f32_e32 v45, v45
	v_add_f32_e32 v46, 1.0, v46
	v_add_f32_e32 v47, 1.0, v47
	v_rcp_f32_e32 v46, v46
	v_rcp_f32_e32 v47, v47
	v_pk_mul_f32 v[38:39], v[38:39], v[44:45]
	global_store_dwordx2 v[150:151], v[122:123], off
	v_pk_mul_f32 v[34:35], v[34:35], v[38:39]
	v_pk_mul_f32 v[38:39], v[40:41], v[46:47]
	v_cvt_pk_bf16_f32 v34, v34, v35
	v_pk_mul_f32 v[36:37], v[36:37], v[38:39]
	v_or_b32_e32 v38, 0x60, v92
	v_cvt_pk_bf16_f32 v35, v36, v37
	global_store_dwordx2 v[54:55], v[34:35], off offset:32
	v_mul_f32_e32 v34, 0xbfb8aa3b, v30
	v_mul_f32_e32 v35, 0xbfb8aa3b, v31
	v_exp_f32_e32 v34, v34
	v_exp_f32_e32 v35, v35
	v_mul_f32_e32 v36, 0xbfb8aa3b, v32
	v_mul_f32_e32 v37, 0xbfb8aa3b, v33
	v_exp_f32_e32 v36, v36
	v_exp_f32_e32 v37, v37
	v_add_f32_e32 v34, 1.0, v34
	v_add_f32_e32 v35, 1.0, v35
	v_rcp_f32_e32 v34, v34
	v_rcp_f32_e32 v35, v35
	v_add_f32_e32 v36, 1.0, v36
	v_add_f32_e32 v37, 1.0, v37
	v_rcp_f32_e32 v36, v36
	v_rcp_f32_e32 v37, v37
	v_pk_mul_f32 v[30:31], v[30:31], v[34:35]
	v_mad_i64_i32 v[38:39], s[0:1], v38, s20, v[90:91]
	v_pk_mul_f32 v[26:27], v[26:27], v[30:31]
	v_pk_mul_f32 v[30:31], v[32:33], v[36:37]
	v_cvt_pk_bf16_f32 v26, v26, v27
	v_mul_f32_e32 v27, 0xbfb8aa3b, v22
	v_pk_mul_f32 v[28:29], v[28:29], v[30:31]
	v_exp_f32_e32 v30, v27
	v_mul_f32_e32 v27, 0xbfb8aa3b, v23
	v_exp_f32_e32 v31, v27
	v_cvt_pk_bf16_f32 v27, v28, v29
	v_add_f32_e32 v28, 1.0, v30
	v_mul_f32_e32 v30, 0xbfb8aa3b, v24
	v_add_f32_e32 v29, 1.0, v31
	v_mul_f32_e32 v31, 0xbfb8aa3b, v25
	v_exp_f32_e32 v30, v30
	v_exp_f32_e32 v31, v31
	v_rcp_f32_e32 v28, v28
	v_rcp_f32_e32 v29, v29
	v_add_f32_e32 v30, 1.0, v30
	v_add_f32_e32 v31, 1.0, v31
	v_rcp_f32_e32 v30, v30
	v_rcp_f32_e32 v31, v31
	v_pk_mul_f32 v[22:23], v[22:23], v[28:29]
	global_store_dwordx2 v[118:119], v[106:107], off
	v_pk_mul_f32 v[18:19], v[18:19], v[22:23]
	v_pk_mul_f32 v[22:23], v[24:25], v[30:31]
	v_cvt_pk_bf16_f32 v18, v18, v19
	v_pk_mul_f32 v[20:21], v[20:21], v[22:23]
	v_or_b32_e32 v22, 0x70, v92
	v_cvt_pk_bf16_f32 v19, v20, v21
	global_store_dwordx2 v[38:39], v[18:19], off offset:32
	v_mul_f32_e32 v18, 0xbfb8aa3b, v14
	v_mul_f32_e32 v19, 0xbfb8aa3b, v15
	v_exp_f32_e32 v18, v18
	v_exp_f32_e32 v19, v19
	v_mul_f32_e32 v20, 0xbfb8aa3b, v16
	v_mul_f32_e32 v21, 0xbfb8aa3b, v17
	v_exp_f32_e32 v20, v20
	v_exp_f32_e32 v21, v21
	v_add_f32_e32 v18, 1.0, v18
	v_add_f32_e32 v19, 1.0, v19
	v_rcp_f32_e32 v18, v18
	v_rcp_f32_e32 v19, v19
	v_add_f32_e32 v20, 1.0, v20
	v_add_f32_e32 v21, 1.0, v21
	v_rcp_f32_e32 v20, v20
	v_rcp_f32_e32 v21, v21
	v_pk_mul_f32 v[14:15], v[14:15], v[18:19]
	v_mad_i64_i32 v[22:23], s[0:1], v22, s20, v[90:91]
	v_pk_mul_f32 v[10:11], v[10:11], v[14:15]
	v_pk_mul_f32 v[14:15], v[16:17], v[20:21]
	v_cvt_pk_bf16_f32 v10, v10, v11
	v_mul_f32_e32 v11, 0xbfb8aa3b, v6
	v_pk_mul_f32 v[12:13], v[12:13], v[14:15]
	v_exp_f32_e32 v14, v11
	v_mul_f32_e32 v11, 0xbfb8aa3b, v7
	v_exp_f32_e32 v15, v11
	v_cvt_pk_bf16_f32 v11, v12, v13
	v_add_f32_e32 v12, 1.0, v14
	v_mul_f32_e32 v14, 0xbfb8aa3b, v8
	v_add_f32_e32 v13, 1.0, v15
	v_mul_f32_e32 v15, 0xbfb8aa3b, v9
	v_exp_f32_e32 v14, v14
	v_exp_f32_e32 v15, v15
	v_rcp_f32_e32 v12, v12
	v_rcp_f32_e32 v13, v13
	v_add_f32_e32 v14, 1.0, v14
	v_add_f32_e32 v15, 1.0, v15
	v_rcp_f32_e32 v14, v14
	v_rcp_f32_e32 v15, v15
	v_pk_mul_f32 v[6:7], v[6:7], v[12:13]
	global_store_dwordx2 v[102:103], v[94:95], off
	v_pk_mul_f32 v[2:3], v[2:3], v[6:7]
	v_pk_mul_f32 v[6:7], v[8:9], v[14:15]
	v_cvt_pk_bf16_f32 v2, v2, v3
	v_pk_mul_f32 v[4:5], v[4:5], v[6:7]
	global_store_dwordx2 v[86:87], v[74:75], off
	v_cvt_pk_bf16_f32 v3, v4, v5
	global_store_dwordx2 v[70:71], v[58:59], off
	global_store_dwordx2 v[54:55], v[42:43], off
	global_store_dwordx2 v[38:39], v[26:27], off
	global_store_dwordx2 v[22:23], v[10:11], off
	global_store_dwordx2 v[22:23], v[2:3], off offset:32
	s_cbranch_scc0 .LBB0_749

.LBB0_773:
	s_lshl_b32 s37, s29, 8
	v_or_b32_e32 v27, s37, v1
	v_mad_i64_i32 v[2:3], s[8:9], v27, s12, v[130:131]
	v_add_co_u32_e32 v6, vcc, 0x58000, v2
	s_lshl_b32 s36, s28, 8
	s_nop 0
	v_addc_co_u32_e32 v7, vcc, 0, v3, vcc
	global_load_dwordx4 v[28:31], v[2:3], off
	global_load_dwordx4 v[32:35], v[6:7], off
	v_add_co_u32_e32 v6, vcc, 0xb0000, v2
	v_or_b32_e32 v60, s36, v1
	s_nop 0
	v_addc_co_u32_e32 v7, vcc, 0, v3, vcc
	v_add_co_u32_e32 v2, vcc, 0x108000, v2
	v_mad_i64_i32 v[4:5], s[8:9], v60, s12, v[132:133]
	s_nop 0
	v_addc_co_u32_e32 v3, vcc, 0, v3, vcc
	global_load_dwordx4 v[36:39], v[6:7], off
	global_load_dwordx4 v[40:43], v[2:3], off
	v_add_co_u32_e32 v2, vcc, s13, v4
	s_waitcnt vmcnt(63) expcnt(7) lgkmcnt(15)
	s_nop 0
	v_addc_co_u32_e32 v3, vcc, 0, v5, vcc
	s_barrier
	global_load_dwordx4 v[44:47], v[4:5], off
	global_load_dwordx4 v[48:51], v[2:3], off
	v_add_co_u32_e32 v2, vcc, s14, v4
	s_mov_b32 s38, 0
	s_nop 0
	v_addc_co_u32_e32 v3, vcc, 0, v5, vcc
	v_add_co_u32_e32 v4, vcc, s15, v4
	s_mov_b64 s[8:9], 0
	s_nop 0
	v_addc_co_u32_e32 v5, vcc, 0, v5, vcc
	global_load_dwordx4 v[52:55], v[2:3], off
	global_load_dwordx4 v[56:59], v[4:5], off
	v_mov_b32_e32 v2, 0
	v_mov_b32_e32 v3, v2
	v_mov_b32_e32 v4, v2
	v_mov_b32_e32 v5, v2
	v_mov_b32_e32 v6, v2
	v_mov_b32_e32 v7, v2
	v_mov_b32_e32 v8, v2
	v_mov_b32_e32 v9, v2
	v_mov_b32_e32 v10, v2
	v_mov_b32_e32 v11, v2
	v_mov_b32_e32 v12, v2
	v_mov_b32_e32 v13, v2
	v_mov_b32_e32 v14, v2
	v_mov_b32_e32 v15, v2
	v_mov_b32_e32 v16, v2
	v_mov_b32_e32 v17, v2
	v_mov_b32_e32 v18, v2
	v_mov_b32_e32 v19, v2
	v_mov_b32_e32 v20, v2
	v_mov_b32_e32 v21, v2
	v_mov_b32_e32 v22, v2
	v_mov_b32_e32 v23, v2
	v_mov_b32_e32 v24, v2
	v_mov_b32_e32 v25, v2
	v_mov_b32_e32 v26, v2
	v_mad_i64_i32 v[136:137], s[40:41], v27, s12, v[134:135]
	v_mad_i64_i32 v[138:139], s[40:41], v60, s12, v[134:135]
	v_mov_b32_e32 v27, v2
	v_mov_b32_e32 v60, v2
	v_mov_b32_e32 v61, v2
	v_mov_b32_e32 v62, v2
	v_mov_b32_e32 v63, v2
	v_mov_b32_e32 v64, v2
	v_mov_b32_e32 v65, v2
	v_mov_b32_e32 v66, v2
	v_mov_b32_e32 v67, v2
	v_mov_b32_e32 v68, v2
	v_mov_b32_e32 v69, v2
	v_mov_b32_e32 v70, v2
	v_mov_b32_e32 v71, v2
	v_mov_b32_e32 v72, v2
	v_mov_b32_e32 v73, v2
	v_mov_b32_e32 v74, v2
	v_mov_b32_e32 v75, v2
	v_mov_b32_e32 v76, v2
	v_mov_b32_e32 v77, v2
	v_mov_b32_e32 v78, v2
	v_mov_b32_e32 v79, v2
	v_mov_b32_e32 v80, v2
	v_mov_b32_e32 v81, v2
	v_mov_b32_e32 v82, v2
	s_waitcnt vmcnt(7)
	ds_write_b128 v146, v[28:31]
	s_waitcnt vmcnt(6)
	ds_write_b128 v146, v[32:35] offset:8192
	s_waitcnt vmcnt(5)
	ds_write_b128 v146, v[36:39] offset:16384
	s_waitcnt vmcnt(4)
	ds_write_b128 v146, v[40:43] offset:24576
	s_waitcnt vmcnt(3)
	ds_write_b128 v147, v[44:47]
	s_waitcnt vmcnt(2)
	ds_write_b128 v147, v[48:51] offset:8192
	s_waitcnt vmcnt(1)
	ds_write_b128 v147, v[52:55] offset:16384
	s_waitcnt vmcnt(0)
	ds_write_b128 v147, v[56:59] offset:24576
	v_mov_b32_e32 v28, v2
	v_mov_b32_e32 v29, v2
	v_mov_b32_e32 v30, v2
	v_mov_b32_e32 v31, v2
	v_mov_b32_e32 v32, v2
	v_mov_b32_e32 v33, v2
	v_mov_b32_e32 v34, v2
	v_mov_b32_e32 v35, v2
	v_mov_b32_e32 v36, v2
	v_mov_b32_e32 v37, v2
	v_mov_b32_e32 v38, v2
	v_mov_b32_e32 v39, v2
	v_mov_b32_e32 v40, v2
	v_mov_b32_e32 v41, v2
	v_mov_b32_e32 v42, v2
	v_mov_b32_e32 v43, v2
	v_mov_b32_e32 v44, v2
	v_mov_b32_e32 v45, v2
	v_mov_b32_e32 v46, v2
	v_mov_b32_e32 v47, v2
	v_mov_b32_e32 v48, v2
	v_mov_b32_e32 v49, v2
	v_mov_b32_e32 v50, v2
	v_mov_b32_e32 v51, v2
	v_mov_b32_e32 v52, v2
	v_mov_b32_e32 v53, v2
	v_mov_b32_e32 v54, v2
	v_mov_b32_e32 v55, v2
	v_mov_b32_e32 v56, v2
	v_mov_b32_e32 v57, v2
	v_mov_b32_e32 v58, v2
	v_mov_b32_e32 v59, v2
	v_mov_b32_e32 v83, v2
	v_mov_b32_e32 v84, v2
	v_mov_b32_e32 v85, v2
	v_mov_b32_e32 v86, v2
	v_mov_b32_e32 v87, v2
	v_mov_b32_e32 v88, v2
	v_mov_b32_e32 v89, v2
	v_mov_b32_e32 v90, v2
	v_mov_b32_e32 v91, v2
	v_mov_b32_e32 v92, v2
	v_mov_b32_e32 v93, v2
	v_mov_b32_e32 v94, v2
	v_mov_b32_e32 v95, v2
	v_mov_b32_e32 v96, v2
	v_mov_b32_e32 v97, v2
	v_mov_b32_e32 v98, v2
	v_mov_b32_e32 v99, v2
	v_mov_b32_e32 v100, v2
	v_mov_b32_e32 v101, v2
	v_mov_b32_e32 v102, v2
	v_mov_b32_e32 v103, v2
	v_mov_b32_e32 v104, v2
	v_mov_b32_e32 v105, v2
	v_mov_b32_e32 v106, v2
	v_mov_b32_e32 v107, v2
	v_mov_b32_e32 v108, v2
	v_mov_b32_e32 v109, v2
	v_mov_b32_e32 v110, v2
	v_mov_b32_e32 v111, v2
	v_mov_b32_e32 v112, v2
	v_mov_b32_e32 v113, v2
	v_mov_b32_e32 v114, v2
	v_mov_b32_e32 v115, v2
	v_mov_b32_e32 v116, v2
	v_mov_b32_e32 v117, v2
	v_mov_b32_e32 v118, v2
	v_mov_b32_e32 v119, v2
	v_mov_b32_e32 v120, v2
	v_mov_b32_e32 v121, v2
	v_mov_b32_e32 v122, v2
	v_mov_b32_e32 v123, v2
	v_mov_b32_e32 v124, v2
	v_mov_b32_e32 v125, v2
	v_mov_b32_e32 v126, v2
	v_mov_b32_e32 v127, v2
	v_mov_b32_e32 v128, v2
	v_mov_b32_e32 v129, v2
	s_waitcnt lgkmcnt(0)
	s_barrier
	v_readfirstlane_b32 s98, v136
	v_readfirstlane_b32 s99, v137
	v_subrev_u32_e32 v248, s98, v136
	s_add_u32 s98, s98, s8
	s_addc_u32 s99, s99, s9
	v_readfirstlane_b32 s100, v138
	v_readfirstlane_b32 s101, v139
	v_subrev_u32_e32 v250, s100, v138
	s_add_u32 s100, s100, s8
	s_addc_u32 s101, s101, s9
	v_add_u32_e32 v142, s16, v248
	v_add_u32_e32 v144, s17, v248
	v_add_u32_e32 v156, s18, v248
	v_add_u32_e32 v160, s19, v248
	global_load_dwordx4 v[140:143], v142, s[98:99] offset:128
	global_load_dwordx4 v[152:155], v144, s[98:99] offset:128
	global_load_dwordx4 v[156:159], v156, s[98:99] offset:128
	global_load_dwordx4 v[160:163], v160, s[98:99] offset:128
	v_add_u32_e32 v164, s20, v250
	v_add_u32_e32 v168, s21, v250
	v_add_u32_e32 v172, s22, v250
	v_add_u32_e32 v144, s23, v250
	global_load_dwordx4 v[164:167], v164, s[100:101] offset:128
	global_load_dwordx4 v[168:171], v168, s[100:101] offset:128
	global_load_dwordx4 v[172:175], v172, s[100:101] offset:128
	global_load_dwordx4 v[176:179], v144, s[100:101] offset:128
	v_mov_b32_e32 v223, v148
	v_mov_b32_e32 v249, v149
	v_xor_b32_e32 v251, 0x8000, v146
	v_xor_b32_e32 v252, 0x8000, v147
	ds_read_b128 v[180:183], v223
	ds_read_b128 v[184:187], v223 offset:2048
	ds_read_b128 v[188:191], v223 offset:4096
	ds_read_b128 v[192:195], v223 offset:6144
	ds_read_b128 v[212:215], v249
	ds_read_b128 v[218:221], v249 offset:2048
	ds_read_b128 v[224:227], v249 offset:4096
	ds_read_b128 v[228:231], v249 offset:6144
.Lg2_p15_loop:
	ds_read_b128 v[196:199], v223 offset:8192
	ds_read_b128 v[200:203], v223 offset:10240
	ds_read_b128 v[204:207], v223 offset:12288
	ds_read_b128 v[208:211], v223 offset:14336
	s_waitcnt lgkmcnt(4)
	v_mfma_f32_16x16x32_bf16 v[126:129], v[212:215], v[180:183], v[126:129]
	v_mfma_f32_16x16x32_bf16 v[122:125], v[218:221], v[180:183], v[122:125]
	v_mfma_f32_16x16x32_bf16 v[118:121], v[224:227], v[180:183], v[118:121]
	v_mfma_f32_16x16x32_bf16 v[114:117], v[228:231], v[180:183], v[114:117]
	v_mfma_f32_16x16x32_bf16 v[110:113], v[212:215], v[184:187], v[110:113]
	v_mfma_f32_16x16x32_bf16 v[106:109], v[218:221], v[184:187], v[106:109]
	v_mfma_f32_16x16x32_bf16 v[102:105], v[224:227], v[184:187], v[102:105]
	v_mfma_f32_16x16x32_bf16 v[98:101], v[228:231], v[184:187], v[98:101]
	v_mfma_f32_16x16x32_bf16 v[94:97], v[212:215], v[188:191], v[94:97]
	v_mfma_f32_16x16x32_bf16 v[90:93], v[218:221], v[188:191], v[90:93]
	v_mfma_f32_16x16x32_bf16 v[86:89], v[224:227], v[188:191], v[86:89]
	v_mfma_f32_16x16x32_bf16 v[82:85], v[228:231], v[188:191], v[82:85]
	v_mfma_f32_16x16x32_bf16 v[78:81], v[212:215], v[192:195], v[78:81]
	v_mfma_f32_16x16x32_bf16 v[74:77], v[218:221], v[192:195], v[74:77]
	v_mfma_f32_16x16x32_bf16 v[70:73], v[224:227], v[192:195], v[70:73]
	v_mfma_f32_16x16x32_bf16 v[66:69], v[228:231], v[192:195], v[66:69]
	ds_read_b128 v[180:183], v216
	ds_read_b128 v[184:187], v216 offset:2048
	ds_read_b128 v[188:191], v216 offset:4096
	ds_read_b128 v[192:195], v216 offset:6144
	ds_read_b128 v[232:235], v217
	ds_read_b128 v[236:239], v217 offset:2048
	ds_read_b128 v[240:243], v217 offset:4096
	ds_read_b128 v[244:247], v217 offset:6144
	s_waitcnt lgkmcnt(8)
	v_mfma_f32_16x16x32_bf16 v[62:65], v[212:215], v[196:199], v[62:65]
	v_mfma_f32_16x16x32_bf16 v[58:61], v[218:221], v[196:199], v[58:61]
	v_mfma_f32_16x16x32_bf16 v[54:57], v[224:227], v[196:199], v[54:57]
	v_mfma_f32_16x16x32_bf16 v[50:53], v[228:231], v[196:199], v[50:53]
	v_mfma_f32_16x16x32_bf16 v[46:49], v[212:215], v[200:203], v[46:49]
	v_mfma_f32_16x16x32_bf16 v[42:45], v[218:221], v[200:203], v[42:45]
	v_mfma_f32_16x16x32_bf16 v[38:41], v[224:227], v[200:203], v[38:41]
	v_mfma_f32_16x16x32_bf16 v[34:37], v[228:231], v[200:203], v[34:37]
	v_mfma_f32_16x16x32_bf16 v[30:33], v[212:215], v[204:207], v[30:33]
	v_mfma_f32_16x16x32_bf16 v[26:29], v[218:221], v[204:207], v[26:29]
	v_mfma_f32_16x16x32_bf16 v[22:25], v[224:227], v[204:207], v[22:25]
	v_mfma_f32_16x16x32_bf16 v[18:21], v[228:231], v[204:207], v[18:21]
	v_mfma_f32_16x16x32_bf16 v[14:17], v[212:215], v[208:211], v[14:17]
	v_mfma_f32_16x16x32_bf16 v[10:13], v[218:221], v[208:211], v[10:13]
	v_mfma_f32_16x16x32_bf16 v[6:9], v[224:227], v[208:211], v[6:9]
	v_mfma_f32_16x16x32_bf16 v[2:5], v[228:231], v[208:211], v[2:5]
	ds_read_b128 v[196:199], v216 offset:8192
	ds_read_b128 v[200:203], v216 offset:10240
	ds_read_b128 v[204:207], v216 offset:12288
	ds_read_b128 v[208:211], v216 offset:14336
	s_waitcnt lgkmcnt(4)
	v_mfma_f32_16x16x32_bf16 v[126:129], v[232:235], v[180:183], v[126:129]
	v_mfma_f32_16x16x32_bf16 v[122:125], v[236:239], v[180:183], v[122:125]
	s_waitcnt vmcnt(7)
	ds_write_b128 v251, v[140:143]
	v_mfma_f32_16x16x32_bf16 v[118:121], v[240:243], v[180:183], v[118:121]
	v_mfma_f32_16x16x32_bf16 v[114:117], v[244:247], v[180:183], v[114:117]
	s_waitcnt vmcnt(6)
	ds_write_b128 v251, v[152:155] offset:8192
	v_mfma_f32_16x16x32_bf16 v[110:113], v[232:235], v[184:187], v[110:113]
	v_mfma_f32_16x16x32_bf16 v[106:109], v[236:239], v[184:187], v[106:109]
	s_waitcnt vmcnt(5)
	ds_write_b128 v251, v[156:159] offset:16384
	v_mfma_f32_16x16x32_bf16 v[102:105], v[240:243], v[184:187], v[102:105]
	v_mfma_f32_16x16x32_bf16 v[98:101], v[244:247], v[184:187], v[98:101]
	s_waitcnt vmcnt(4)
	ds_write_b128 v251, v[160:163] offset:24576
	v_mfma_f32_16x16x32_bf16 v[94:97], v[232:235], v[188:191], v[94:97]
	v_mfma_f32_16x16x32_bf16 v[90:93], v[236:239], v[188:191], v[90:93]
	s_waitcnt vmcnt(3)
	ds_write_b128 v252, v[164:167]
	v_mfma_f32_16x16x32_bf16 v[86:89], v[240:243], v[188:191], v[86:89]
	v_mfma_f32_16x16x32_bf16 v[82:85], v[244:247], v[188:191], v[82:85]
	s_waitcnt vmcnt(2)
	ds_write_b128 v252, v[168:171] offset:8192
	v_mfma_f32_16x16x32_bf16 v[78:81], v[232:235], v[192:195], v[78:81]
	v_mfma_f32_16x16x32_bf16 v[74:77], v[236:239], v[192:195], v[74:77]
	s_waitcnt vmcnt(1)
	ds_write_b128 v252, v[172:175] offset:16384
	v_mfma_f32_16x16x32_bf16 v[70:73], v[240:243], v[192:195], v[70:73]
	v_mfma_f32_16x16x32_bf16 v[66:69], v[244:247], v[192:195], v[66:69]
	s_waitcnt vmcnt(0)
	ds_write_b128 v252, v[176:179] offset:24576
	s_waitcnt lgkmcnt(0)
	s_barrier
	s_add_u32 s8, s8, 0x80
	s_addc_u32 s9, s9, 0
	s_add_u32 s98, s98, 0x80
	s_addc_u32 s99, s99, 0
	s_add_u32 s100, s100, 0x80
	s_addc_u32 s101, s101, 0
	s_cmpk_eq_i32 s8, 0x1580
	s_cbranch_scc1 .Lg2_p15_tail
	v_xor_b32_e32 v223, 0x8000, v223
	v_xor_b32_e32 v249, 0x8000, v249
	v_xor_b32_e32 v216, 0x8000, v216
	v_xor_b32_e32 v217, 0x8000, v217
	v_xor_b32_e32 v251, 0x8000, v251
	v_xor_b32_e32 v252, 0x8000, v252
	ds_read_b128 v[180:183], v223
	ds_read_b128 v[184:187], v223 offset:2048
	ds_read_b128 v[188:191], v223 offset:4096
	ds_read_b128 v[192:195], v223 offset:6144
	ds_read_b128 v[212:215], v249
	ds_read_b128 v[218:221], v249 offset:2048
	ds_read_b128 v[224:227], v249 offset:4096
	ds_read_b128 v[228:231], v249 offset:6144
	v_mfma_f32_16x16x32_bf16 v[62:65], v[232:235], v[196:199], v[62:65]
	v_add_u32_e32 v142, s16, v248
	v_mfma_f32_16x16x32_bf16 v[58:61], v[236:239], v[196:199], v[58:61]
	v_add_u32_e32 v144, s17, v248
	v_mfma_f32_16x16x32_bf16 v[54:57], v[240:243], v[196:199], v[54:57]
	v_add_u32_e32 v156, s18, v248
	v_mfma_f32_16x16x32_bf16 v[50:53], v[244:247], v[196:199], v[50:53]
	v_add_u32_e32 v160, s19, v248
	v_mfma_f32_16x16x32_bf16 v[46:49], v[232:235], v[200:203], v[46:49]
	global_load_dwordx4 v[140:143], v142, s[98:99] offset:128
	v_mfma_f32_16x16x32_bf16 v[42:45], v[236:239], v[200:203], v[42:45]
	global_load_dwordx4 v[152:155], v144, s[98:99] offset:128
	v_mfma_f32_16x16x32_bf16 v[38:41], v[240:243], v[200:203], v[38:41]
	global_load_dwordx4 v[156:159], v156, s[98:99] offset:128
	v_mfma_f32_16x16x32_bf16 v[34:37], v[244:247], v[200:203], v[34:37]
	global_load_dwordx4 v[160:163], v160, s[98:99] offset:128
	v_mfma_f32_16x16x32_bf16 v[30:33], v[232:235], v[204:207], v[30:33]
	v_add_u32_e32 v164, s20, v250
	v_mfma_f32_16x16x32_bf16 v[26:29], v[236:239], v[204:207], v[26:29]
	v_add_u32_e32 v168, s21, v250
	v_mfma_f32_16x16x32_bf16 v[22:25], v[240:243], v[204:207], v[22:25]
	v_add_u32_e32 v172, s22, v250
	v_mfma_f32_16x16x32_bf16 v[18:21], v[244:247], v[204:207], v[18:21]
	v_add_u32_e32 v144, s23, v250
	v_mfma_f32_16x16x32_bf16 v[14:17], v[232:235], v[208:211], v[14:17]
	global_load_dwordx4 v[164:167], v164, s[100:101] offset:128
	v_mfma_f32_16x16x32_bf16 v[10:13], v[236:239], v[208:211], v[10:13]
	global_load_dwordx4 v[168:171], v168, s[100:101] offset:128
	v_mfma_f32_16x16x32_bf16 v[6:9], v[240:243], v[208:211], v[6:9]
	global_load_dwordx4 v[172:175], v172, s[100:101] offset:128
	v_mfma_f32_16x16x32_bf16 v[2:5], v[244:247], v[208:211], v[2:5]
	global_load_dwordx4 v[176:179], v144, s[100:101] offset:128
	s_branch .Lg2_p15_loop
.Lg2_p15_tail:
	v_xor_b32_e32 v216, 64, v148
	v_xor_b32_e32 v217, 64, v149
	v_mfma_f32_16x16x32_bf16 v[62:65], v[232:235], v[196:199], v[62:65]
	v_mfma_f32_16x16x32_bf16 v[58:61], v[236:239], v[196:199], v[58:61]
	v_mfma_f32_16x16x32_bf16 v[54:57], v[240:243], v[196:199], v[54:57]
	v_mfma_f32_16x16x32_bf16 v[50:53], v[244:247], v[196:199], v[50:53]
	v_mfma_f32_16x16x32_bf16 v[46:49], v[232:235], v[200:203], v[46:49]
	v_mfma_f32_16x16x32_bf16 v[42:45], v[236:239], v[200:203], v[42:45]
	v_mfma_f32_16x16x32_bf16 v[38:41], v[240:243], v[200:203], v[38:41]
	v_mfma_f32_16x16x32_bf16 v[34:37], v[244:247], v[200:203], v[34:37]
	v_mfma_f32_16x16x32_bf16 v[30:33], v[232:235], v[204:207], v[30:33]
	v_mfma_f32_16x16x32_bf16 v[26:29], v[236:239], v[204:207], v[26:29]
	v_mfma_f32_16x16x32_bf16 v[22:25], v[240:243], v[204:207], v[22:25]
	v_mfma_f32_16x16x32_bf16 v[18:21], v[244:247], v[204:207], v[18:21]
	v_mfma_f32_16x16x32_bf16 v[14:17], v[232:235], v[208:211], v[14:17]
	v_mfma_f32_16x16x32_bf16 v[10:13], v[236:239], v[208:211], v[10:13]
	v_mfma_f32_16x16x32_bf16 v[6:9], v[240:243], v[208:211], v[6:9]
	v_mfma_f32_16x16x32_bf16 v[2:5], v[244:247], v[208:211], v[2:5]
	ds_read_b128 v[136:139], v149 offset:32768
	ds_read_b128 v[140:143], v149 offset:34816
	ds_read_b128 v[152:155], v149 offset:36864
	ds_read_b128 v[156:159], v149 offset:38912
	ds_read_b128 v[160:163], v148 offset:32768
	ds_read_b128 v[164:167], v148 offset:34816
	ds_read_b128 v[168:171], v148 offset:36864
	ds_read_b128 v[172:175], v148 offset:38912
	s_setprio 1
	s_waitcnt lgkmcnt(3)
	v_mfma_f32_16x16x32_bf16 v[126:129], v[136:139], v[160:163], v[126:129]
	v_mfma_f32_16x16x32_bf16 v[122:125], v[140:143], v[160:163], v[122:125]
	v_mfma_f32_16x16x32_bf16 v[118:121], v[152:155], v[160:163], v[118:121]
	v_mfma_f32_16x16x32_bf16 v[114:117], v[156:159], v[160:163], v[114:117]
	s_waitcnt lgkmcnt(2)
	v_mfma_f32_16x16x32_bf16 v[110:113], v[136:139], v[164:167], v[110:113]
	v_mfma_f32_16x16x32_bf16 v[106:109], v[140:143], v[164:167], v[106:109]
	v_mfma_f32_16x16x32_bf16 v[102:105], v[152:155], v[164:167], v[102:105]
	v_mfma_f32_16x16x32_bf16 v[98:101], v[156:159], v[164:167], v[98:101]
	s_waitcnt lgkmcnt(1)
	v_mfma_f32_16x16x32_bf16 v[94:97], v[136:139], v[168:171], v[94:97]
	v_mfma_f32_16x16x32_bf16 v[90:93], v[140:143], v[168:171], v[90:93]
	v_mfma_f32_16x16x32_bf16 v[86:89], v[152:155], v[168:171], v[86:89]
	v_mfma_f32_16x16x32_bf16 v[82:85], v[156:159], v[168:171], v[82:85]
	s_waitcnt lgkmcnt(0)
	v_mfma_f32_16x16x32_bf16 v[78:81], v[136:139], v[172:175], v[78:81]
	v_mfma_f32_16x16x32_bf16 v[74:77], v[140:143], v[172:175], v[74:77]
	v_mfma_f32_16x16x32_bf16 v[70:73], v[152:155], v[172:175], v[70:73]
	v_mfma_f32_16x16x32_bf16 v[66:69], v[156:159], v[172:175], v[66:69]
	s_setprio 0
	ds_read_b128 v[160:163], v148 offset:40960
	ds_read_b128 v[164:167], v148 offset:43008
	ds_read_b128 v[168:171], v148 offset:45056
	ds_read_b128 v[172:175], v148 offset:47104
	s_setprio 1
	s_waitcnt lgkmcnt(3)
	v_mfma_f32_16x16x32_bf16 v[62:65], v[136:139], v[160:163], v[62:65]
	v_mfma_f32_16x16x32_bf16 v[58:61], v[140:143], v[160:163], v[58:61]
	v_mfma_f32_16x16x32_bf16 v[54:57], v[152:155], v[160:163], v[54:57]
	v_mfma_f32_16x16x32_bf16 v[50:53], v[156:159], v[160:163], v[50:53]
	s_waitcnt lgkmcnt(2)
	v_mfma_f32_16x16x32_bf16 v[46:49], v[136:139], v[164:167], v[46:49]
	v_mfma_f32_16x16x32_bf16 v[42:45], v[140:143], v[164:167], v[42:45]
	v_mfma_f32_16x16x32_bf16 v[38:41], v[152:155], v[164:167], v[38:41]
	v_mfma_f32_16x16x32_bf16 v[34:37], v[156:159], v[164:167], v[34:37]
	s_waitcnt lgkmcnt(1)
	v_mfma_f32_16x16x32_bf16 v[30:33], v[136:139], v[168:171], v[30:33]
	v_mfma_f32_16x16x32_bf16 v[26:29], v[140:143], v[168:171], v[26:29]
	v_mfma_f32_16x16x32_bf16 v[22:25], v[152:155], v[168:171], v[22:25]
	v_mfma_f32_16x16x32_bf16 v[18:21], v[156:159], v[168:171], v[18:21]
	s_waitcnt lgkmcnt(0)
	v_mfma_f32_16x16x32_bf16 v[14:17], v[136:139], v[172:175], v[14:17]
	v_mfma_f32_16x16x32_bf16 v[10:13], v[140:143], v[172:175], v[10:13]
	v_mfma_f32_16x16x32_bf16 v[6:9], v[152:155], v[172:175], v[6:9]
	v_mfma_f32_16x16x32_bf16 v[2:5], v[156:159], v[172:175], v[2:5]
	s_setprio 0
	ds_read_b128 v[136:139], v217 offset:32768
	ds_read_b128 v[140:143], v217 offset:34816
	ds_read_b128 v[152:155], v217 offset:36864
	ds_read_b128 v[156:159], v217 offset:38912
	ds_read_b128 v[160:163], v216 offset:32768
	ds_read_b128 v[164:167], v216 offset:34816
	ds_read_b128 v[168:171], v216 offset:36864
	ds_read_b128 v[172:175], v216 offset:38912
	s_setprio 1
	s_waitcnt lgkmcnt(3)
	v_mfma_f32_16x16x32_bf16 v[126:129], v[136:139], v[160:163], v[126:129]
	v_mfma_f32_16x16x32_bf16 v[122:125], v[140:143], v[160:163], v[122:125]
	v_mfma_f32_16x16x32_bf16 v[118:121], v[152:155], v[160:163], v[118:121]
	v_mfma_f32_16x16x32_bf16 v[114:117], v[156:159], v[160:163], v[114:117]
	s_waitcnt lgkmcnt(2)
	v_mfma_f32_16x16x32_bf16 v[110:113], v[136:139], v[164:167], v[110:113]
	v_mfma_f32_16x16x32_bf16 v[106:109], v[140:143], v[164:167], v[106:109]
	v_mfma_f32_16x16x32_bf16 v[102:105], v[152:155], v[164:167], v[102:105]
	v_mfma_f32_16x16x32_bf16 v[98:101], v[156:159], v[164:167], v[98:101]
	s_waitcnt lgkmcnt(1)
	v_mfma_f32_16x16x32_bf16 v[94:97], v[136:139], v[168:171], v[94:97]
	v_mfma_f32_16x16x32_bf16 v[90:93], v[140:143], v[168:171], v[90:93]
	v_mfma_f32_16x16x32_bf16 v[86:89], v[152:155], v[168:171], v[86:89]
	v_mfma_f32_16x16x32_bf16 v[82:85], v[156:159], v[168:171], v[82:85]
	s_waitcnt lgkmcnt(0)
	v_mfma_f32_16x16x32_bf16 v[78:81], v[136:139], v[172:175], v[78:81]
	v_mfma_f32_16x16x32_bf16 v[74:77], v[140:143], v[172:175], v[74:77]
	v_mfma_f32_16x16x32_bf16 v[70:73], v[152:155], v[172:175], v[70:73]
	v_mfma_f32_16x16x32_bf16 v[66:69], v[156:159], v[172:175], v[66:69]
	s_setprio 0
	ds_read_b128 v[160:163], v216 offset:40960
	ds_read_b128 v[164:167], v216 offset:43008
	ds_read_b128 v[168:171], v216 offset:45056
	ds_read_b128 v[172:175], v216 offset:47104
	s_setprio 1
	s_waitcnt lgkmcnt(3)
	v_mfma_f32_16x16x32_bf16 v[62:65], v[136:139], v[160:163], v[62:65]
	v_mfma_f32_16x16x32_bf16 v[58:61], v[140:143], v[160:163], v[58:61]
	v_mfma_f32_16x16x32_bf16 v[54:57], v[152:155], v[160:163], v[54:57]
	v_mfma_f32_16x16x32_bf16 v[50:53], v[156:159], v[160:163], v[50:53]
	s_waitcnt lgkmcnt(2)
	v_mfma_f32_16x16x32_bf16 v[46:49], v[136:139], v[164:167], v[46:49]
	v_mfma_f32_16x16x32_bf16 v[42:45], v[140:143], v[164:167], v[42:45]
	v_mfma_f32_16x16x32_bf16 v[38:41], v[152:155], v[164:167], v[38:41]
	v_mfma_f32_16x16x32_bf16 v[34:37], v[156:159], v[164:167], v[34:37]
	s_waitcnt lgkmcnt(1)
	v_mfma_f32_16x16x32_bf16 v[30:33], v[136:139], v[168:171], v[30:33]
	v_mfma_f32_16x16x32_bf16 v[26:29], v[140:143], v[168:171], v[26:29]
	v_mfma_f32_16x16x32_bf16 v[22:25], v[152:155], v[168:171], v[22:25]
	v_mfma_f32_16x16x32_bf16 v[18:21], v[156:159], v[168:171], v[18:21]
	s_waitcnt lgkmcnt(0)
	v_mfma_f32_16x16x32_bf16 v[14:17], v[136:139], v[172:175], v[14:17]
	v_mfma_f32_16x16x32_bf16 v[10:13], v[140:143], v[172:175], v[10:13]
	v_mfma_f32_16x16x32_bf16 v[6:9], v[152:155], v[172:175], v[6:9]
	v_mfma_f32_16x16x32_bf16 v[2:5], v[156:159], v[172:175], v[2:5]
	s_setprio 0
	v_add_u32_e32 v152, s37, v150
	v_mul_hi_i32 v136, v152, s24
	v_lshrrev_b32_e32 v137, 31, v136
	v_ashrrev_i32_e32 v136, 11, v136
	v_add_u32_e32 v137, v136, v137
	v_mad_i32_i24 v142, v137, s25, v152
	v_lshlrev_b32_e32 v139, 13, v137
	v_cmp_lt_i32_e32 vcc, s26, v142
	v_add3_u32 v138, v139, v142, s27
	s_barrier
	s_and_saveexec_b64 s[8:9], vcc
	s_xor_b64 s[8:9], exec, s[8:9]
	v_add3_u32 v136, v139, v142, s27
	s_or_saveexec_b64 s[8:9], s[8:9]
	v_mov_b64_e32 v[140:141], s[84:85]
	v_lshl_add_u32 v139, v137, 8, v142
	s_xor_b64 exec, exec, s[8:9]
	v_lshl_add_u32 v136, v137, 8, v142
	v_mov_b64_e32 v[140:141], s[4:5]
	s_or_b64 exec, exec, s[8:9]
	s_and_saveexec_b64 s[8:9], vcc
	s_xor_b64 s[8:9], exec, s[8:9]
	s_cbranch_execz .LBB0_781
	v_mul_hi_i32_i24_e32 v143, 0x6000, v137
	v_mul_i32_i24_e32 v142, 0x6000, v137
	s_or_saveexec_b64 s[8:9], s[8:9]
	v_mov_b64_e32 v[144:145], s[84:85]
	s_xor_b64 exec, exec, s[8:9]
	s_cbranch_execnz .LBB0_782
	s_branch .LBB0_783
